# peeled first K-iteration in all 11 GEMM k-loops (C=0 on first-touch MFMAs), per-unit accumulator zeroing (128 v_mov) removed
# speedup vs baseline: 1.0157x; 1.0085x over previous
.LBB0_504:
	s_mov_b32 s39, 0
	s_mov_b64 s[66:67], -1
	s_mov_b64 s[72:73], 0
	s_add_u32 s20, s62, s39
	s_addc_u32 s21, s63, 0
	s_add_u32 s22, s20, 0x100
	s_addc_u32 s23, s21, 0
	s_and_b64 s[18:19], s[72:73], exec
	s_cselect_b32 vcc_hi, s49, s23
	s_cselect_b32 vcc_lo, s48, s22
	s_add_u32 s18, s60, s39
	s_addc_u32 s19, s61, 0
	s_add_u32 s22, s18, 0x100
	s_addc_u32 s23, s19, 0
	s_add_i32 s24, 0, 0x10000
	s_and_b64 s[18:19], s[72:73], exec
	s_cselect_b32 s51, s59, s23
	s_cselect_b32 s50, s58, s22
	s_add_i32 s22, 0, 0x14000
	s_add_u32 s64, s20, 0x40080
	s_addc_u32 s65, s21, 0
	s_add_i32 s21, s24, s69
	s_add_i32 m0, s4, 0xc000
	s_add_i32 s25, s4, 0xe000
	s_add_i32 s18, s21, 0x2000
	s_add_u32 s78, s50, 0x10000
	v_add_u32_e32 v140, s24, v170
	v_add_u32_e32 v162, s22, v170
	s_addc_u32 s79, s51, 0
	s_add_i32 s19, s22, s69
	ds_read_b128 v[128:131], v140
	ds_read_b128 v[132:135], v140 offset:1024
	ds_read_b128 v[136:139], v140 offset:2048
	ds_read_b128 v[140:143], v140 offset:3072
	ds_read_b128 v[152:155], v162
	ds_read_b128 v[156:159], v162 offset:1024
	ds_read_b128 v[164:167], v162 offset:2048
	ds_read_b128 v[172:175], v162 offset:3072
	s_add_i32 s20, s19, 0x2000
	s_add_i32 s54, 0, 0x18000
	s_add_i32 s43, 0, 0x1c000
	s_add_u32 s74, vcc_lo, 0x40000
	s_addc_u32 s75, vcc_hi, 0
	s_add_i32 s41, s54, s69
	s_add_i32 s39, s41, 0x2000
	s_add_u32 s72, s50, 0x10080
	s_addc_u32 s73, s51, 0
	s_add_i32 s23, s43, s69
	s_add_i32 s22, s23, 0x2000
	v_lshl_add_u64 v[200:201], s[64:65], 0, v[150:151]
	ds_read_b128 v[176:179], v171
	ds_read_b128 v[180:183], v171 offset:1024
	ds_read_b128 v[184:187], v171 offset:2048
	ds_read_b128 v[188:191], v171 offset:3072
	ds_read_b128 v[192:195], v171 offset:4096
	ds_read_b128 v[196:199], v171 offset:5120
	ds_read_b128 v[206:209], v171 offset:6144
	ds_read_b128 v[210:213], v171 offset:7168
	global_load_lds_dwordx4 v[200:201], off
	v_lshl_add_u64 v[200:201], s[64:65], 0, v[146:147]
	s_mov_b32 m0, s25
	s_nop 0
	global_load_lds_dwordx4 v[200:201], off
	s_waitcnt vmcnt(8)
	s_waitcnt lgkmcnt(0)
	s_barrier
	s_setprio 1
	s_waitcnt lgkmcnt(0)
	v_mfma_f32_16x16x32_bf16 v[124:127], v[128:131], v[176:179], 0
	v_mfma_f32_16x16x32_bf16 v[120:123], v[136:139], v[176:179], 0
	v_mfma_f32_16x16x32_bf16 v[112:115], v[128:131], v[184:187], 0
	v_mfma_f32_16x16x32_bf16 v[104:107], v[136:139], v[184:187], 0
	v_mfma_f32_16x16x32_bf16 v[96:99], v[128:131], v[192:195], 0
	v_mfma_f32_16x16x32_bf16 v[88:91], v[136:139], v[192:195], 0
	v_mfma_f32_16x16x32_bf16 v[80:83], v[128:131], v[206:209], 0
	v_mfma_f32_16x16x32_bf16 v[72:75], v[136:139], v[206:209], 0
	v_mfma_f32_16x16x32_bf16 v[124:127], v[132:135], v[180:183], v[124:127]
	v_mfma_f32_16x16x32_bf16 v[120:123], v[140:143], v[180:183], v[120:123]
	v_mfma_f32_16x16x32_bf16 v[112:115], v[132:135], v[188:191], v[112:115]
	v_mfma_f32_16x16x32_bf16 v[104:107], v[140:143], v[188:191], v[104:107]
	v_mfma_f32_16x16x32_bf16 v[96:99], v[132:135], v[196:199], v[96:99]
	v_mfma_f32_16x16x32_bf16 v[88:91], v[140:143], v[196:199], v[88:91]
	v_mfma_f32_16x16x32_bf16 v[80:83], v[132:135], v[210:213], v[80:83]
	v_mfma_f32_16x16x32_bf16 v[72:75], v[140:143], v[210:213], v[72:75]
	s_setprio 0
	s_setprio 1
	v_mfma_f32_16x16x32_bf16 v[116:119], v[152:155], v[176:179], 0
	v_mfma_f32_16x16x32_bf16 v[108:111], v[164:167], v[176:179], 0
	v_mfma_f32_16x16x32_bf16 v[100:103], v[152:155], v[184:187], 0
	v_mfma_f32_16x16x32_bf16 v[92:95], v[164:167], v[184:187], 0
	v_mfma_f32_16x16x32_bf16 v[84:87], v[152:155], v[192:195], 0
	v_mfma_f32_16x16x32_bf16 v[76:79], v[164:167], v[192:195], 0
	v_mfma_f32_16x16x32_bf16 v[68:71], v[152:155], v[206:209], 0
	v_mfma_f32_16x16x32_bf16 v[64:67], v[164:167], v[206:209], 0
	v_mfma_f32_16x16x32_bf16 v[116:119], v[156:159], v[180:183], v[116:119]
	v_mfma_f32_16x16x32_bf16 v[108:111], v[172:175], v[180:183], v[108:111]
	v_mfma_f32_16x16x32_bf16 v[100:103], v[156:159], v[188:191], v[100:103]
	v_mfma_f32_16x16x32_bf16 v[92:95], v[172:175], v[188:191], v[92:95]
	v_mfma_f32_16x16x32_bf16 v[84:87], v[156:159], v[196:199], v[84:87]
	v_mfma_f32_16x16x32_bf16 v[76:79], v[172:175], v[196:199], v[76:79]
	v_mfma_f32_16x16x32_bf16 v[68:71], v[156:159], v[210:213], v[68:71]
	v_mfma_f32_16x16x32_bf16 v[64:67], v[172:175], v[210:213], v[64:67]
	s_setprio 0
	s_barrier
	s_mov_b32 m0, s21
	v_lshl_add_u64 v[200:201], s[50:51], 0, v[148:149]
	ds_read_b128 v[176:179], v171 offset:16384
	ds_read_b128 v[180:183], v171 offset:17408
	ds_read_b128 v[184:187], v171 offset:18432
	ds_read_b128 v[188:191], v171 offset:19456
	ds_read_b128 v[192:195], v171 offset:20480
	ds_read_b128 v[196:199], v171 offset:21504
	ds_read_b128 v[206:209], v171 offset:22528
	ds_read_b128 v[210:213], v171 offset:23552
	global_load_lds_dwordx4 v[200:201], off
	v_lshl_add_u64 v[214:215], s[50:51], 0, v[144:145]
	s_mov_b32 m0, s18
	v_lshl_add_u64 v[216:217], s[78:79], 0, v[148:149]
	global_load_lds_dwordx4 v[214:215], off
	s_mov_b32 m0, s19
	v_lshl_add_u64 v[218:219], vcc, 0, v[146:147]
	global_load_lds_dwordx4 v[216:217], off
	v_lshl_add_u64 v[216:217], s[78:79], 0, v[144:145]
	s_mov_b32 m0, s20
	s_nop 0
	global_load_lds_dwordx4 v[216:217], off
	v_lshl_add_u64 v[216:217], vcc, 0, v[150:151]
	s_mov_b32 m0, s4
	s_nop 0
	global_load_lds_dwordx4 v[216:217], off
	s_mov_b32 m0, s5
	s_nop 0
	global_load_lds_dwordx4 v[218:219], off
	s_waitcnt vmcnt(8)
	s_waitcnt lgkmcnt(0)
	s_barrier
	s_setprio 1
	s_waitcnt lgkmcnt(0)
	v_mfma_f32_16x16x32_bf16 v[60:63], v[128:131], v[176:179], 0
	v_mfma_f32_16x16x32_bf16 v[56:59], v[136:139], v[176:179], 0
	v_mfma_f32_16x16x32_bf16 v[48:51], v[128:131], v[184:187], 0
	v_mfma_f32_16x16x32_bf16 v[40:43], v[136:139], v[184:187], 0
	v_mfma_f32_16x16x32_bf16 v[32:35], v[128:131], v[192:195], 0
	v_mfma_f32_16x16x32_bf16 v[24:27], v[136:139], v[192:195], 0
	v_mfma_f32_16x16x32_bf16 v[16:19], v[128:131], v[206:209], 0
	v_mfma_f32_16x16x32_bf16 v[8:11], v[136:139], v[206:209], 0
	v_mfma_f32_16x16x32_bf16 v[60:63], v[132:135], v[180:183], v[60:63]
	v_mfma_f32_16x16x32_bf16 v[56:59], v[140:143], v[180:183], v[56:59]
	v_mfma_f32_16x16x32_bf16 v[48:51], v[132:135], v[188:191], v[48:51]
	v_mfma_f32_16x16x32_bf16 v[40:43], v[140:143], v[188:191], v[40:43]
	v_mfma_f32_16x16x32_bf16 v[32:35], v[132:135], v[196:199], v[32:35]
	v_mfma_f32_16x16x32_bf16 v[24:27], v[140:143], v[196:199], v[24:27]
	v_mfma_f32_16x16x32_bf16 v[16:19], v[132:135], v[210:213], v[16:19]
	v_mfma_f32_16x16x32_bf16 v[8:11], v[140:143], v[210:213], v[8:11]
	s_setprio 0
	s_setprio 1
	v_mfma_f32_16x16x32_bf16 v[52:55], v[152:155], v[176:179], 0
	v_mfma_f32_16x16x32_bf16 v[44:47], v[164:167], v[176:179], 0
	v_mfma_f32_16x16x32_bf16 v[36:39], v[152:155], v[184:187], 0
	v_mfma_f32_16x16x32_bf16 v[28:31], v[164:167], v[184:187], 0
	v_mfma_f32_16x16x32_bf16 v[20:23], v[152:155], v[192:195], 0
	v_mfma_f32_16x16x32_bf16 v[12:15], v[164:167], v[192:195], 0
	v_mfma_f32_16x16x32_bf16 v[4:7], v[152:155], v[206:209], 0
	v_mfma_f32_16x16x32_bf16 v[0:3], v[164:167], v[206:209], 0
	v_mfma_f32_16x16x32_bf16 v[52:55], v[156:159], v[180:183], v[52:55]
	v_mfma_f32_16x16x32_bf16 v[44:47], v[172:175], v[180:183], v[44:47]
	v_mfma_f32_16x16x32_bf16 v[36:39], v[156:159], v[188:191], v[36:39]
	v_mfma_f32_16x16x32_bf16 v[28:31], v[172:175], v[188:191], v[28:31]
	v_mfma_f32_16x16x32_bf16 v[20:23], v[156:159], v[196:199], v[20:23]
	v_mfma_f32_16x16x32_bf16 v[12:15], v[172:175], v[196:199], v[12:15]
	v_mfma_f32_16x16x32_bf16 v[4:7], v[156:159], v[210:213], v[4:7]
	v_mfma_f32_16x16x32_bf16 v[0:3], v[172:175], v[210:213], v[0:3]
	s_setprio 0
	s_barrier
	v_add_u32_e32 v140, s54, v170
	v_add_u32_e32 v162, s43, v170
	ds_read_b128 v[128:131], v140
	ds_read_b128 v[132:135], v140 offset:1024
	ds_read_b128 v[136:139], v140 offset:2048
	ds_read_b128 v[140:143], v140 offset:3072
	ds_read_b128 v[152:155], v162
	ds_read_b128 v[156:159], v162 offset:1024
	ds_read_b128 v[164:167], v162 offset:2048
	ds_read_b128 v[172:175], v162 offset:3072
	s_mov_b32 m0, s6
	v_lshl_add_u64 v[220:221], s[74:75], 0, v[150:151]
	ds_read_b128 v[176:179], v171 offset:32768
	ds_read_b128 v[180:183], v171 offset:33792
	ds_read_b128 v[184:187], v171 offset:34816
	ds_read_b128 v[188:191], v171 offset:35840
	ds_read_b128 v[192:195], v171 offset:36864
	ds_read_b128 v[196:199], v171 offset:37888
	ds_read_b128 v[206:209], v171 offset:38912
	ds_read_b128 v[210:213], v171 offset:39936
	global_load_lds_dwordx4 v[220:221], off
	v_lshl_add_u64 v[220:221], s[74:75], 0, v[146:147]
	s_mov_b32 m0, s7
	s_nop 0
	global_load_lds_dwordx4 v[220:221], off
	s_waitcnt vmcnt(8)
	s_waitcnt lgkmcnt(0)
	s_barrier
	s_setprio 1
	s_waitcnt lgkmcnt(0)
	v_mfma_f32_16x16x32_bf16 v[124:127], v[128:131], v[176:179], v[124:127]
	v_mfma_f32_16x16x32_bf16 v[120:123], v[136:139], v[176:179], v[120:123]
	v_mfma_f32_16x16x32_bf16 v[112:115], v[128:131], v[184:187], v[112:115]
	v_mfma_f32_16x16x32_bf16 v[104:107], v[136:139], v[184:187], v[104:107]
	v_mfma_f32_16x16x32_bf16 v[96:99], v[128:131], v[192:195], v[96:99]
	v_mfma_f32_16x16x32_bf16 v[88:91], v[136:139], v[192:195], v[88:91]
	v_mfma_f32_16x16x32_bf16 v[80:83], v[128:131], v[206:209], v[80:83]
	v_mfma_f32_16x16x32_bf16 v[72:75], v[136:139], v[206:209], v[72:75]
	v_mfma_f32_16x16x32_bf16 v[124:127], v[132:135], v[180:183], v[124:127]
	v_mfma_f32_16x16x32_bf16 v[120:123], v[140:143], v[180:183], v[120:123]
	v_mfma_f32_16x16x32_bf16 v[112:115], v[132:135], v[188:191], v[112:115]
	v_mfma_f32_16x16x32_bf16 v[104:107], v[140:143], v[188:191], v[104:107]
	v_mfma_f32_16x16x32_bf16 v[96:99], v[132:135], v[196:199], v[96:99]
	v_mfma_f32_16x16x32_bf16 v[88:91], v[140:143], v[196:199], v[88:91]
	v_mfma_f32_16x16x32_bf16 v[80:83], v[132:135], v[210:213], v[80:83]
	v_mfma_f32_16x16x32_bf16 v[72:75], v[140:143], v[210:213], v[72:75]
	s_setprio 0
	s_setprio 1
	v_mfma_f32_16x16x32_bf16 v[116:119], v[152:155], v[176:179], v[116:119]
	v_mfma_f32_16x16x32_bf16 v[108:111], v[164:167], v[176:179], v[108:111]
	v_mfma_f32_16x16x32_bf16 v[100:103], v[152:155], v[184:187], v[100:103]
	v_mfma_f32_16x16x32_bf16 v[92:95], v[164:167], v[184:187], v[92:95]
	v_mfma_f32_16x16x32_bf16 v[84:87], v[152:155], v[192:195], v[84:87]
	v_mfma_f32_16x16x32_bf16 v[76:79], v[164:167], v[192:195], v[76:79]
	v_mfma_f32_16x16x32_bf16 v[68:71], v[152:155], v[206:209], v[68:71]
	v_mfma_f32_16x16x32_bf16 v[64:67], v[164:167], v[206:209], v[64:67]
	v_mfma_f32_16x16x32_bf16 v[116:119], v[156:159], v[180:183], v[116:119]
	v_mfma_f32_16x16x32_bf16 v[108:111], v[172:175], v[180:183], v[108:111]
	v_mfma_f32_16x16x32_bf16 v[100:103], v[156:159], v[188:191], v[100:103]
	v_mfma_f32_16x16x32_bf16 v[92:95], v[172:175], v[188:191], v[92:95]
	v_mfma_f32_16x16x32_bf16 v[84:87], v[156:159], v[196:199], v[84:87]
	v_mfma_f32_16x16x32_bf16 v[76:79], v[172:175], v[196:199], v[76:79]
	v_mfma_f32_16x16x32_bf16 v[68:71], v[156:159], v[210:213], v[68:71]
	v_mfma_f32_16x16x32_bf16 v[64:67], v[172:175], v[210:213], v[64:67]
	s_setprio 0
	s_barrier
	s_mov_b32 m0, s41
	v_lshl_add_u64 v[200:201], v[200:201], 0, s[76:77]
	ds_read_b128 v[176:179], v171 offset:49152
	ds_read_b128 v[180:183], v171 offset:50176
	ds_read_b128 v[184:187], v171 offset:51200
	ds_read_b128 v[188:191], v171 offset:52224
	ds_read_b128 v[192:195], v171 offset:53248
	ds_read_b128 v[196:199], v171 offset:54272
	ds_read_b128 v[206:209], v171 offset:55296
	ds_read_b128 v[210:213], v171 offset:56320
	global_load_lds_dwordx4 v[200:201], off
	v_lshl_add_u64 v[200:201], v[214:215], 0, s[76:77]
	s_mov_b32 m0, s39
	s_nop 0
	global_load_lds_dwordx4 v[200:201], off
	v_lshl_add_u64 v[200:201], s[72:73], 0, v[148:149]
	s_mov_b32 m0, s23
	s_nop 0
	global_load_lds_dwordx4 v[200:201], off
	v_lshl_add_u64 v[200:201], s[72:73], 0, v[144:145]
	s_mov_b32 m0, s22
	s_nop 0
	global_load_lds_dwordx4 v[200:201], off
	v_lshl_add_u64 v[200:201], v[216:217], 0, s[76:77]
	s_mov_b32 m0, s11
	s_nop 0
	global_load_lds_dwordx4 v[200:201], off
	v_lshl_add_u64 v[200:201], v[218:219], 0, s[76:77]
	s_mov_b32 m0, s12
	s_nop 0
	global_load_lds_dwordx4 v[200:201], off
	s_waitcnt vmcnt(8)
	s_waitcnt lgkmcnt(0)
	s_barrier
	s_setprio 1
	s_waitcnt lgkmcnt(0)
	v_mfma_f32_16x16x32_bf16 v[60:63], v[128:131], v[176:179], v[60:63]
	v_mfma_f32_16x16x32_bf16 v[56:59], v[136:139], v[176:179], v[56:59]
	v_mfma_f32_16x16x32_bf16 v[48:51], v[128:131], v[184:187], v[48:51]
	v_mfma_f32_16x16x32_bf16 v[40:43], v[136:139], v[184:187], v[40:43]
	v_mfma_f32_16x16x32_bf16 v[32:35], v[128:131], v[192:195], v[32:35]
	v_mfma_f32_16x16x32_bf16 v[24:27], v[136:139], v[192:195], v[24:27]
	v_mfma_f32_16x16x32_bf16 v[16:19], v[128:131], v[206:209], v[16:19]
	v_mfma_f32_16x16x32_bf16 v[8:11], v[136:139], v[206:209], v[8:11]
	v_mfma_f32_16x16x32_bf16 v[60:63], v[132:135], v[180:183], v[60:63]
	v_mfma_f32_16x16x32_bf16 v[56:59], v[140:143], v[180:183], v[56:59]
	v_mfma_f32_16x16x32_bf16 v[48:51], v[132:135], v[188:191], v[48:51]
	v_mfma_f32_16x16x32_bf16 v[40:43], v[140:143], v[188:191], v[40:43]
	v_mfma_f32_16x16x32_bf16 v[32:35], v[132:135], v[196:199], v[32:35]
	v_mfma_f32_16x16x32_bf16 v[24:27], v[140:143], v[196:199], v[24:27]
	v_mfma_f32_16x16x32_bf16 v[16:19], v[132:135], v[210:213], v[16:19]
	v_mfma_f32_16x16x32_bf16 v[8:11], v[140:143], v[210:213], v[8:11]
	s_setprio 0
	s_setprio 1
	v_mfma_f32_16x16x32_bf16 v[52:55], v[152:155], v[176:179], v[52:55]
	v_mfma_f32_16x16x32_bf16 v[44:47], v[164:167], v[176:179], v[44:47]
	v_mfma_f32_16x16x32_bf16 v[36:39], v[152:155], v[184:187], v[36:39]
	v_mfma_f32_16x16x32_bf16 v[28:31], v[164:167], v[184:187], v[28:31]
	v_mfma_f32_16x16x32_bf16 v[20:23], v[152:155], v[192:195], v[20:23]
	v_mfma_f32_16x16x32_bf16 v[12:15], v[164:167], v[192:195], v[12:15]
	v_mfma_f32_16x16x32_bf16 v[4:7], v[152:155], v[206:209], v[4:7]
	v_mfma_f32_16x16x32_bf16 v[0:3], v[164:167], v[206:209], v[0:3]
	v_mfma_f32_16x16x32_bf16 v[52:55], v[156:159], v[180:183], v[52:55]
	v_mfma_f32_16x16x32_bf16 v[44:47], v[172:175], v[180:183], v[44:47]
	v_mfma_f32_16x16x32_bf16 v[36:39], v[156:159], v[188:191], v[36:39]
	v_mfma_f32_16x16x32_bf16 v[28:31], v[172:175], v[188:191], v[28:31]
	v_mfma_f32_16x16x32_bf16 v[20:23], v[156:159], v[196:199], v[20:23]
	v_mfma_f32_16x16x32_bf16 v[12:15], v[172:175], v[196:199], v[12:15]
	v_mfma_f32_16x16x32_bf16 v[4:7], v[156:159], v[210:213], v[4:7]
	v_mfma_f32_16x16x32_bf16 v[0:3], v[172:175], v[210:213], v[0:3]
	s_setprio 0
	s_barrier
	s_movk_i32 s39, 0x100
	s_andn2_b64 vcc, exec, s[66:67]
	s_mov_b64 s[72:73], -1
	s_mov_b64 s[66:67], 0
	s_cbranch_vccz .LBB0_505
	s_branch .Lpeel_x_505

.Lpeel_x_505:
	s_and_b64 vcc, exec, s[2:3]
	s_cbranch_vccz .LBB0_508
	s_barrier

.LBB0_649:
	s_ashr_i32 s59, s58, 31
	s_lshl_b64 s[6:7], s[58:59], 19
	s_add_u32 s62, s96, s6
	s_addc_u32 s63, s97, s7
	s_and_b64 s[6:7], s[72:73], exec
	s_cselect_b32 s6, s63, s39
	s_cselect_b32 s7, s62, s38
	s_ashr_i32 s61, s60, 31
	s_lshl_b64 s[8:9], s[60:61], 19
	s_add_u32 s74, s50, s8
	s_addc_u32 s75, s51, s9
	s_and_b64 s[8:9], s[72:73], exec
	s_cselect_b32 s8, s75, s41
	s_cselect_b32 s9, s74, s40
	s_add_u32 s38, s38, 0x40080
	s_addc_u32 s39, s39, 0
	s_add_u32 s10, s40, 0x100
	s_addc_u32 s11, s41, 0
	s_mov_b32 s12, -2
	s_add_u32 s13, s38, 0xfffc0080
	s_addc_u32 s14, s39, -1
	s_add_i32 s15, 0, 0x10000
	s_cmp_eq_u32 s12, 12
	s_cselect_b32 s43, s6, s14
	s_cselect_b32 s42, s7, s13
	s_cselect_b32 s41, s8, s11
	s_cselect_b32 s40, s9, s10
	s_add_i32 s13, 0, 0x14000
	v_add_u32_e32 v140, s15, v181
	v_add_u32_e32 v156, s13, v181
	ds_read_b128 v[128:131], v140
	ds_read_b128 v[132:135], v140 offset:1024
	ds_read_b128 v[136:139], v140 offset:2048
	ds_read_b128 v[140:143], v140 offset:3072
	ds_read_b128 v[144:147], v156
	ds_read_b128 v[148:151], v156 offset:1024
	ds_read_b128 v[152:155], v156 offset:2048
	ds_read_b128 v[156:159], v156 offset:3072
	v_lshl_add_u64 v[178:179], s[38:39], 0, v[174:175]
	s_add_i32 m0, s66, 0xc000
	ds_read_b128 v[186:189], v185
	ds_read_b128 v[190:193], v185 offset:1024
	ds_read_b128 v[194:197], v185 offset:2048
	ds_read_b128 v[198:201], v185 offset:3072
	ds_read_b128 v[206:209], v185 offset:4096
	ds_read_b128 v[210:213], v185 offset:5120
	ds_read_b128 v[214:217], v185 offset:6144
	ds_read_b128 v[218:221], v185 offset:7168
	global_load_lds_dwordx4 v[178:179], off
	v_lshl_add_u64 v[178:179], s[38:39], 0, v[176:177]
	s_add_i32 m0, s66, 0xe000
	s_nop 0
	global_load_lds_dwordx4 v[178:179], off
	s_waitcnt vmcnt(8)
	s_waitcnt lgkmcnt(0)
	s_barrier
	s_setprio 1
	s_waitcnt lgkmcnt(0)
	v_mfma_f32_16x16x32_bf16 v[120:123], v[128:131], v[186:189], 0
	v_mfma_f32_16x16x32_bf16 v[124:127], v[136:139], v[186:189], 0
	v_mfma_f32_16x16x32_bf16 v[104:107], v[128:131], v[194:197], 0
	v_mfma_f32_16x16x32_bf16 v[108:111], v[136:139], v[194:197], 0
	v_mfma_f32_16x16x32_bf16 v[88:91], v[128:131], v[206:209], 0
	v_mfma_f32_16x16x32_bf16 v[92:95], v[136:139], v[206:209], 0
	v_mfma_f32_16x16x32_bf16 v[72:75], v[128:131], v[214:217], 0
	v_mfma_f32_16x16x32_bf16 v[76:79], v[136:139], v[214:217], 0
	v_mfma_f32_16x16x32_bf16 v[120:123], v[132:135], v[190:193], v[120:123]
	v_mfma_f32_16x16x32_bf16 v[124:127], v[140:143], v[190:193], v[124:127]
	v_mfma_f32_16x16x32_bf16 v[104:107], v[132:135], v[198:201], v[104:107]
	v_mfma_f32_16x16x32_bf16 v[108:111], v[140:143], v[198:201], v[108:111]
	v_mfma_f32_16x16x32_bf16 v[88:91], v[132:135], v[210:213], v[88:91]
	v_mfma_f32_16x16x32_bf16 v[92:95], v[140:143], v[210:213], v[92:95]
	v_mfma_f32_16x16x32_bf16 v[72:75], v[132:135], v[218:221], v[72:75]
	v_mfma_f32_16x16x32_bf16 v[76:79], v[140:143], v[218:221], v[76:79]
	s_setprio 0
	s_setprio 1
	v_mfma_f32_16x16x32_bf16 v[116:119], v[144:147], v[186:189], 0
	v_mfma_f32_16x16x32_bf16 v[112:115], v[152:155], v[186:189], 0
	v_mfma_f32_16x16x32_bf16 v[100:103], v[144:147], v[194:197], 0
	v_mfma_f32_16x16x32_bf16 v[96:99], v[152:155], v[194:197], 0
	v_mfma_f32_16x16x32_bf16 v[84:87], v[144:147], v[206:209], 0
	v_mfma_f32_16x16x32_bf16 v[80:83], v[152:155], v[206:209], 0
	v_mfma_f32_16x16x32_bf16 v[68:71], v[144:147], v[214:217], 0
	v_mfma_f32_16x16x32_bf16 v[64:67], v[152:155], v[214:217], 0
	v_mfma_f32_16x16x32_bf16 v[116:119], v[148:151], v[190:193], v[116:119]
	v_mfma_f32_16x16x32_bf16 v[112:115], v[156:159], v[190:193], v[112:115]
	v_mfma_f32_16x16x32_bf16 v[100:103], v[148:151], v[198:201], v[100:103]
	v_mfma_f32_16x16x32_bf16 v[96:99], v[156:159], v[198:201], v[96:99]
	v_mfma_f32_16x16x32_bf16 v[84:87], v[148:151], v[210:213], v[84:87]
	v_mfma_f32_16x16x32_bf16 v[80:83], v[156:159], v[210:213], v[80:83]
	v_mfma_f32_16x16x32_bf16 v[68:71], v[148:151], v[218:221], v[68:71]
	v_mfma_f32_16x16x32_bf16 v[64:67], v[156:159], v[218:221], v[64:67]
	s_setprio 0
	s_barrier
	s_add_i32 s14, s15, s65
	v_lshl_add_u64 v[178:179], s[40:41], 0, v[168:169]
	s_mov_b32 m0, s14
	ds_read_b128 v[186:189], v185 offset:16384
	ds_read_b128 v[190:193], v185 offset:17408
	ds_read_b128 v[194:197], v185 offset:18432
	ds_read_b128 v[198:201], v185 offset:19456
	ds_read_b128 v[206:209], v185 offset:20480
	ds_read_b128 v[210:213], v185 offset:21504
	ds_read_b128 v[214:217], v185 offset:22528
	ds_read_b128 v[218:221], v185 offset:23552
	global_load_lds_dwordx4 v[178:179], off
	s_add_i32 m0, s14, 0x2000
	s_add_u32 s14, s40, 0x40000
	v_lshl_add_u64 v[222:223], s[40:41], 0, v[164:165]
	s_addc_u32 s15, s41, 0
	s_add_i32 s13, s13, s65
	global_load_lds_dwordx4 v[222:223], off
	v_lshl_add_u64 v[224:225], s[14:15], 0, v[168:169]
	s_mov_b32 m0, s13
	v_lshl_add_u64 v[226:227], s[42:43], 0, v[166:167]
	global_load_lds_dwordx4 v[224:225], off
	v_lshl_add_u64 v[224:225], s[14:15], 0, v[164:165]
	s_add_i32 m0, s13, 0x2000
	s_nop 0
	global_load_lds_dwordx4 v[224:225], off
	v_lshl_add_u64 v[224:225], s[42:43], 0, v[170:171]
	s_mov_b32 m0, s66
	s_nop 0
	global_load_lds_dwordx4 v[224:225], off
	s_mov_b32 m0, s67
	s_nop 0
	global_load_lds_dwordx4 v[226:227], off
	s_waitcnt vmcnt(8)
	s_waitcnt lgkmcnt(0)
	s_barrier
	s_setprio 1
	s_waitcnt lgkmcnt(0)
	v_mfma_f32_16x16x32_bf16 v[56:59], v[128:131], v[186:189], 0
	v_mfma_f32_16x16x32_bf16 v[60:63], v[136:139], v[186:189], 0
	v_mfma_f32_16x16x32_bf16 v[40:43], v[128:131], v[194:197], 0
	v_mfma_f32_16x16x32_bf16 v[44:47], v[136:139], v[194:197], 0
	v_mfma_f32_16x16x32_bf16 v[24:27], v[128:131], v[206:209], 0
	v_mfma_f32_16x16x32_bf16 v[28:31], v[136:139], v[206:209], 0
	v_mfma_f32_16x16x32_bf16 v[8:11], v[128:131], v[214:217], 0
	v_mfma_f32_16x16x32_bf16 v[12:15], v[136:139], v[214:217], 0
	v_mfma_f32_16x16x32_bf16 v[56:59], v[132:135], v[190:193], v[56:59]
	v_mfma_f32_16x16x32_bf16 v[60:63], v[140:143], v[190:193], v[60:63]
	v_mfma_f32_16x16x32_bf16 v[40:43], v[132:135], v[198:201], v[40:43]
	v_mfma_f32_16x16x32_bf16 v[44:47], v[140:143], v[198:201], v[44:47]
	v_mfma_f32_16x16x32_bf16 v[24:27], v[132:135], v[210:213], v[24:27]
	v_mfma_f32_16x16x32_bf16 v[28:31], v[140:143], v[210:213], v[28:31]
	v_mfma_f32_16x16x32_bf16 v[8:11], v[132:135], v[218:221], v[8:11]
	v_mfma_f32_16x16x32_bf16 v[12:15], v[140:143], v[218:221], v[12:15]
	s_setprio 0
	s_setprio 1
	v_mfma_f32_16x16x32_bf16 v[52:55], v[144:147], v[186:189], 0
	v_mfma_f32_16x16x32_bf16 v[48:51], v[152:155], v[186:189], 0
	v_mfma_f32_16x16x32_bf16 v[36:39], v[144:147], v[194:197], 0
	v_mfma_f32_16x16x32_bf16 v[32:35], v[152:155], v[194:197], 0
	v_mfma_f32_16x16x32_bf16 v[20:23], v[144:147], v[206:209], 0
	v_mfma_f32_16x16x32_bf16 v[16:19], v[152:155], v[206:209], 0
	v_mfma_f32_16x16x32_bf16 v[4:7], v[144:147], v[214:217], 0
	v_mfma_f32_16x16x32_bf16 v[0:3], v[152:155], v[214:217], 0
	v_mfma_f32_16x16x32_bf16 v[52:55], v[148:151], v[190:193], v[52:55]
	v_mfma_f32_16x16x32_bf16 v[48:51], v[156:159], v[190:193], v[48:51]
	v_mfma_f32_16x16x32_bf16 v[36:39], v[148:151], v[198:201], v[36:39]
	v_mfma_f32_16x16x32_bf16 v[32:35], v[156:159], v[198:201], v[32:35]
	v_mfma_f32_16x16x32_bf16 v[20:23], v[148:151], v[210:213], v[20:23]
	v_mfma_f32_16x16x32_bf16 v[16:19], v[156:159], v[210:213], v[16:19]
	v_mfma_f32_16x16x32_bf16 v[4:7], v[148:151], v[218:221], v[4:7]
	v_mfma_f32_16x16x32_bf16 v[0:3], v[156:159], v[218:221], v[0:3]
	s_setprio 0
	s_barrier
	s_add_i32 s13, 0, 0x18000
	s_add_i32 s16, 0, 0x1c000
	v_add_u32_e32 v140, s13, v181
	v_add_u32_e32 v156, s16, v181
	ds_read_b128 v[128:131], v140
	ds_read_b128 v[132:135], v140 offset:1024
	ds_read_b128 v[136:139], v140 offset:2048
	ds_read_b128 v[140:143], v140 offset:3072
	ds_read_b128 v[144:147], v156
	ds_read_b128 v[148:151], v156 offset:1024
	ds_read_b128 v[152:155], v156 offset:2048
	ds_read_b128 v[156:159], v156 offset:3072
	s_add_u32 s14, s42, 0x40000
	s_addc_u32 s15, s43, 0
	s_mov_b32 m0, s68
	v_lshl_add_u64 v[228:229], s[14:15], 0, v[170:171]
	ds_read_b128 v[186:189], v185 offset:32768
	ds_read_b128 v[190:193], v185 offset:33792
	ds_read_b128 v[194:197], v185 offset:34816
	ds_read_b128 v[198:201], v185 offset:35840
	ds_read_b128 v[206:209], v185 offset:36864
	ds_read_b128 v[210:213], v185 offset:37888
	ds_read_b128 v[214:217], v185 offset:38912
	ds_read_b128 v[218:221], v185 offset:39936
	global_load_lds_dwordx4 v[228:229], off
	v_lshl_add_u64 v[228:229], s[14:15], 0, v[166:167]
	s_mov_b32 m0, s69
	s_nop 0
	global_load_lds_dwordx4 v[228:229], off
	s_waitcnt vmcnt(8)
	s_waitcnt lgkmcnt(0)
	s_barrier
	s_setprio 1
	s_waitcnt lgkmcnt(0)
	v_mfma_f32_16x16x32_bf16 v[120:123], v[128:131], v[186:189], v[120:123]
	v_mfma_f32_16x16x32_bf16 v[124:127], v[136:139], v[186:189], v[124:127]
	v_mfma_f32_16x16x32_bf16 v[104:107], v[128:131], v[194:197], v[104:107]
	v_mfma_f32_16x16x32_bf16 v[108:111], v[136:139], v[194:197], v[108:111]
	v_mfma_f32_16x16x32_bf16 v[88:91], v[128:131], v[206:209], v[88:91]
	v_mfma_f32_16x16x32_bf16 v[92:95], v[136:139], v[206:209], v[92:95]
	v_mfma_f32_16x16x32_bf16 v[72:75], v[128:131], v[214:217], v[72:75]
	v_mfma_f32_16x16x32_bf16 v[76:79], v[136:139], v[214:217], v[76:79]
	v_mfma_f32_16x16x32_bf16 v[120:123], v[132:135], v[190:193], v[120:123]
	v_mfma_f32_16x16x32_bf16 v[124:127], v[140:143], v[190:193], v[124:127]
	v_mfma_f32_16x16x32_bf16 v[104:107], v[132:135], v[198:201], v[104:107]
	v_mfma_f32_16x16x32_bf16 v[108:111], v[140:143], v[198:201], v[108:111]
	v_mfma_f32_16x16x32_bf16 v[88:91], v[132:135], v[210:213], v[88:91]
	v_mfma_f32_16x16x32_bf16 v[92:95], v[140:143], v[210:213], v[92:95]
	v_mfma_f32_16x16x32_bf16 v[72:75], v[132:135], v[218:221], v[72:75]
	v_mfma_f32_16x16x32_bf16 v[76:79], v[140:143], v[218:221], v[76:79]
	s_setprio 0
	s_setprio 1
	v_mfma_f32_16x16x32_bf16 v[116:119], v[144:147], v[186:189], v[116:119]
	v_mfma_f32_16x16x32_bf16 v[112:115], v[152:155], v[186:189], v[112:115]
	v_mfma_f32_16x16x32_bf16 v[100:103], v[144:147], v[194:197], v[100:103]
	v_mfma_f32_16x16x32_bf16 v[96:99], v[152:155], v[194:197], v[96:99]
	v_mfma_f32_16x16x32_bf16 v[84:87], v[144:147], v[206:209], v[84:87]
	v_mfma_f32_16x16x32_bf16 v[80:83], v[152:155], v[206:209], v[80:83]
	v_mfma_f32_16x16x32_bf16 v[68:71], v[144:147], v[214:217], v[68:71]
	v_mfma_f32_16x16x32_bf16 v[64:67], v[152:155], v[214:217], v[64:67]
	v_mfma_f32_16x16x32_bf16 v[116:119], v[148:151], v[190:193], v[116:119]
	v_mfma_f32_16x16x32_bf16 v[112:115], v[156:159], v[190:193], v[112:115]
	v_mfma_f32_16x16x32_bf16 v[100:103], v[148:151], v[198:201], v[100:103]
	v_mfma_f32_16x16x32_bf16 v[96:99], v[156:159], v[198:201], v[96:99]
	v_mfma_f32_16x16x32_bf16 v[84:87], v[148:151], v[210:213], v[84:87]
	v_mfma_f32_16x16x32_bf16 v[80:83], v[156:159], v[210:213], v[80:83]
	v_mfma_f32_16x16x32_bf16 v[68:71], v[148:151], v[218:221], v[68:71]
	v_mfma_f32_16x16x32_bf16 v[64:67], v[156:159], v[218:221], v[64:67]
	s_setprio 0
	s_barrier
	s_add_i32 s13, s13, s65
	v_lshl_add_u64 v[178:179], v[178:179], 0, s[76:77]
	s_mov_b32 m0, s13
	ds_read_b128 v[186:189], v185 offset:49152
	ds_read_b128 v[190:193], v185 offset:50176
	ds_read_b128 v[194:197], v185 offset:51200
	ds_read_b128 v[198:201], v185 offset:52224
	ds_read_b128 v[206:209], v185 offset:53248
	ds_read_b128 v[210:213], v185 offset:54272
	ds_read_b128 v[214:217], v185 offset:55296
	ds_read_b128 v[218:221], v185 offset:56320
	global_load_lds_dwordx4 v[178:179], off
	s_add_i32 m0, s13, 0x2000
	s_add_u32 s14, s40, 0x40080
	v_lshl_add_u64 v[178:179], v[222:223], 0, s[76:77]
	s_addc_u32 s15, s41, 0
	s_add_i32 s13, s16, s65
	global_load_lds_dwordx4 v[178:179], off
	v_lshl_add_u64 v[178:179], s[14:15], 0, v[168:169]
	s_mov_b32 m0, s13
	s_nop 0
	global_load_lds_dwordx4 v[178:179], off
	v_lshl_add_u64 v[178:179], s[14:15], 0, v[164:165]
	s_add_i32 m0, s13, 0x2000
	s_nop 0
	global_load_lds_dwordx4 v[178:179], off
	v_lshl_add_u64 v[178:179], v[224:225], 0, s[76:77]
	s_mov_b32 m0, s79
	s_nop 0
	global_load_lds_dwordx4 v[178:179], off
	v_lshl_add_u64 v[178:179], v[226:227], 0, s[76:77]
	s_mov_b32 m0, s46
	s_nop 0
	global_load_lds_dwordx4 v[178:179], off
	s_waitcnt vmcnt(8)
	s_waitcnt lgkmcnt(0)
	s_barrier
	s_setprio 1
	s_waitcnt lgkmcnt(0)
	v_mfma_f32_16x16x32_bf16 v[56:59], v[128:131], v[186:189], v[56:59]
	v_mfma_f32_16x16x32_bf16 v[60:63], v[136:139], v[186:189], v[60:63]
	v_mfma_f32_16x16x32_bf16 v[40:43], v[128:131], v[194:197], v[40:43]
	v_mfma_f32_16x16x32_bf16 v[44:47], v[136:139], v[194:197], v[44:47]
	v_mfma_f32_16x16x32_bf16 v[24:27], v[128:131], v[206:209], v[24:27]
	v_mfma_f32_16x16x32_bf16 v[28:31], v[136:139], v[206:209], v[28:31]
	v_mfma_f32_16x16x32_bf16 v[8:11], v[128:131], v[214:217], v[8:11]
	v_mfma_f32_16x16x32_bf16 v[12:15], v[136:139], v[214:217], v[12:15]
	v_mfma_f32_16x16x32_bf16 v[56:59], v[132:135], v[190:193], v[56:59]
	v_mfma_f32_16x16x32_bf16 v[60:63], v[140:143], v[190:193], v[60:63]
	v_mfma_f32_16x16x32_bf16 v[40:43], v[132:135], v[198:201], v[40:43]
	v_mfma_f32_16x16x32_bf16 v[44:47], v[140:143], v[198:201], v[44:47]
	v_mfma_f32_16x16x32_bf16 v[24:27], v[132:135], v[210:213], v[24:27]
	v_mfma_f32_16x16x32_bf16 v[28:31], v[140:143], v[210:213], v[28:31]
	v_mfma_f32_16x16x32_bf16 v[8:11], v[132:135], v[218:221], v[8:11]
	v_mfma_f32_16x16x32_bf16 v[12:15], v[140:143], v[218:221], v[12:15]
	s_setprio 0
	s_setprio 1
	v_mfma_f32_16x16x32_bf16 v[52:55], v[144:147], v[186:189], v[52:55]
	v_mfma_f32_16x16x32_bf16 v[48:51], v[152:155], v[186:189], v[48:51]
	v_mfma_f32_16x16x32_bf16 v[36:39], v[144:147], v[194:197], v[36:39]
	v_mfma_f32_16x16x32_bf16 v[32:35], v[152:155], v[194:197], v[32:35]
	v_mfma_f32_16x16x32_bf16 v[20:23], v[144:147], v[206:209], v[20:23]
	v_mfma_f32_16x16x32_bf16 v[16:19], v[152:155], v[206:209], v[16:19]
	v_mfma_f32_16x16x32_bf16 v[4:7], v[144:147], v[214:217], v[4:7]
	v_mfma_f32_16x16x32_bf16 v[0:3], v[152:155], v[214:217], v[0:3]
	v_mfma_f32_16x16x32_bf16 v[52:55], v[148:151], v[190:193], v[52:55]
	v_mfma_f32_16x16x32_bf16 v[48:51], v[156:159], v[190:193], v[48:51]
	v_mfma_f32_16x16x32_bf16 v[36:39], v[148:151], v[198:201], v[36:39]
	v_mfma_f32_16x16x32_bf16 v[32:35], v[156:159], v[198:201], v[32:35]
	v_mfma_f32_16x16x32_bf16 v[20:23], v[148:151], v[210:213], v[20:23]
	v_mfma_f32_16x16x32_bf16 v[16:19], v[156:159], v[210:213], v[16:19]
	v_mfma_f32_16x16x32_bf16 v[4:7], v[148:151], v[218:221], v[4:7]
	v_mfma_f32_16x16x32_bf16 v[0:3], v[156:159], v[218:221], v[0:3]
	s_setprio 0
	s_barrier
	s_add_i32 s12, s12, 2
	s_add_u32 s38, s38, 0x100
	s_addc_u32 s39, s39, 0
	s_add_u32 s10, s10, 0x100
	s_addc_u32 s11, s11, 0
	s_cmp_gt_u32 s12, 13
	s_cbranch_scc0 .LBB0_650
	s_branch .Lpeel_x_650

.LBB0_698:
	s_ashr_i32 s39, s38, 31
	s_lshl_b64 s[16:17], s[38:39], 19
	s_add_u32 s42, s4, s16
	s_addc_u32 s43, s5, s17
	s_and_b64 s[16:17], s[48:49], exec
	s_cselect_b32 s16, s43, s63
	s_cselect_b32 s17, s42, s62
	s_ashr_i32 s41, s40, 31
	s_lshl_b64 s[18:19], s[40:41], 19
	s_add_u32 s58, s96, s18
	s_addc_u32 s59, s97, s19
	s_and_b64 s[18:19], s[48:49], exec
	s_cselect_b32 s39, s59, s67
	s_cselect_b32 s41, s58, s66
	s_add_u32 s62, s62, 0x40080
	s_addc_u32 s63, s63, 0
	s_add_u32 s47, s66, 0x100
	s_addc_u32 s54, s67, 0
	s_mov_b32 s61, -2
	s_add_u32 s18, s62, 0xfffc0080
	s_addc_u32 s19, s63, -1
	s_add_i32 s20, 0, 0x10000
	s_cmp_eq_u32 s61, 12
	s_cselect_b32 s65, s16, s19
	s_cselect_b32 s64, s17, s18
	s_cselect_b32 s51, s39, s54
	s_cselect_b32 s50, s41, s47
	s_add_i32 s21, 0, 0x14000
	v_add_u32_e32 v156, s20, v141
	v_add_u32_e32 v162, s21, v141
	ds_read_b128 v[144:147], v156
	ds_read_b128 v[148:151], v156 offset:1024
	ds_read_b128 v[152:155], v156 offset:2048
	ds_read_b128 v[156:159], v156 offset:3072
	ds_read_b128 v[164:167], v162
	ds_read_b128 v[168:171], v162 offset:1024
	ds_read_b128 v[172:175], v162 offset:2048
	ds_read_b128 v[176:179], v162 offset:3072
	v_lshl_add_u64 v[200:201], s[62:63], 0, v[136:137]
	s_add_i32 m0, s8, 0xc000
	ds_read_b128 v[180:183], v143
	ds_read_b128 v[184:187], v143 offset:1024
	ds_read_b128 v[188:191], v143 offset:2048
	ds_read_b128 v[192:195], v143 offset:3072
	ds_read_b128 v[196:199], v143 offset:4096
	ds_read_b128 v[206:209], v143 offset:5120
	ds_read_b128 v[210:213], v143 offset:6144
	ds_read_b128 v[214:217], v143 offset:7168
	global_load_lds_dwordx4 v[200:201], off
	v_lshl_add_u64 v[200:201], s[62:63], 0, v[138:139]
	s_add_i32 m0, s8, 0xe000
	s_nop 0
	global_load_lds_dwordx4 v[200:201], off
	s_waitcnt vmcnt(8)
	s_waitcnt lgkmcnt(0)
	s_barrier
	s_setprio 1
	s_waitcnt lgkmcnt(0)
	v_mfma_f32_16x16x32_bf16 v[124:127], v[144:147], v[180:183], 0
	v_mfma_f32_16x16x32_bf16 v[120:123], v[152:155], v[180:183], 0
	v_mfma_f32_16x16x32_bf16 v[116:119], v[144:147], v[188:191], 0
	v_mfma_f32_16x16x32_bf16 v[108:111], v[152:155], v[188:191], 0
	v_mfma_f32_16x16x32_bf16 v[100:103], v[144:147], v[196:199], 0
	v_mfma_f32_16x16x32_bf16 v[92:95], v[152:155], v[196:199], 0
	v_mfma_f32_16x16x32_bf16 v[84:87], v[144:147], v[210:213], 0
	v_mfma_f32_16x16x32_bf16 v[76:79], v[152:155], v[210:213], 0
	v_mfma_f32_16x16x32_bf16 v[124:127], v[148:151], v[184:187], v[124:127]
	v_mfma_f32_16x16x32_bf16 v[120:123], v[156:159], v[184:187], v[120:123]
	v_mfma_f32_16x16x32_bf16 v[116:119], v[148:151], v[192:195], v[116:119]
	v_mfma_f32_16x16x32_bf16 v[108:111], v[156:159], v[192:195], v[108:111]
	v_mfma_f32_16x16x32_bf16 v[100:103], v[148:151], v[206:209], v[100:103]
	v_mfma_f32_16x16x32_bf16 v[92:95], v[156:159], v[206:209], v[92:95]
	v_mfma_f32_16x16x32_bf16 v[84:87], v[148:151], v[214:217], v[84:87]
	v_mfma_f32_16x16x32_bf16 v[76:79], v[156:159], v[214:217], v[76:79]
	s_setprio 0
	s_setprio 1
	v_mfma_f32_16x16x32_bf16 v[112:115], v[164:167], v[180:183], 0
	v_mfma_f32_16x16x32_bf16 v[104:107], v[172:175], v[180:183], 0
	v_mfma_f32_16x16x32_bf16 v[96:99], v[164:167], v[188:191], 0
	v_mfma_f32_16x16x32_bf16 v[88:91], v[172:175], v[188:191], 0
	v_mfma_f32_16x16x32_bf16 v[80:83], v[164:167], v[196:199], 0
	v_mfma_f32_16x16x32_bf16 v[72:75], v[172:175], v[196:199], 0
	v_mfma_f32_16x16x32_bf16 v[68:71], v[164:167], v[210:213], 0
	v_mfma_f32_16x16x32_bf16 v[64:67], v[172:175], v[210:213], 0
	v_mfma_f32_16x16x32_bf16 v[112:115], v[168:171], v[184:187], v[112:115]
	v_mfma_f32_16x16x32_bf16 v[104:107], v[176:179], v[184:187], v[104:107]
	v_mfma_f32_16x16x32_bf16 v[96:99], v[168:171], v[192:195], v[96:99]
	v_mfma_f32_16x16x32_bf16 v[88:91], v[176:179], v[192:195], v[88:91]
	v_mfma_f32_16x16x32_bf16 v[80:83], v[168:171], v[206:209], v[80:83]
	v_mfma_f32_16x16x32_bf16 v[72:75], v[176:179], v[206:209], v[72:75]
	v_mfma_f32_16x16x32_bf16 v[68:71], v[168:171], v[214:217], v[68:71]
	v_mfma_f32_16x16x32_bf16 v[64:67], v[176:179], v[214:217], v[64:67]
	s_setprio 0
	s_barrier
	s_add_i32 s18, s20, s7
	v_lshl_add_u64 v[200:201], s[50:51], 0, v[132:133]
	s_mov_b32 m0, s18
	ds_read_b128 v[180:183], v143 offset:16384
	ds_read_b128 v[184:187], v143 offset:17408
	ds_read_b128 v[188:191], v143 offset:18432
	ds_read_b128 v[192:195], v143 offset:19456
	ds_read_b128 v[196:199], v143 offset:20480
	ds_read_b128 v[206:209], v143 offset:21504
	ds_read_b128 v[210:213], v143 offset:22528
	ds_read_b128 v[214:217], v143 offset:23552
	global_load_lds_dwordx4 v[200:201], off
	s_add_i32 m0, s18, 0x2000
	s_add_u32 s18, s50, 0x40000
	v_lshl_add_u64 v[218:219], s[50:51], 0, v[128:129]
	s_addc_u32 s19, s51, 0
	s_add_i32 s20, s21, s7
	global_load_lds_dwordx4 v[218:219], off
	v_lshl_add_u64 v[220:221], s[18:19], 0, v[132:133]
	s_mov_b32 m0, s20
	v_lshl_add_u64 v[222:223], s[64:65], 0, v[130:131]
	global_load_lds_dwordx4 v[220:221], off
	v_lshl_add_u64 v[220:221], s[18:19], 0, v[128:129]
	s_add_i32 m0, s20, 0x2000
	s_nop 0
	global_load_lds_dwordx4 v[220:221], off
	v_lshl_add_u64 v[220:221], s[64:65], 0, v[134:135]
	s_mov_b32 m0, s8
	s_nop 0
	global_load_lds_dwordx4 v[220:221], off
	s_mov_b32 m0, s9
	s_nop 0
	global_load_lds_dwordx4 v[222:223], off
	s_waitcnt vmcnt(8)
	s_waitcnt lgkmcnt(0)
	s_barrier
	s_setprio 1
	s_waitcnt lgkmcnt(0)
	v_mfma_f32_16x16x32_bf16 v[60:63], v[144:147], v[180:183], 0
	v_mfma_f32_16x16x32_bf16 v[56:59], v[152:155], v[180:183], 0
	v_mfma_f32_16x16x32_bf16 v[52:55], v[144:147], v[188:191], 0
	v_mfma_f32_16x16x32_bf16 v[44:47], v[152:155], v[188:191], 0
	v_mfma_f32_16x16x32_bf16 v[36:39], v[144:147], v[196:199], 0
	v_mfma_f32_16x16x32_bf16 v[28:31], v[152:155], v[196:199], 0
	v_mfma_f32_16x16x32_bf16 v[20:23], v[144:147], v[210:213], 0
	v_mfma_f32_16x16x32_bf16 v[12:15], v[152:155], v[210:213], 0
	v_mfma_f32_16x16x32_bf16 v[60:63], v[148:151], v[184:187], v[60:63]
	v_mfma_f32_16x16x32_bf16 v[56:59], v[156:159], v[184:187], v[56:59]
	v_mfma_f32_16x16x32_bf16 v[52:55], v[148:151], v[192:195], v[52:55]
	v_mfma_f32_16x16x32_bf16 v[44:47], v[156:159], v[192:195], v[44:47]
	v_mfma_f32_16x16x32_bf16 v[36:39], v[148:151], v[206:209], v[36:39]
	v_mfma_f32_16x16x32_bf16 v[28:31], v[156:159], v[206:209], v[28:31]
	v_mfma_f32_16x16x32_bf16 v[20:23], v[148:151], v[214:217], v[20:23]
	v_mfma_f32_16x16x32_bf16 v[12:15], v[156:159], v[214:217], v[12:15]
	s_setprio 0
	s_setprio 1
	v_mfma_f32_16x16x32_bf16 v[48:51], v[164:167], v[180:183], 0
	v_mfma_f32_16x16x32_bf16 v[40:43], v[172:175], v[180:183], 0
	v_mfma_f32_16x16x32_bf16 v[32:35], v[164:167], v[188:191], 0
	v_mfma_f32_16x16x32_bf16 v[24:27], v[172:175], v[188:191], 0
	v_mfma_f32_16x16x32_bf16 v[16:19], v[164:167], v[196:199], 0
	v_mfma_f32_16x16x32_bf16 v[8:11], v[172:175], v[196:199], 0
	v_mfma_f32_16x16x32_bf16 v[4:7], v[164:167], v[210:213], 0
	v_mfma_f32_16x16x32_bf16 v[0:3], v[172:175], v[210:213], 0
	v_mfma_f32_16x16x32_bf16 v[48:51], v[168:171], v[184:187], v[48:51]
	v_mfma_f32_16x16x32_bf16 v[40:43], v[176:179], v[184:187], v[40:43]
	v_mfma_f32_16x16x32_bf16 v[32:35], v[168:171], v[192:195], v[32:35]
	v_mfma_f32_16x16x32_bf16 v[24:27], v[176:179], v[192:195], v[24:27]
	v_mfma_f32_16x16x32_bf16 v[16:19], v[168:171], v[206:209], v[16:19]
	v_mfma_f32_16x16x32_bf16 v[8:11], v[176:179], v[206:209], v[8:11]
	v_mfma_f32_16x16x32_bf16 v[4:7], v[168:171], v[214:217], v[4:7]
	v_mfma_f32_16x16x32_bf16 v[0:3], v[176:179], v[214:217], v[0:3]
	s_setprio 0
	s_barrier
	s_add_i32 s20, 0, 0x18000
	s_add_i32 s21, 0, 0x1c000
	v_add_u32_e32 v156, s20, v141
	v_add_u32_e32 v162, s21, v141
	ds_read_b128 v[144:147], v156
	ds_read_b128 v[148:151], v156 offset:1024
	ds_read_b128 v[152:155], v156 offset:2048
	ds_read_b128 v[156:159], v156 offset:3072
	ds_read_b128 v[164:167], v162
	ds_read_b128 v[168:171], v162 offset:1024
	ds_read_b128 v[172:175], v162 offset:2048
	ds_read_b128 v[176:179], v162 offset:3072
	s_add_u32 s18, s64, 0x40000
	s_addc_u32 s19, s65, 0
	s_mov_b32 m0, s10
	v_lshl_add_u64 v[224:225], s[18:19], 0, v[134:135]
	ds_read_b128 v[180:183], v143 offset:32768
	ds_read_b128 v[184:187], v143 offset:33792
	ds_read_b128 v[188:191], v143 offset:34816
	ds_read_b128 v[192:195], v143 offset:35840
	ds_read_b128 v[196:199], v143 offset:36864
	ds_read_b128 v[206:209], v143 offset:37888
	ds_read_b128 v[210:213], v143 offset:38912
	ds_read_b128 v[214:217], v143 offset:39936
	global_load_lds_dwordx4 v[224:225], off
	v_lshl_add_u64 v[224:225], s[18:19], 0, v[130:131]
	s_mov_b32 m0, s11
	s_nop 0
	global_load_lds_dwordx4 v[224:225], off
	s_waitcnt vmcnt(8)
	s_waitcnt lgkmcnt(0)
	s_barrier
	s_setprio 1
	s_waitcnt lgkmcnt(0)
	v_mfma_f32_16x16x32_bf16 v[124:127], v[144:147], v[180:183], v[124:127]
	v_mfma_f32_16x16x32_bf16 v[120:123], v[152:155], v[180:183], v[120:123]
	v_mfma_f32_16x16x32_bf16 v[116:119], v[144:147], v[188:191], v[116:119]
	v_mfma_f32_16x16x32_bf16 v[108:111], v[152:155], v[188:191], v[108:111]
	v_mfma_f32_16x16x32_bf16 v[100:103], v[144:147], v[196:199], v[100:103]
	v_mfma_f32_16x16x32_bf16 v[92:95], v[152:155], v[196:199], v[92:95]
	v_mfma_f32_16x16x32_bf16 v[84:87], v[144:147], v[210:213], v[84:87]
	v_mfma_f32_16x16x32_bf16 v[76:79], v[152:155], v[210:213], v[76:79]
	v_mfma_f32_16x16x32_bf16 v[124:127], v[148:151], v[184:187], v[124:127]
	v_mfma_f32_16x16x32_bf16 v[120:123], v[156:159], v[184:187], v[120:123]
	v_mfma_f32_16x16x32_bf16 v[116:119], v[148:151], v[192:195], v[116:119]
	v_mfma_f32_16x16x32_bf16 v[108:111], v[156:159], v[192:195], v[108:111]
	v_mfma_f32_16x16x32_bf16 v[100:103], v[148:151], v[206:209], v[100:103]
	v_mfma_f32_16x16x32_bf16 v[92:95], v[156:159], v[206:209], v[92:95]
	v_mfma_f32_16x16x32_bf16 v[84:87], v[148:151], v[214:217], v[84:87]
	v_mfma_f32_16x16x32_bf16 v[76:79], v[156:159], v[214:217], v[76:79]
	s_setprio 0
	s_setprio 1
	v_mfma_f32_16x16x32_bf16 v[112:115], v[164:167], v[180:183], v[112:115]
	v_mfma_f32_16x16x32_bf16 v[104:107], v[172:175], v[180:183], v[104:107]
	v_mfma_f32_16x16x32_bf16 v[96:99], v[164:167], v[188:191], v[96:99]
	v_mfma_f32_16x16x32_bf16 v[88:91], v[172:175], v[188:191], v[88:91]
	v_mfma_f32_16x16x32_bf16 v[80:83], v[164:167], v[196:199], v[80:83]
	v_mfma_f32_16x16x32_bf16 v[72:75], v[172:175], v[196:199], v[72:75]
	v_mfma_f32_16x16x32_bf16 v[68:71], v[164:167], v[210:213], v[68:71]
	v_mfma_f32_16x16x32_bf16 v[64:67], v[172:175], v[210:213], v[64:67]
	v_mfma_f32_16x16x32_bf16 v[112:115], v[168:171], v[184:187], v[112:115]
	v_mfma_f32_16x16x32_bf16 v[104:107], v[176:179], v[184:187], v[104:107]
	v_mfma_f32_16x16x32_bf16 v[96:99], v[168:171], v[192:195], v[96:99]
	v_mfma_f32_16x16x32_bf16 v[88:91], v[176:179], v[192:195], v[88:91]
	v_mfma_f32_16x16x32_bf16 v[80:83], v[168:171], v[206:209], v[80:83]
	v_mfma_f32_16x16x32_bf16 v[72:75], v[176:179], v[206:209], v[72:75]
	v_mfma_f32_16x16x32_bf16 v[68:71], v[168:171], v[214:217], v[68:71]
	v_mfma_f32_16x16x32_bf16 v[64:67], v[176:179], v[214:217], v[64:67]
	s_setprio 0
	s_barrier
	s_add_i32 s18, s20, s7
	v_lshl_add_u64 v[200:201], v[200:201], 0, s[76:77]
	s_mov_b32 m0, s18
	ds_read_b128 v[180:183], v143 offset:49152
	ds_read_b128 v[184:187], v143 offset:50176
	ds_read_b128 v[188:191], v143 offset:51200
	ds_read_b128 v[192:195], v143 offset:52224
	ds_read_b128 v[196:199], v143 offset:53248
	ds_read_b128 v[206:209], v143 offset:54272
	ds_read_b128 v[210:213], v143 offset:55296
	ds_read_b128 v[214:217], v143 offset:56320
	global_load_lds_dwordx4 v[200:201], off
	s_add_i32 m0, s18, 0x2000
	s_add_u32 s18, s50, 0x40080
	v_lshl_add_u64 v[200:201], v[218:219], 0, s[76:77]
	s_addc_u32 s19, s51, 0
	s_add_i32 s20, s21, s7
	global_load_lds_dwordx4 v[200:201], off
	v_lshl_add_u64 v[200:201], s[18:19], 0, v[132:133]
	s_mov_b32 m0, s20
	s_nop 0
	global_load_lds_dwordx4 v[200:201], off
	v_lshl_add_u64 v[200:201], s[18:19], 0, v[128:129]
	s_add_i32 m0, s20, 0x2000
	s_nop 0
	global_load_lds_dwordx4 v[200:201], off
	v_lshl_add_u64 v[200:201], v[220:221], 0, s[76:77]
	s_mov_b32 m0, s13
	s_nop 0
	global_load_lds_dwordx4 v[200:201], off
	v_lshl_add_u64 v[200:201], v[222:223], 0, s[76:77]
	s_mov_b32 m0, s14
	s_nop 0
	global_load_lds_dwordx4 v[200:201], off
	s_waitcnt vmcnt(8)
	s_waitcnt lgkmcnt(0)
	s_barrier
	s_setprio 1
	s_waitcnt lgkmcnt(0)
	v_mfma_f32_16x16x32_bf16 v[60:63], v[144:147], v[180:183], v[60:63]
	v_mfma_f32_16x16x32_bf16 v[56:59], v[152:155], v[180:183], v[56:59]
	v_mfma_f32_16x16x32_bf16 v[52:55], v[144:147], v[188:191], v[52:55]
	v_mfma_f32_16x16x32_bf16 v[44:47], v[152:155], v[188:191], v[44:47]
	v_mfma_f32_16x16x32_bf16 v[36:39], v[144:147], v[196:199], v[36:39]
	v_mfma_f32_16x16x32_bf16 v[28:31], v[152:155], v[196:199], v[28:31]
	v_mfma_f32_16x16x32_bf16 v[20:23], v[144:147], v[210:213], v[20:23]
	v_mfma_f32_16x16x32_bf16 v[12:15], v[152:155], v[210:213], v[12:15]
	v_mfma_f32_16x16x32_bf16 v[60:63], v[148:151], v[184:187], v[60:63]
	v_mfma_f32_16x16x32_bf16 v[56:59], v[156:159], v[184:187], v[56:59]
	v_mfma_f32_16x16x32_bf16 v[52:55], v[148:151], v[192:195], v[52:55]
	v_mfma_f32_16x16x32_bf16 v[44:47], v[156:159], v[192:195], v[44:47]
	v_mfma_f32_16x16x32_bf16 v[36:39], v[148:151], v[206:209], v[36:39]
	v_mfma_f32_16x16x32_bf16 v[28:31], v[156:159], v[206:209], v[28:31]
	v_mfma_f32_16x16x32_bf16 v[20:23], v[148:151], v[214:217], v[20:23]
	v_mfma_f32_16x16x32_bf16 v[12:15], v[156:159], v[214:217], v[12:15]
	s_setprio 0
	s_setprio 1
	v_mfma_f32_16x16x32_bf16 v[48:51], v[164:167], v[180:183], v[48:51]
	v_mfma_f32_16x16x32_bf16 v[40:43], v[172:175], v[180:183], v[40:43]
	v_mfma_f32_16x16x32_bf16 v[32:35], v[164:167], v[188:191], v[32:35]
	v_mfma_f32_16x16x32_bf16 v[24:27], v[172:175], v[188:191], v[24:27]
	v_mfma_f32_16x16x32_bf16 v[16:19], v[164:167], v[196:199], v[16:19]
	v_mfma_f32_16x16x32_bf16 v[8:11], v[172:175], v[196:199], v[8:11]
	v_mfma_f32_16x16x32_bf16 v[4:7], v[164:167], v[210:213], v[4:7]
	v_mfma_f32_16x16x32_bf16 v[0:3], v[172:175], v[210:213], v[0:3]
	v_mfma_f32_16x16x32_bf16 v[48:51], v[168:171], v[184:187], v[48:51]
	v_mfma_f32_16x16x32_bf16 v[40:43], v[176:179], v[184:187], v[40:43]
	v_mfma_f32_16x16x32_bf16 v[32:35], v[168:171], v[192:195], v[32:35]
	v_mfma_f32_16x16x32_bf16 v[24:27], v[176:179], v[192:195], v[24:27]
	v_mfma_f32_16x16x32_bf16 v[16:19], v[168:171], v[206:209], v[16:19]
	v_mfma_f32_16x16x32_bf16 v[8:11], v[176:179], v[206:209], v[8:11]
	v_mfma_f32_16x16x32_bf16 v[4:7], v[168:171], v[214:217], v[4:7]
	v_mfma_f32_16x16x32_bf16 v[0:3], v[176:179], v[214:217], v[0:3]
	s_setprio 0
	s_barrier
	s_add_i32 s61, s61, 2
	s_add_u32 s62, s62, 0x100
	s_addc_u32 s63, s63, 0
	s_add_u32 s47, s47, 0x100
	s_addc_u32 s54, s54, 0
	s_cmp_gt_u32 s61, 13
	s_cbranch_scc0 .LBB0_699
	s_branch .Lpeel_x_699

.Lpeel_x_699:
	s_and_b64 vcc, exec, s[36:37]
	s_cbranch_vccz .LBB0_704
	s_barrier
	s_cmpk_gt_i32 s60, 0x7f
	s_mov_b64 s[50:51], -1
	s_cbranch_scc1 .LBB0_705

.LBB0_778:
	s_add_i32 s11, s11, 1
	s_mov_b32 s14, s12
	s_mul_i32 s12, s11, s86
	v_readlane_b32 s15, v245, 26
	s_add_i32 s12, s12, s15
	s_cmp_lt_u32 s12, 16
	s_mov_b32 s26, s40
	s_cselect_b64 s[48:49], -1, 0
	s_lshr_b32 s40, s12, 1
	s_and_b32 s12, s12, 1
	s_and_b64 s[16:17], s[48:49], exec
	s_mov_b32 s41, s27
	s_cselect_b32 s15, s89, s51
	s_cselect_b32 s16, s88, s50
	s_lshl_b64 s[20:21], s[40:41], 19
	v_readlane_b32 s17, v244, 0
	s_add_u32 s17, s17, s20
	v_readlane_b32 s20, v244, 1
	s_addc_u32 s20, s20, s21
	s_lshl_b32 s21, s12, 18
	s_add_u32 s17, s17, s21
	s_addc_u32 s22, s20, 0
	s_mov_b64 s[18:19], s[42:43]
	s_and_b64 s[20:21], s[48:49], exec
	s_cselect_b32 s43, s22, s19
	s_cselect_b32 s42, s17, s18
	s_add_u32 s58, s50, 0x20080
	s_addc_u32 s59, s51, 0
	s_add_u32 s17, s18, 0x100
	s_addc_u32 s39, s19, 0
	s_mov_b32 s41, -2
	s_add_u32 s18, s58, 0xfffe0080
	s_addc_u32 s19, s59, -1
	s_add_i32 s20, 0, 0x10000
	s_cmp_eq_u32 s41, 4
	s_cselect_b32 s61, s15, s19
	s_cselect_b32 s60, s16, s18
	v_add_u32_e32 v140, s20, v143
	s_cselect_b32 s51, s43, s39
	s_cselect_b32 s50, s42, s17
	s_add_i32 s21, 0, 0x14000
	ds_read_b128 v[146:149], v140
	ds_read_b128 v[150:153], v140 offset:1024
	ds_read_b128 v[154:157], v140 offset:2048
	ds_read_b128 v[164:167], v140 offset:3072
	v_add_u32_e32 v140, s21, v143
	ds_read_b128 v[168:171], v140
	ds_read_b128 v[172:175], v140 offset:1024
	ds_read_b128 v[176:179], v140 offset:2048
	ds_read_b128 v[180:183], v140 offset:3072
	v_lshl_add_u64 v[140:141], s[58:59], 0, v[136:137]
	s_add_i32 m0, s5, 0xc000
	ds_read_b128 v[184:187], v144
	ds_read_b128 v[188:191], v144 offset:1024
	ds_read_b128 v[192:195], v144 offset:2048
	ds_read_b128 v[196:199], v144 offset:3072
	ds_read_b128 v[206:209], v144 offset:4096
	ds_read_b128 v[210:213], v144 offset:5120
	ds_read_b128 v[214:217], v144 offset:6144
	ds_read_b128 v[218:221], v144 offset:7168
	global_load_lds_dwordx4 v[140:141], off
	v_lshl_add_u64 v[140:141], s[58:59], 0, v[138:139]
	s_add_i32 m0, s5, 0xe000
	s_nop 0
	global_load_lds_dwordx4 v[140:141], off
	s_waitcnt vmcnt(8)
	s_waitcnt lgkmcnt(0)
	s_barrier
	s_setprio 1
	s_waitcnt lgkmcnt(0)
	v_mfma_f32_16x16x32_bf16 v[124:127], v[146:149], v[184:187], 0
	v_mfma_f32_16x16x32_bf16 v[120:123], v[154:157], v[184:187], 0
	v_mfma_f32_16x16x32_bf16 v[116:119], v[146:149], v[192:195], 0
	v_mfma_f32_16x16x32_bf16 v[108:111], v[154:157], v[192:195], 0
	v_mfma_f32_16x16x32_bf16 v[100:103], v[146:149], v[206:209], 0
	v_mfma_f32_16x16x32_bf16 v[92:95], v[154:157], v[206:209], 0
	v_mfma_f32_16x16x32_bf16 v[84:87], v[146:149], v[214:217], 0
	v_mfma_f32_16x16x32_bf16 v[76:79], v[154:157], v[214:217], 0
	v_mfma_f32_16x16x32_bf16 v[124:127], v[150:153], v[188:191], v[124:127]
	v_mfma_f32_16x16x32_bf16 v[120:123], v[164:167], v[188:191], v[120:123]
	v_mfma_f32_16x16x32_bf16 v[116:119], v[150:153], v[196:199], v[116:119]
	v_mfma_f32_16x16x32_bf16 v[108:111], v[164:167], v[196:199], v[108:111]
	v_mfma_f32_16x16x32_bf16 v[100:103], v[150:153], v[210:213], v[100:103]
	v_mfma_f32_16x16x32_bf16 v[92:95], v[164:167], v[210:213], v[92:95]
	v_mfma_f32_16x16x32_bf16 v[84:87], v[150:153], v[218:221], v[84:87]
	v_mfma_f32_16x16x32_bf16 v[76:79], v[164:167], v[218:221], v[76:79]
	s_setprio 0
	s_setprio 1
	v_mfma_f32_16x16x32_bf16 v[112:115], v[168:171], v[184:187], 0
	v_mfma_f32_16x16x32_bf16 v[104:107], v[176:179], v[184:187], 0
	v_mfma_f32_16x16x32_bf16 v[96:99], v[168:171], v[192:195], 0
	v_mfma_f32_16x16x32_bf16 v[88:91], v[176:179], v[192:195], 0
	v_mfma_f32_16x16x32_bf16 v[80:83], v[168:171], v[206:209], 0
	v_mfma_f32_16x16x32_bf16 v[72:75], v[176:179], v[206:209], 0
	v_mfma_f32_16x16x32_bf16 v[68:71], v[168:171], v[214:217], 0
	v_mfma_f32_16x16x32_bf16 v[64:67], v[176:179], v[214:217], 0
	v_mfma_f32_16x16x32_bf16 v[112:115], v[172:175], v[188:191], v[112:115]
	v_mfma_f32_16x16x32_bf16 v[104:107], v[180:183], v[188:191], v[104:107]
	v_mfma_f32_16x16x32_bf16 v[96:99], v[172:175], v[196:199], v[96:99]
	v_mfma_f32_16x16x32_bf16 v[88:91], v[180:183], v[196:199], v[88:91]
	v_mfma_f32_16x16x32_bf16 v[80:83], v[172:175], v[210:213], v[80:83]
	v_mfma_f32_16x16x32_bf16 v[72:75], v[180:183], v[210:213], v[72:75]
	v_mfma_f32_16x16x32_bf16 v[68:71], v[172:175], v[218:221], v[68:71]
	v_mfma_f32_16x16x32_bf16 v[64:67], v[180:183], v[218:221], v[64:67]
	s_setprio 0
	s_barrier
	s_add_i32 s18, s20, s4
	v_lshl_add_u64 v[140:141], s[50:51], 0, v[130:131]
	s_mov_b32 m0, s18
	ds_read_b128 v[184:187], v144 offset:16384
	ds_read_b128 v[188:191], v144 offset:17408
	ds_read_b128 v[192:195], v144 offset:18432
	ds_read_b128 v[196:199], v144 offset:19456
	ds_read_b128 v[206:209], v144 offset:20480
	ds_read_b128 v[210:213], v144 offset:21504
	ds_read_b128 v[214:217], v144 offset:22528
	ds_read_b128 v[218:221], v144 offset:23552
	global_load_lds_dwordx4 v[140:141], off
	s_add_i32 m0, s18, 0x2000
	s_add_u32 s18, s50, 0x20000
	v_lshl_add_u64 v[158:159], s[50:51], 0, v[134:135]
	s_addc_u32 s19, s51, 0
	s_add_i32 s20, s21, s4
	global_load_lds_dwordx4 v[158:159], off
	v_lshl_add_u64 v[200:201], s[18:19], 0, v[130:131]
	s_mov_b32 m0, s20
	v_lshl_add_u64 v[222:223], s[60:61], 0, v[132:133]
	global_load_lds_dwordx4 v[200:201], off
	v_lshl_add_u64 v[200:201], s[18:19], 0, v[134:135]
	s_add_i32 m0, s20, 0x2000
	s_nop 0
	global_load_lds_dwordx4 v[200:201], off
	v_lshl_add_u64 v[200:201], s[60:61], 0, v[128:129]
	s_mov_b32 m0, s5
	s_nop 0
	global_load_lds_dwordx4 v[200:201], off
	s_mov_b32 m0, s6
	s_nop 0
	global_load_lds_dwordx4 v[222:223], off
	s_waitcnt vmcnt(8)
	s_waitcnt lgkmcnt(0)
	s_barrier
	s_setprio 1
	s_waitcnt lgkmcnt(0)
	v_mfma_f32_16x16x32_bf16 v[60:63], v[146:149], v[184:187], 0
	v_mfma_f32_16x16x32_bf16 v[56:59], v[154:157], v[184:187], 0
	v_mfma_f32_16x16x32_bf16 v[52:55], v[146:149], v[192:195], 0
	v_mfma_f32_16x16x32_bf16 v[44:47], v[154:157], v[192:195], 0
	v_mfma_f32_16x16x32_bf16 v[36:39], v[146:149], v[206:209], 0
	v_mfma_f32_16x16x32_bf16 v[28:31], v[154:157], v[206:209], 0
	v_mfma_f32_16x16x32_bf16 v[20:23], v[146:149], v[214:217], 0
	v_mfma_f32_16x16x32_bf16 v[12:15], v[154:157], v[214:217], 0
	v_mfma_f32_16x16x32_bf16 v[60:63], v[150:153], v[188:191], v[60:63]
	v_mfma_f32_16x16x32_bf16 v[56:59], v[164:167], v[188:191], v[56:59]
	v_mfma_f32_16x16x32_bf16 v[52:55], v[150:153], v[196:199], v[52:55]
	v_mfma_f32_16x16x32_bf16 v[44:47], v[164:167], v[196:199], v[44:47]
	v_mfma_f32_16x16x32_bf16 v[36:39], v[150:153], v[210:213], v[36:39]
	v_mfma_f32_16x16x32_bf16 v[28:31], v[164:167], v[210:213], v[28:31]
	v_mfma_f32_16x16x32_bf16 v[20:23], v[150:153], v[218:221], v[20:23]
	v_mfma_f32_16x16x32_bf16 v[12:15], v[164:167], v[218:221], v[12:15]
	s_setprio 0
	s_setprio 1
	v_mfma_f32_16x16x32_bf16 v[48:51], v[168:171], v[184:187], 0
	v_mfma_f32_16x16x32_bf16 v[40:43], v[176:179], v[184:187], 0
	v_mfma_f32_16x16x32_bf16 v[32:35], v[168:171], v[192:195], 0
	v_mfma_f32_16x16x32_bf16 v[24:27], v[176:179], v[192:195], 0
	v_mfma_f32_16x16x32_bf16 v[16:19], v[168:171], v[206:209], 0
	v_mfma_f32_16x16x32_bf16 v[8:11], v[176:179], v[206:209], 0
	v_mfma_f32_16x16x32_bf16 v[4:7], v[168:171], v[214:217], 0
	v_mfma_f32_16x16x32_bf16 v[0:3], v[176:179], v[214:217], 0
	v_mfma_f32_16x16x32_bf16 v[48:51], v[172:175], v[188:191], v[48:51]
	v_mfma_f32_16x16x32_bf16 v[40:43], v[180:183], v[188:191], v[40:43]
	v_mfma_f32_16x16x32_bf16 v[32:35], v[172:175], v[196:199], v[32:35]
	v_mfma_f32_16x16x32_bf16 v[24:27], v[180:183], v[196:199], v[24:27]
	v_mfma_f32_16x16x32_bf16 v[16:19], v[172:175], v[210:213], v[16:19]
	v_mfma_f32_16x16x32_bf16 v[8:11], v[180:183], v[210:213], v[8:11]
	v_mfma_f32_16x16x32_bf16 v[4:7], v[172:175], v[218:221], v[4:7]
	v_mfma_f32_16x16x32_bf16 v[0:3], v[180:183], v[218:221], v[0:3]
	s_setprio 0
	s_barrier
	s_add_i32 s20, 0, 0x18000
	v_add_u32_e32 v145, s20, v143
	s_add_i32 s21, 0, 0x1c000
	ds_read_b128 v[146:149], v145
	ds_read_b128 v[150:153], v145 offset:1024
	ds_read_b128 v[154:157], v145 offset:2048
	ds_read_b128 v[164:167], v145 offset:3072
	v_add_u32_e32 v145, s21, v143
	ds_read_b128 v[168:171], v145
	ds_read_b128 v[172:175], v145 offset:1024
	ds_read_b128 v[176:179], v145 offset:2048
	ds_read_b128 v[180:183], v145 offset:3072
	s_add_u32 s18, s60, 0x20000
	s_addc_u32 s19, s61, 0
	s_mov_b32 m0, s7
	v_lshl_add_u64 v[224:225], s[18:19], 0, v[128:129]
	ds_read_b128 v[184:187], v144 offset:32768
	ds_read_b128 v[188:191], v144 offset:33792
	ds_read_b128 v[192:195], v144 offset:34816
	ds_read_b128 v[196:199], v144 offset:35840
	ds_read_b128 v[206:209], v144 offset:36864
	ds_read_b128 v[210:213], v144 offset:37888
	ds_read_b128 v[214:217], v144 offset:38912
	ds_read_b128 v[218:221], v144 offset:39936
	global_load_lds_dwordx4 v[224:225], off
	v_lshl_add_u64 v[224:225], s[18:19], 0, v[132:133]
	s_mov_b32 m0, s8
	s_nop 0
	global_load_lds_dwordx4 v[224:225], off
	s_waitcnt vmcnt(8)
	s_waitcnt lgkmcnt(0)
	s_barrier
	s_setprio 1
	s_waitcnt lgkmcnt(0)
	v_mfma_f32_16x16x32_bf16 v[124:127], v[146:149], v[184:187], v[124:127]
	v_mfma_f32_16x16x32_bf16 v[120:123], v[154:157], v[184:187], v[120:123]
	v_mfma_f32_16x16x32_bf16 v[116:119], v[146:149], v[192:195], v[116:119]
	v_mfma_f32_16x16x32_bf16 v[108:111], v[154:157], v[192:195], v[108:111]
	v_mfma_f32_16x16x32_bf16 v[100:103], v[146:149], v[206:209], v[100:103]
	v_mfma_f32_16x16x32_bf16 v[92:95], v[154:157], v[206:209], v[92:95]
	v_mfma_f32_16x16x32_bf16 v[84:87], v[146:149], v[214:217], v[84:87]
	v_mfma_f32_16x16x32_bf16 v[76:79], v[154:157], v[214:217], v[76:79]
	v_mfma_f32_16x16x32_bf16 v[124:127], v[150:153], v[188:191], v[124:127]
	v_mfma_f32_16x16x32_bf16 v[120:123], v[164:167], v[188:191], v[120:123]
	v_mfma_f32_16x16x32_bf16 v[116:119], v[150:153], v[196:199], v[116:119]
	v_mfma_f32_16x16x32_bf16 v[108:111], v[164:167], v[196:199], v[108:111]
	v_mfma_f32_16x16x32_bf16 v[100:103], v[150:153], v[210:213], v[100:103]
	v_mfma_f32_16x16x32_bf16 v[92:95], v[164:167], v[210:213], v[92:95]
	v_mfma_f32_16x16x32_bf16 v[84:87], v[150:153], v[218:221], v[84:87]
	v_mfma_f32_16x16x32_bf16 v[76:79], v[164:167], v[218:221], v[76:79]
	s_setprio 0
	s_setprio 1
	v_mfma_f32_16x16x32_bf16 v[112:115], v[168:171], v[184:187], v[112:115]
	v_mfma_f32_16x16x32_bf16 v[104:107], v[176:179], v[184:187], v[104:107]
	v_mfma_f32_16x16x32_bf16 v[96:99], v[168:171], v[192:195], v[96:99]
	v_mfma_f32_16x16x32_bf16 v[88:91], v[176:179], v[192:195], v[88:91]
	v_mfma_f32_16x16x32_bf16 v[80:83], v[168:171], v[206:209], v[80:83]
	v_mfma_f32_16x16x32_bf16 v[72:75], v[176:179], v[206:209], v[72:75]
	v_mfma_f32_16x16x32_bf16 v[68:71], v[168:171], v[214:217], v[68:71]
	v_mfma_f32_16x16x32_bf16 v[64:67], v[176:179], v[214:217], v[64:67]
	v_mfma_f32_16x16x32_bf16 v[112:115], v[172:175], v[188:191], v[112:115]
	v_mfma_f32_16x16x32_bf16 v[104:107], v[180:183], v[188:191], v[104:107]
	v_mfma_f32_16x16x32_bf16 v[96:99], v[172:175], v[196:199], v[96:99]
	v_mfma_f32_16x16x32_bf16 v[88:91], v[180:183], v[196:199], v[88:91]
	v_mfma_f32_16x16x32_bf16 v[80:83], v[172:175], v[210:213], v[80:83]
	v_mfma_f32_16x16x32_bf16 v[72:75], v[180:183], v[210:213], v[72:75]
	v_mfma_f32_16x16x32_bf16 v[68:71], v[172:175], v[218:221], v[68:71]
	v_mfma_f32_16x16x32_bf16 v[64:67], v[180:183], v[218:221], v[64:67]
	s_setprio 0
	s_barrier
	s_add_i32 s18, s20, s4
	v_lshl_add_u64 v[140:141], v[140:141], 0, s[76:77]
	s_mov_b32 m0, s18
	ds_read_b128 v[184:187], v144 offset:49152
	ds_read_b128 v[188:191], v144 offset:50176
	ds_read_b128 v[192:195], v144 offset:51200
	ds_read_b128 v[196:199], v144 offset:52224
	ds_read_b128 v[206:209], v144 offset:53248
	ds_read_b128 v[210:213], v144 offset:54272
	ds_read_b128 v[214:217], v144 offset:55296
	ds_read_b128 v[218:221], v144 offset:56320
	global_load_lds_dwordx4 v[140:141], off
	s_add_i32 m0, s18, 0x2000
	s_add_u32 s18, s50, 0x20080
	v_lshl_add_u64 v[140:141], v[158:159], 0, s[76:77]
	s_addc_u32 s19, s51, 0
	s_add_i32 s20, s21, s4
	global_load_lds_dwordx4 v[140:141], off
	v_lshl_add_u64 v[140:141], s[18:19], 0, v[130:131]
	s_mov_b32 m0, s20
	s_nop 0
	global_load_lds_dwordx4 v[140:141], off
	v_lshl_add_u64 v[140:141], s[18:19], 0, v[134:135]
	s_add_i32 m0, s20, 0x2000
	s_nop 0
	global_load_lds_dwordx4 v[140:141], off
	v_lshl_add_u64 v[140:141], v[200:201], 0, s[76:77]
	s_mov_b32 m0, s9
	s_nop 0
	global_load_lds_dwordx4 v[140:141], off
	v_lshl_add_u64 v[140:141], v[222:223], 0, s[76:77]
	s_mov_b32 m0, s10
	s_nop 0
	global_load_lds_dwordx4 v[140:141], off
	s_waitcnt vmcnt(8)
	s_waitcnt lgkmcnt(0)
	s_barrier
	s_setprio 1
	s_waitcnt lgkmcnt(0)
	v_mfma_f32_16x16x32_bf16 v[60:63], v[146:149], v[184:187], v[60:63]
	v_mfma_f32_16x16x32_bf16 v[56:59], v[154:157], v[184:187], v[56:59]
	v_mfma_f32_16x16x32_bf16 v[52:55], v[146:149], v[192:195], v[52:55]
	v_mfma_f32_16x16x32_bf16 v[44:47], v[154:157], v[192:195], v[44:47]
	v_mfma_f32_16x16x32_bf16 v[36:39], v[146:149], v[206:209], v[36:39]
	v_mfma_f32_16x16x32_bf16 v[28:31], v[154:157], v[206:209], v[28:31]
	v_mfma_f32_16x16x32_bf16 v[20:23], v[146:149], v[214:217], v[20:23]
	v_mfma_f32_16x16x32_bf16 v[12:15], v[154:157], v[214:217], v[12:15]
	v_mfma_f32_16x16x32_bf16 v[60:63], v[150:153], v[188:191], v[60:63]
	v_mfma_f32_16x16x32_bf16 v[56:59], v[164:167], v[188:191], v[56:59]
	v_mfma_f32_16x16x32_bf16 v[52:55], v[150:153], v[196:199], v[52:55]
	v_mfma_f32_16x16x32_bf16 v[44:47], v[164:167], v[196:199], v[44:47]
	v_mfma_f32_16x16x32_bf16 v[36:39], v[150:153], v[210:213], v[36:39]
	v_mfma_f32_16x16x32_bf16 v[28:31], v[164:167], v[210:213], v[28:31]
	v_mfma_f32_16x16x32_bf16 v[20:23], v[150:153], v[218:221], v[20:23]
	v_mfma_f32_16x16x32_bf16 v[12:15], v[164:167], v[218:221], v[12:15]
	s_setprio 0
	s_setprio 1
	v_mfma_f32_16x16x32_bf16 v[48:51], v[168:171], v[184:187], v[48:51]
	v_mfma_f32_16x16x32_bf16 v[40:43], v[176:179], v[184:187], v[40:43]
	v_mfma_f32_16x16x32_bf16 v[32:35], v[168:171], v[192:195], v[32:35]
	v_mfma_f32_16x16x32_bf16 v[24:27], v[176:179], v[192:195], v[24:27]
	v_mfma_f32_16x16x32_bf16 v[16:19], v[168:171], v[206:209], v[16:19]
	v_mfma_f32_16x16x32_bf16 v[8:11], v[176:179], v[206:209], v[8:11]
	v_mfma_f32_16x16x32_bf16 v[4:7], v[168:171], v[214:217], v[4:7]
	v_mfma_f32_16x16x32_bf16 v[0:3], v[176:179], v[214:217], v[0:3]
	v_mfma_f32_16x16x32_bf16 v[48:51], v[172:175], v[188:191], v[48:51]
	v_mfma_f32_16x16x32_bf16 v[40:43], v[180:183], v[188:191], v[40:43]
	v_mfma_f32_16x16x32_bf16 v[32:35], v[172:175], v[196:199], v[32:35]
	v_mfma_f32_16x16x32_bf16 v[24:27], v[180:183], v[196:199], v[24:27]
	v_mfma_f32_16x16x32_bf16 v[16:19], v[172:175], v[210:213], v[16:19]
	v_mfma_f32_16x16x32_bf16 v[8:11], v[180:183], v[210:213], v[8:11]
	v_mfma_f32_16x16x32_bf16 v[4:7], v[172:175], v[218:221], v[4:7]
	v_mfma_f32_16x16x32_bf16 v[0:3], v[180:183], v[218:221], v[0:3]
	s_setprio 0
	s_barrier
	s_add_i32 s41, s41, 2
	s_add_u32 s58, s58, 0x100
	s_addc_u32 s59, s59, 0
	s_add_u32 s17, s17, 0x100
	s_addc_u32 s39, s39, 0
	s_cmp_gt_u32 s41, 5
	s_cbranch_scc0 .LBB0_779
	s_branch .Lpeel_x_779

.Lpeel_x_779:
	s_and_b64 vcc, exec, s[36:37]
	s_cbranch_vccz .LBB0_782
	s_barrier

.LBB0_890:
	s_ashr_i32 s49, s48, 31
	s_lshl_b64 s[16:17], s[48:49], 20
	s_add_u32 s60, s24, s16
	s_addc_u32 s61, s25, s17
	s_and_b64 s[16:17], s[66:67], exec
	s_cselect_b32 s16, s61, s65
	s_cselect_b32 s17, s60, s64
	s_add_u32 s66, s64, 0x1080
	s_addc_u32 s67, s65, 0
	s_add_u32 s41, s50, 0x100
	s_addc_u32 s43, s51, 0
	s_mov_b32 s46, -2
	s_add_u32 s18, s66, 0xfffff080
	s_addc_u32 s19, s67, -1
	s_add_i32 s20, 0, 0x10000
	s_cmp_eq_u32 s46, 28
	s_cselect_b32 s65, s16, s19
	s_cselect_b32 s64, s17, s18
	s_cselect_b32 s51, s59, s43
	s_cselect_b32 s50, s58, s41
	s_add_i32 s21, 0, 0x14000
	v_add_u32_e32 v90, s20, v88
	v_add_u32_e32 v106, s21, v88
	ds_read_b128 v[74:77], v90
	ds_read_b128 v[78:81], v90 offset:1024
	ds_read_b128 v[82:85], v90 offset:2048
	ds_read_b128 v[90:93], v90 offset:3072
	ds_read_b128 v[94:97], v106
	ds_read_b128 v[98:101], v106 offset:1024
	ds_read_b128 v[102:105], v106 offset:2048
	ds_read_b128 v[106:109], v106 offset:3072
	v_lshl_add_u64 v[142:143], s[66:67], 0, v[70:71]
	s_add_i32 m0, s5, 0xc000
	ds_read_b128 v[110:113], v89
	ds_read_b128 v[114:117], v89 offset:1024
	ds_read_b128 v[118:121], v89 offset:2048
	ds_read_b128 v[122:125], v89 offset:3072
	ds_read_b128 v[126:129], v89 offset:4096
	ds_read_b128 v[130:133], v89 offset:5120
	ds_read_b128 v[134:137], v89 offset:6144
	ds_read_b128 v[138:141], v89 offset:7168
	global_load_lds_dwordx4 v[142:143], off
	v_lshl_add_u64 v[142:143], s[66:67], 0, v[72:73]
	s_add_i32 m0, s5, 0xe000
	s_nop 0
	global_load_lds_dwordx4 v[142:143], off
	s_waitcnt vmcnt(8)
	s_waitcnt lgkmcnt(0)
	s_barrier
	s_setprio 1
	s_waitcnt lgkmcnt(0)
	v_mfma_f32_16x16x32_bf16 v[60:63], v[74:77], v[110:113], 0
	v_mfma_f32_16x16x32_bf16 v[56:59], v[82:85], v[110:113], 0
	v_mfma_f32_16x16x32_bf16 v[44:47], v[74:77], v[118:121], 0
	v_mfma_f32_16x16x32_bf16 v[40:43], v[82:85], v[118:121], 0
	v_mfma_f32_16x16x32_bf16 v[28:31], v[74:77], v[126:129], 0
	v_mfma_f32_16x16x32_bf16 v[24:27], v[82:85], v[126:129], 0
	v_mfma_f32_16x16x32_bf16 v[12:15], v[74:77], v[134:137], 0
	v_mfma_f32_16x16x32_bf16 v[8:11], v[82:85], v[134:137], 0
	v_mfma_f32_16x16x32_bf16 v[60:63], v[78:81], v[114:117], v[60:63]
	v_mfma_f32_16x16x32_bf16 v[56:59], v[90:93], v[114:117], v[56:59]
	v_mfma_f32_16x16x32_bf16 v[44:47], v[78:81], v[122:125], v[44:47]
	v_mfma_f32_16x16x32_bf16 v[40:43], v[90:93], v[122:125], v[40:43]
	v_mfma_f32_16x16x32_bf16 v[28:31], v[78:81], v[130:133], v[28:31]
	v_mfma_f32_16x16x32_bf16 v[24:27], v[90:93], v[130:133], v[24:27]
	v_mfma_f32_16x16x32_bf16 v[12:15], v[78:81], v[138:141], v[12:15]
	v_mfma_f32_16x16x32_bf16 v[8:11], v[90:93], v[138:141], v[8:11]
	s_setprio 0
	s_barrier
	s_add_i32 s18, s20, s4
	v_lshl_add_u64 v[142:143], s[50:51], 0, v[162:163]
	s_mov_b32 m0, s18
	ds_read_b128 v[74:77], v89 offset:16384
	ds_read_b128 v[78:81], v89 offset:17408
	ds_read_b128 v[82:85], v89 offset:18432
	ds_read_b128 v[90:93], v89 offset:19456
	ds_read_b128 v[110:113], v89 offset:20480
	ds_read_b128 v[114:117], v89 offset:21504
	ds_read_b128 v[118:121], v89 offset:22528
	ds_read_b128 v[122:125], v89 offset:23552
	global_load_lds_dwordx4 v[142:143], off
	s_add_i32 m0, s18, 0x2000
	s_add_u32 s18, s50, 0x1000
	v_lshl_add_u64 v[144:145], s[50:51], 0, v[64:65]
	s_addc_u32 s19, s51, 0
	s_add_i32 s20, s21, s4
	global_load_lds_dwordx4 v[144:145], off
	v_lshl_add_u64 v[126:127], s[18:19], 0, v[162:163]
	s_mov_b32 m0, s20
	v_lshl_add_u64 v[146:147], s[64:65], 0, v[68:69]
	global_load_lds_dwordx4 v[126:127], off
	v_lshl_add_u64 v[126:127], s[18:19], 0, v[64:65]
	s_add_i32 m0, s20, 0x2000
	v_lshl_add_u64 v[148:149], s[64:65], 0, v[66:67]
	global_load_lds_dwordx4 v[126:127], off
	s_mov_b32 m0, s5
	s_nop 0
	global_load_lds_dwordx4 v[146:147], off
	s_mov_b32 m0, s6
	s_nop 0
	global_load_lds_dwordx4 v[148:149], off
	s_waitcnt vmcnt(8)
	s_waitcnt lgkmcnt(0)
	s_barrier
	s_setprio 1
	s_waitcnt lgkmcnt(0)
	v_mfma_f32_16x16x32_bf16 v[52:55], v[94:97], v[74:77], 0
	v_mfma_f32_16x16x32_bf16 v[48:51], v[102:105], v[74:77], 0
	v_mfma_f32_16x16x32_bf16 v[36:39], v[94:97], v[82:85], 0
	v_mfma_f32_16x16x32_bf16 v[32:35], v[102:105], v[82:85], 0
	v_mfma_f32_16x16x32_bf16 v[20:23], v[94:97], v[110:113], 0
	v_mfma_f32_16x16x32_bf16 v[16:19], v[102:105], v[110:113], 0
	v_mfma_f32_16x16x32_bf16 v[4:7], v[94:97], v[118:121], 0
	v_mfma_f32_16x16x32_bf16 v[0:3], v[102:105], v[118:121], 0
	v_mfma_f32_16x16x32_bf16 v[52:55], v[98:101], v[78:81], v[52:55]
	v_mfma_f32_16x16x32_bf16 v[48:51], v[106:109], v[78:81], v[48:51]
	v_mfma_f32_16x16x32_bf16 v[36:39], v[98:101], v[90:93], v[36:39]
	v_mfma_f32_16x16x32_bf16 v[32:35], v[106:109], v[90:93], v[32:35]
	v_mfma_f32_16x16x32_bf16 v[20:23], v[98:101], v[114:117], v[20:23]
	v_mfma_f32_16x16x32_bf16 v[16:19], v[106:109], v[114:117], v[16:19]
	v_mfma_f32_16x16x32_bf16 v[4:7], v[98:101], v[122:125], v[4:7]
	v_mfma_f32_16x16x32_bf16 v[0:3], v[106:109], v[122:125], v[0:3]
	s_setprio 0
	s_barrier
	s_add_i32 s20, 0, 0x18000
	s_add_i32 s21, 0, 0x1c000
	v_add_u32_e32 v90, s20, v88
	v_add_u32_e32 v106, s21, v88
	ds_read_b128 v[74:77], v90
	ds_read_b128 v[78:81], v90 offset:1024
	ds_read_b128 v[82:85], v90 offset:2048
	ds_read_b128 v[90:93], v90 offset:3072
	ds_read_b128 v[94:97], v106
	ds_read_b128 v[98:101], v106 offset:1024
	ds_read_b128 v[102:105], v106 offset:2048
	ds_read_b128 v[106:109], v106 offset:3072
	s_add_u32 s18, s64, 0x1000
	s_addc_u32 s19, s65, 0
	s_mov_b32 m0, s7
	v_lshl_add_u64 v[150:151], s[18:19], 0, v[68:69]
	ds_read_b128 v[110:113], v89 offset:32768
	ds_read_b128 v[114:117], v89 offset:33792
	ds_read_b128 v[118:121], v89 offset:34816
	ds_read_b128 v[122:125], v89 offset:35840
	ds_read_b128 v[126:129], v89 offset:36864
	ds_read_b128 v[130:133], v89 offset:37888
	ds_read_b128 v[134:137], v89 offset:38912
	ds_read_b128 v[138:141], v89 offset:39936
	global_load_lds_dwordx4 v[150:151], off
	v_lshl_add_u64 v[150:151], s[18:19], 0, v[66:67]
	s_mov_b32 m0, s8
	s_nop 0
	global_load_lds_dwordx4 v[150:151], off
	s_waitcnt vmcnt(8)
	s_waitcnt lgkmcnt(0)
	s_barrier
	s_setprio 1
	s_waitcnt lgkmcnt(0)
	v_mfma_f32_16x16x32_bf16 v[60:63], v[74:77], v[110:113], v[60:63]
	v_mfma_f32_16x16x32_bf16 v[56:59], v[82:85], v[110:113], v[56:59]
	v_mfma_f32_16x16x32_bf16 v[44:47], v[74:77], v[118:121], v[44:47]
	v_mfma_f32_16x16x32_bf16 v[40:43], v[82:85], v[118:121], v[40:43]
	v_mfma_f32_16x16x32_bf16 v[28:31], v[74:77], v[126:129], v[28:31]
	v_mfma_f32_16x16x32_bf16 v[24:27], v[82:85], v[126:129], v[24:27]
	v_mfma_f32_16x16x32_bf16 v[12:15], v[74:77], v[134:137], v[12:15]
	v_mfma_f32_16x16x32_bf16 v[8:11], v[82:85], v[134:137], v[8:11]
	v_mfma_f32_16x16x32_bf16 v[60:63], v[78:81], v[114:117], v[60:63]
	v_mfma_f32_16x16x32_bf16 v[56:59], v[90:93], v[114:117], v[56:59]
	v_mfma_f32_16x16x32_bf16 v[44:47], v[78:81], v[122:125], v[44:47]
	v_mfma_f32_16x16x32_bf16 v[40:43], v[90:93], v[122:125], v[40:43]
	v_mfma_f32_16x16x32_bf16 v[28:31], v[78:81], v[130:133], v[28:31]
	v_mfma_f32_16x16x32_bf16 v[24:27], v[90:93], v[130:133], v[24:27]
	v_mfma_f32_16x16x32_bf16 v[12:15], v[78:81], v[138:141], v[12:15]
	v_mfma_f32_16x16x32_bf16 v[8:11], v[90:93], v[138:141], v[8:11]
	s_setprio 0
	s_barrier
	s_add_i32 s18, s20, s4
	v_lshl_add_u64 v[126:127], v[142:143], 0, s[76:77]
	s_mov_b32 m0, s18
	ds_read_b128 v[74:77], v89 offset:49152
	ds_read_b128 v[78:81], v89 offset:50176
	ds_read_b128 v[82:85], v89 offset:51200
	ds_read_b128 v[90:93], v89 offset:52224
	ds_read_b128 v[110:113], v89 offset:53248
	ds_read_b128 v[114:117], v89 offset:54272
	ds_read_b128 v[118:121], v89 offset:55296
	ds_read_b128 v[122:125], v89 offset:56320
	global_load_lds_dwordx4 v[126:127], off
	s_add_i32 m0, s18, 0x2000
	s_add_u32 s18, s50, 0x1080
	v_lshl_add_u64 v[126:127], v[144:145], 0, s[76:77]
	s_addc_u32 s19, s51, 0
	s_add_i32 s20, s21, s4
	global_load_lds_dwordx4 v[126:127], off
	v_lshl_add_u64 v[126:127], s[18:19], 0, v[162:163]
	s_mov_b32 m0, s20
	s_nop 0
	global_load_lds_dwordx4 v[126:127], off
	v_lshl_add_u64 v[126:127], s[18:19], 0, v[64:65]
	s_add_i32 m0, s20, 0x2000
	s_nop 0
	global_load_lds_dwordx4 v[126:127], off
	v_lshl_add_u64 v[126:127], v[146:147], 0, s[76:77]
	s_mov_b32 m0, s11
	s_nop 0
	global_load_lds_dwordx4 v[126:127], off
	v_lshl_add_u64 v[126:127], v[148:149], 0, s[76:77]
	s_mov_b32 m0, s12
	s_nop 0
	global_load_lds_dwordx4 v[126:127], off
	s_waitcnt vmcnt(8)
	s_waitcnt lgkmcnt(0)
	s_barrier
	s_setprio 1
	s_waitcnt lgkmcnt(0)
	v_mfma_f32_16x16x32_bf16 v[52:55], v[94:97], v[74:77], v[52:55]
	v_mfma_f32_16x16x32_bf16 v[48:51], v[102:105], v[74:77], v[48:51]
	v_mfma_f32_16x16x32_bf16 v[36:39], v[94:97], v[82:85], v[36:39]
	v_mfma_f32_16x16x32_bf16 v[32:35], v[102:105], v[82:85], v[32:35]
	v_mfma_f32_16x16x32_bf16 v[20:23], v[94:97], v[110:113], v[20:23]
	v_mfma_f32_16x16x32_bf16 v[16:19], v[102:105], v[110:113], v[16:19]
	v_mfma_f32_16x16x32_bf16 v[4:7], v[94:97], v[118:121], v[4:7]
	v_mfma_f32_16x16x32_bf16 v[0:3], v[102:105], v[118:121], v[0:3]
	v_mfma_f32_16x16x32_bf16 v[52:55], v[98:101], v[78:81], v[52:55]
	v_mfma_f32_16x16x32_bf16 v[48:51], v[106:109], v[78:81], v[48:51]
	v_mfma_f32_16x16x32_bf16 v[36:39], v[98:101], v[90:93], v[36:39]
	v_mfma_f32_16x16x32_bf16 v[32:35], v[106:109], v[90:93], v[32:35]
	v_mfma_f32_16x16x32_bf16 v[20:23], v[98:101], v[114:117], v[20:23]
	v_mfma_f32_16x16x32_bf16 v[16:19], v[106:109], v[114:117], v[16:19]
	v_mfma_f32_16x16x32_bf16 v[4:7], v[98:101], v[122:125], v[4:7]
	v_mfma_f32_16x16x32_bf16 v[0:3], v[106:109], v[122:125], v[0:3]
	s_setprio 0
	s_barrier
	s_add_i32 s46, s46, 2
	s_add_u32 s66, s66, 0x100
	s_addc_u32 s67, s67, 0
	s_add_u32 s41, s41, 0x100
	s_addc_u32 s43, s43, 0
	s_cmp_gt_u32 s46, 29
	s_cbranch_scc0 .LBB0_891
	s_branch .Lpeel_x_891

.Lpeel_x_891:
	s_and_b64 vcc, exec, s[38:39]
	s_cbranch_vccz .LBB0_894
	s_barrier

.LBB0_913:
	s_add_i32 s11, s11, 1
	s_mov_b32 s13, s12
	s_mul_i32 s12, s11, s86
	s_add_i32 s12, s12, s45
	s_cmp_lt_u32 s12, 16
	s_mov_b32 s26, s40
	s_cselect_b64 s[48:49], -1, 0
	s_lshr_b32 s40, s12, 1
	s_mov_b32 s41, s27
	s_and_b32 s12, s12, 1
	s_lshl_b64 s[16:17], s[40:41], 19
	s_add_u32 s16, s21, s16
	s_addc_u32 s17, s22, s17
	s_lshl_b32 s18, s12, 18
	s_add_u32 s18, s16, s18
	s_addc_u32 s19, s17, 0
	s_mov_b64 s[14:15], s[42:43]
	s_and_b64 s[16:17], s[48:49], exec
	s_cselect_b32 s43, s19, s15
	s_cselect_b32 s42, s18, s14
	s_add_u32 s14, s14, 0x100
	s_addc_u32 s15, s15, 0
	s_mov_b32 s16, -2
	s_mov_b64 s[58:59], 0
	s_add_u32 s60, s58, 0x100
	s_addc_u32 s61, s59, 0
	s_add_u32 s17, s14, s58
	s_addc_u32 s18, s15, s59
	s_cmp_eq_u32 s16, 4
	s_cselect_b32 s20, 0, s60
	s_cselect_b32 s19, 0, s61
	s_cselect_b32 s50, s42, s17
	s_cselect_b32 s51, s43, s18
	s_add_u32 s62, s88, s20
	s_addc_u32 s63, s89, s19
	s_add_i32 s17, 0, 0x10000
	v_add_u32_e32 v142, s17, v144
	s_add_i32 s20, 0, 0x14000
	ds_read_b128 v[146:149], v142
	ds_read_b128 v[150:153], v142 offset:1024
	ds_read_b128 v[154:157], v142 offset:2048
	ds_read_b128 v[164:167], v142 offset:3072
	v_add_u32_e32 v142, s20, v144
	ds_read_b128 v[168:171], v142
	ds_read_b128 v[172:175], v142 offset:1024
	ds_read_b128 v[176:179], v142 offset:2048
	ds_read_b128 v[180:183], v142 offset:3072
	v_lshl_add_u64 v[142:143], v[138:139], 0, s[58:59]
	s_add_i32 m0, s5, 0xc000
	ds_read_b128 v[184:187], v145
	ds_read_b128 v[188:191], v145 offset:1024
	ds_read_b128 v[192:195], v145 offset:2048
	ds_read_b128 v[196:199], v145 offset:3072
	ds_read_b128 v[206:209], v145 offset:4096
	ds_read_b128 v[210:213], v145 offset:5120
	ds_read_b128 v[214:217], v145 offset:6144
	ds_read_b128 v[218:221], v145 offset:7168
	global_load_lds_dwordx4 v[142:143], off
	v_lshl_add_u64 v[142:143], v[140:141], 0, s[58:59]
	s_add_i32 m0, s5, 0xe000
	s_nop 0
	global_load_lds_dwordx4 v[142:143], off
	s_waitcnt vmcnt(8)
	s_waitcnt lgkmcnt(0)
	s_barrier
	s_setprio 1
	s_waitcnt lgkmcnt(0)
	v_mfma_f32_16x16x32_bf16 v[124:127], v[146:149], v[184:187], 0
	v_mfma_f32_16x16x32_bf16 v[120:123], v[154:157], v[184:187], 0
	v_mfma_f32_16x16x32_bf16 v[116:119], v[146:149], v[192:195], 0
	v_mfma_f32_16x16x32_bf16 v[108:111], v[154:157], v[192:195], 0
	v_mfma_f32_16x16x32_bf16 v[100:103], v[146:149], v[206:209], 0
	v_mfma_f32_16x16x32_bf16 v[92:95], v[154:157], v[206:209], 0
	v_mfma_f32_16x16x32_bf16 v[84:87], v[146:149], v[214:217], 0
	v_mfma_f32_16x16x32_bf16 v[76:79], v[154:157], v[214:217], 0
	v_mfma_f32_16x16x32_bf16 v[124:127], v[150:153], v[188:191], v[124:127]
	v_mfma_f32_16x16x32_bf16 v[120:123], v[164:167], v[188:191], v[120:123]
	v_mfma_f32_16x16x32_bf16 v[116:119], v[150:153], v[196:199], v[116:119]
	v_mfma_f32_16x16x32_bf16 v[108:111], v[164:167], v[196:199], v[108:111]
	v_mfma_f32_16x16x32_bf16 v[100:103], v[150:153], v[210:213], v[100:103]
	v_mfma_f32_16x16x32_bf16 v[92:95], v[164:167], v[210:213], v[92:95]
	v_mfma_f32_16x16x32_bf16 v[84:87], v[150:153], v[218:221], v[84:87]
	v_mfma_f32_16x16x32_bf16 v[76:79], v[164:167], v[218:221], v[76:79]
	s_setprio 0
	s_setprio 1
	v_mfma_f32_16x16x32_bf16 v[112:115], v[168:171], v[184:187], 0
	v_mfma_f32_16x16x32_bf16 v[104:107], v[176:179], v[184:187], 0
	v_mfma_f32_16x16x32_bf16 v[96:99], v[168:171], v[192:195], 0
	v_mfma_f32_16x16x32_bf16 v[88:91], v[176:179], v[192:195], 0
	v_mfma_f32_16x16x32_bf16 v[80:83], v[168:171], v[206:209], 0
	v_mfma_f32_16x16x32_bf16 v[72:75], v[176:179], v[206:209], 0
	v_mfma_f32_16x16x32_bf16 v[68:71], v[168:171], v[214:217], 0
	v_mfma_f32_16x16x32_bf16 v[64:67], v[176:179], v[214:217], 0
	v_mfma_f32_16x16x32_bf16 v[112:115], v[172:175], v[188:191], v[112:115]
	v_mfma_f32_16x16x32_bf16 v[104:107], v[180:183], v[188:191], v[104:107]
	v_mfma_f32_16x16x32_bf16 v[96:99], v[172:175], v[196:199], v[96:99]
	v_mfma_f32_16x16x32_bf16 v[88:91], v[180:183], v[196:199], v[88:91]
	v_mfma_f32_16x16x32_bf16 v[80:83], v[172:175], v[210:213], v[80:83]
	v_mfma_f32_16x16x32_bf16 v[72:75], v[180:183], v[210:213], v[72:75]
	v_mfma_f32_16x16x32_bf16 v[68:71], v[172:175], v[218:221], v[68:71]
	v_mfma_f32_16x16x32_bf16 v[64:67], v[180:183], v[218:221], v[64:67]
	s_setprio 0
	s_barrier
	s_add_i32 s17, s17, s4
	v_lshl_add_u64 v[142:143], s[50:51], 0, v[132:133]
	s_mov_b32 m0, s17
	ds_read_b128 v[184:187], v145 offset:16384
	ds_read_b128 v[188:191], v145 offset:17408
	ds_read_b128 v[192:195], v145 offset:18432
	ds_read_b128 v[196:199], v145 offset:19456
	ds_read_b128 v[206:209], v145 offset:20480
	ds_read_b128 v[210:213], v145 offset:21504
	ds_read_b128 v[214:217], v145 offset:22528
	ds_read_b128 v[218:221], v145 offset:23552
	global_load_lds_dwordx4 v[142:143], off
	s_add_i32 m0, s17, 0x2000
	s_add_u32 s18, s50, 0x20000
	v_lshl_add_u64 v[158:159], s[50:51], 0, v[128:129]
	s_addc_u32 s19, s51, 0
	s_add_i32 s17, s20, s4
	global_load_lds_dwordx4 v[158:159], off
	v_lshl_add_u64 v[200:201], s[18:19], 0, v[132:133]
	s_mov_b32 m0, s17
	v_lshl_add_u64 v[222:223], s[62:63], 0, v[130:131]
	global_load_lds_dwordx4 v[200:201], off
	v_lshl_add_u64 v[200:201], s[18:19], 0, v[128:129]
	s_add_i32 m0, s17, 0x2000
	s_nop 0
	global_load_lds_dwordx4 v[200:201], off
	v_lshl_add_u64 v[200:201], s[62:63], 0, v[134:135]
	s_mov_b32 m0, s5
	s_nop 0
	global_load_lds_dwordx4 v[200:201], off
	s_mov_b32 m0, s6
	s_nop 0
	global_load_lds_dwordx4 v[222:223], off
	s_waitcnt vmcnt(8)
	s_waitcnt lgkmcnt(0)
	s_barrier
	s_setprio 1
	s_waitcnt lgkmcnt(0)
	v_mfma_f32_16x16x32_bf16 v[60:63], v[146:149], v[184:187], 0
	v_mfma_f32_16x16x32_bf16 v[56:59], v[154:157], v[184:187], 0
	v_mfma_f32_16x16x32_bf16 v[52:55], v[146:149], v[192:195], 0
	v_mfma_f32_16x16x32_bf16 v[44:47], v[154:157], v[192:195], 0
	v_mfma_f32_16x16x32_bf16 v[36:39], v[146:149], v[206:209], 0
	v_mfma_f32_16x16x32_bf16 v[28:31], v[154:157], v[206:209], 0
	v_mfma_f32_16x16x32_bf16 v[20:23], v[146:149], v[214:217], 0
	v_mfma_f32_16x16x32_bf16 v[12:15], v[154:157], v[214:217], 0
	v_mfma_f32_16x16x32_bf16 v[60:63], v[150:153], v[188:191], v[60:63]
	v_mfma_f32_16x16x32_bf16 v[56:59], v[164:167], v[188:191], v[56:59]
	v_mfma_f32_16x16x32_bf16 v[52:55], v[150:153], v[196:199], v[52:55]
	v_mfma_f32_16x16x32_bf16 v[44:47], v[164:167], v[196:199], v[44:47]
	v_mfma_f32_16x16x32_bf16 v[36:39], v[150:153], v[210:213], v[36:39]
	v_mfma_f32_16x16x32_bf16 v[28:31], v[164:167], v[210:213], v[28:31]
	v_mfma_f32_16x16x32_bf16 v[20:23], v[150:153], v[218:221], v[20:23]
	v_mfma_f32_16x16x32_bf16 v[12:15], v[164:167], v[218:221], v[12:15]
	s_setprio 0
	s_setprio 1
	v_mfma_f32_16x16x32_bf16 v[48:51], v[168:171], v[184:187], 0
	v_mfma_f32_16x16x32_bf16 v[40:43], v[176:179], v[184:187], 0
	v_mfma_f32_16x16x32_bf16 v[32:35], v[168:171], v[192:195], 0
	v_mfma_f32_16x16x32_bf16 v[24:27], v[176:179], v[192:195], 0
	v_mfma_f32_16x16x32_bf16 v[16:19], v[168:171], v[206:209], 0
	v_mfma_f32_16x16x32_bf16 v[8:11], v[176:179], v[206:209], 0
	v_mfma_f32_16x16x32_bf16 v[4:7], v[168:171], v[214:217], 0
	v_mfma_f32_16x16x32_bf16 v[0:3], v[176:179], v[214:217], 0
	v_mfma_f32_16x16x32_bf16 v[48:51], v[172:175], v[188:191], v[48:51]
	v_mfma_f32_16x16x32_bf16 v[40:43], v[180:183], v[188:191], v[40:43]
	v_mfma_f32_16x16x32_bf16 v[32:35], v[172:175], v[196:199], v[32:35]
	v_mfma_f32_16x16x32_bf16 v[24:27], v[180:183], v[196:199], v[24:27]
	v_mfma_f32_16x16x32_bf16 v[16:19], v[172:175], v[210:213], v[16:19]
	v_mfma_f32_16x16x32_bf16 v[8:11], v[180:183], v[210:213], v[8:11]
	v_mfma_f32_16x16x32_bf16 v[4:7], v[172:175], v[218:221], v[4:7]
	v_mfma_f32_16x16x32_bf16 v[0:3], v[180:183], v[218:221], v[0:3]
	s_setprio 0
	s_barrier
	s_add_i32 s17, 0, 0x18000
	s_add_i32 s20, 0, 0x1c000
	v_add_u32_e32 v164, s17, v144
	v_add_u32_e32 v180, s20, v144
	ds_read_b128 v[146:149], v164
	ds_read_b128 v[150:153], v164 offset:1024
	ds_read_b128 v[154:157], v164 offset:2048
	ds_read_b128 v[164:167], v164 offset:3072
	ds_read_b128 v[168:171], v180
	ds_read_b128 v[172:175], v180 offset:1024
	ds_read_b128 v[176:179], v180 offset:2048
	ds_read_b128 v[180:183], v180 offset:3072
	s_add_u32 s18, s62, 0x20000
	s_addc_u32 s19, s63, 0
	s_mov_b32 m0, s7
	v_lshl_add_u64 v[224:225], s[18:19], 0, v[134:135]
	ds_read_b128 v[184:187], v145 offset:32768
	ds_read_b128 v[188:191], v145 offset:33792
	ds_read_b128 v[192:195], v145 offset:34816
	ds_read_b128 v[196:199], v145 offset:35840
	ds_read_b128 v[206:209], v145 offset:36864
	ds_read_b128 v[210:213], v145 offset:37888
	ds_read_b128 v[214:217], v145 offset:38912
	ds_read_b128 v[218:221], v145 offset:39936
	global_load_lds_dwordx4 v[224:225], off
	v_lshl_add_u64 v[224:225], s[18:19], 0, v[130:131]
	s_mov_b32 m0, s8
	s_nop 0
	global_load_lds_dwordx4 v[224:225], off
	s_waitcnt vmcnt(8)
	s_waitcnt lgkmcnt(0)
	s_barrier
	s_setprio 1
	s_waitcnt lgkmcnt(0)
	v_mfma_f32_16x16x32_bf16 v[124:127], v[146:149], v[184:187], v[124:127]
	v_mfma_f32_16x16x32_bf16 v[120:123], v[154:157], v[184:187], v[120:123]
	v_mfma_f32_16x16x32_bf16 v[116:119], v[146:149], v[192:195], v[116:119]
	v_mfma_f32_16x16x32_bf16 v[108:111], v[154:157], v[192:195], v[108:111]
	v_mfma_f32_16x16x32_bf16 v[100:103], v[146:149], v[206:209], v[100:103]
	v_mfma_f32_16x16x32_bf16 v[92:95], v[154:157], v[206:209], v[92:95]
	v_mfma_f32_16x16x32_bf16 v[84:87], v[146:149], v[214:217], v[84:87]
	v_mfma_f32_16x16x32_bf16 v[76:79], v[154:157], v[214:217], v[76:79]
	v_mfma_f32_16x16x32_bf16 v[124:127], v[150:153], v[188:191], v[124:127]
	v_mfma_f32_16x16x32_bf16 v[120:123], v[164:167], v[188:191], v[120:123]
	v_mfma_f32_16x16x32_bf16 v[116:119], v[150:153], v[196:199], v[116:119]
	v_mfma_f32_16x16x32_bf16 v[108:111], v[164:167], v[196:199], v[108:111]
	v_mfma_f32_16x16x32_bf16 v[100:103], v[150:153], v[210:213], v[100:103]
	v_mfma_f32_16x16x32_bf16 v[92:95], v[164:167], v[210:213], v[92:95]
	v_mfma_f32_16x16x32_bf16 v[84:87], v[150:153], v[218:221], v[84:87]
	v_mfma_f32_16x16x32_bf16 v[76:79], v[164:167], v[218:221], v[76:79]
	s_setprio 0
	s_setprio 1
	v_mfma_f32_16x16x32_bf16 v[112:115], v[168:171], v[184:187], v[112:115]
	v_mfma_f32_16x16x32_bf16 v[104:107], v[176:179], v[184:187], v[104:107]
	v_mfma_f32_16x16x32_bf16 v[96:99], v[168:171], v[192:195], v[96:99]
	v_mfma_f32_16x16x32_bf16 v[88:91], v[176:179], v[192:195], v[88:91]
	v_mfma_f32_16x16x32_bf16 v[80:83], v[168:171], v[206:209], v[80:83]
	v_mfma_f32_16x16x32_bf16 v[72:75], v[176:179], v[206:209], v[72:75]
	v_mfma_f32_16x16x32_bf16 v[68:71], v[168:171], v[214:217], v[68:71]
	v_mfma_f32_16x16x32_bf16 v[64:67], v[176:179], v[214:217], v[64:67]
	v_mfma_f32_16x16x32_bf16 v[112:115], v[172:175], v[188:191], v[112:115]
	v_mfma_f32_16x16x32_bf16 v[104:107], v[180:183], v[188:191], v[104:107]
	v_mfma_f32_16x16x32_bf16 v[96:99], v[172:175], v[196:199], v[96:99]
	v_mfma_f32_16x16x32_bf16 v[88:91], v[180:183], v[196:199], v[88:91]
	v_mfma_f32_16x16x32_bf16 v[80:83], v[172:175], v[210:213], v[80:83]
	v_mfma_f32_16x16x32_bf16 v[72:75], v[180:183], v[210:213], v[72:75]
	v_mfma_f32_16x16x32_bf16 v[68:71], v[172:175], v[218:221], v[68:71]
	v_mfma_f32_16x16x32_bf16 v[64:67], v[180:183], v[218:221], v[64:67]
	s_setprio 0
	s_barrier
	s_add_i32 s17, s17, s4
	v_lshl_add_u64 v[142:143], v[142:143], 0, s[76:77]
	s_mov_b32 m0, s17
	ds_read_b128 v[184:187], v145 offset:49152
	ds_read_b128 v[188:191], v145 offset:50176
	ds_read_b128 v[192:195], v145 offset:51200
	ds_read_b128 v[196:199], v145 offset:52224
	ds_read_b128 v[206:209], v145 offset:53248
	ds_read_b128 v[210:213], v145 offset:54272
	ds_read_b128 v[214:217], v145 offset:55296
	ds_read_b128 v[218:221], v145 offset:56320
	global_load_lds_dwordx4 v[142:143], off
	s_add_i32 m0, s17, 0x2000
	s_add_u32 s18, s50, 0x20080
	v_lshl_add_u64 v[142:143], v[158:159], 0, s[76:77]
	s_addc_u32 s19, s51, 0
	s_add_i32 s17, s20, s4
	global_load_lds_dwordx4 v[142:143], off
	v_lshl_add_u64 v[142:143], s[18:19], 0, v[132:133]
	s_mov_b32 m0, s17
	s_nop 0
	global_load_lds_dwordx4 v[142:143], off
	v_lshl_add_u64 v[142:143], s[18:19], 0, v[128:129]
	s_add_i32 m0, s17, 0x2000
	s_nop 0
	global_load_lds_dwordx4 v[142:143], off
	v_lshl_add_u64 v[142:143], v[200:201], 0, s[76:77]
	s_mov_b32 m0, s9
	s_nop 0
	global_load_lds_dwordx4 v[142:143], off
	v_lshl_add_u64 v[142:143], v[222:223], 0, s[76:77]
	s_mov_b32 m0, s10
	s_nop 0
	global_load_lds_dwordx4 v[142:143], off
	s_waitcnt vmcnt(8)
	s_waitcnt lgkmcnt(0)
	s_barrier
	s_setprio 1
	s_waitcnt lgkmcnt(0)
	v_mfma_f32_16x16x32_bf16 v[60:63], v[146:149], v[184:187], v[60:63]
	v_mfma_f32_16x16x32_bf16 v[56:59], v[154:157], v[184:187], v[56:59]
	v_mfma_f32_16x16x32_bf16 v[52:55], v[146:149], v[192:195], v[52:55]
	v_mfma_f32_16x16x32_bf16 v[44:47], v[154:157], v[192:195], v[44:47]
	v_mfma_f32_16x16x32_bf16 v[36:39], v[146:149], v[206:209], v[36:39]
	v_mfma_f32_16x16x32_bf16 v[28:31], v[154:157], v[206:209], v[28:31]
	v_mfma_f32_16x16x32_bf16 v[20:23], v[146:149], v[214:217], v[20:23]
	v_mfma_f32_16x16x32_bf16 v[12:15], v[154:157], v[214:217], v[12:15]
	v_mfma_f32_16x16x32_bf16 v[60:63], v[150:153], v[188:191], v[60:63]
	v_mfma_f32_16x16x32_bf16 v[56:59], v[164:167], v[188:191], v[56:59]
	v_mfma_f32_16x16x32_bf16 v[52:55], v[150:153], v[196:199], v[52:55]
	v_mfma_f32_16x16x32_bf16 v[44:47], v[164:167], v[196:199], v[44:47]
	v_mfma_f32_16x16x32_bf16 v[36:39], v[150:153], v[210:213], v[36:39]
	v_mfma_f32_16x16x32_bf16 v[28:31], v[164:167], v[210:213], v[28:31]
	v_mfma_f32_16x16x32_bf16 v[20:23], v[150:153], v[218:221], v[20:23]
	v_mfma_f32_16x16x32_bf16 v[12:15], v[164:167], v[218:221], v[12:15]
	s_setprio 0
	s_setprio 1
	v_mfma_f32_16x16x32_bf16 v[48:51], v[168:171], v[184:187], v[48:51]
	v_mfma_f32_16x16x32_bf16 v[40:43], v[176:179], v[184:187], v[40:43]
	v_mfma_f32_16x16x32_bf16 v[32:35], v[168:171], v[192:195], v[32:35]
	v_mfma_f32_16x16x32_bf16 v[24:27], v[176:179], v[192:195], v[24:27]
	v_mfma_f32_16x16x32_bf16 v[16:19], v[168:171], v[206:209], v[16:19]
	v_mfma_f32_16x16x32_bf16 v[8:11], v[176:179], v[206:209], v[8:11]
	v_mfma_f32_16x16x32_bf16 v[4:7], v[168:171], v[214:217], v[4:7]
	v_mfma_f32_16x16x32_bf16 v[0:3], v[176:179], v[214:217], v[0:3]
	v_mfma_f32_16x16x32_bf16 v[48:51], v[172:175], v[188:191], v[48:51]
	v_mfma_f32_16x16x32_bf16 v[40:43], v[180:183], v[188:191], v[40:43]
	v_mfma_f32_16x16x32_bf16 v[32:35], v[172:175], v[196:199], v[32:35]
	v_mfma_f32_16x16x32_bf16 v[24:27], v[180:183], v[196:199], v[24:27]
	v_mfma_f32_16x16x32_bf16 v[16:19], v[172:175], v[210:213], v[16:19]
	v_mfma_f32_16x16x32_bf16 v[8:11], v[180:183], v[210:213], v[8:11]
	v_mfma_f32_16x16x32_bf16 v[4:7], v[172:175], v[218:221], v[4:7]
	v_mfma_f32_16x16x32_bf16 v[0:3], v[180:183], v[218:221], v[0:3]
	s_setprio 0
	s_barrier
	s_add_i32 s16, s16, 2
	s_cmp_gt_u32 s16, 5
	s_mov_b64 s[58:59], s[60:61]
	s_cbranch_scc0 .LBB0_914
	s_branch .Lpeel_x_914

.LBB0_982:
	s_ashr_i32 s37, s36, 31
	s_lshl_b64 s[16:17], s[36:37], 19
	s_add_u32 s40, s94, s16
	s_addc_u32 s41, s95, s17
	s_and_b64 s[16:17], s[42:43], exec
	s_cselect_b32 s15, s41, s51
	s_cselect_b32 s16, s40, s50
	s_ashr_i32 s39, s38, 31
	s_lshl_b64 s[18:19], s[38:39], 19
	s_add_u32 s48, s22, s18
	s_addc_u32 s49, s23, s19
	s_and_b64 s[18:19], s[42:43], exec
	s_cselect_b32 s17, s49, s61
	s_cselect_b32 s37, s48, s60
	s_add_u32 s58, s50, 0x40080
	s_addc_u32 s59, s51, 0
	s_add_u32 s39, s60, 0x100
	s_addc_u32 s47, s61, 0
	s_mov_b32 s54, -2
	s_add_u32 s18, s58, 0xfffc0080
	s_addc_u32 s19, s59, -1
	s_add_i32 s20, 0, 0x10000
	s_cmp_eq_u32 s54, 12
	s_cselect_b32 s61, s15, s19
	s_cselect_b32 s60, s16, s18
	s_cselect_b32 s51, s17, s47
	s_cselect_b32 s50, s37, s39
	s_add_i32 s21, 0, 0x14000
	v_add_u32_e32 v140, s20, v174
	v_add_u32_e32 v162, s21, v174
	ds_read_b128 v[128:131], v140
	ds_read_b128 v[132:135], v140 offset:1024
	ds_read_b128 v[136:139], v140 offset:2048
	ds_read_b128 v[140:143], v140 offset:3072
	ds_read_b128 v[156:159], v162
	ds_read_b128 v[164:167], v162 offset:1024
	ds_read_b128 v[168:171], v162 offset:2048
	ds_read_b128 v[176:179], v162 offset:3072
	v_lshl_add_u64 v[200:201], s[58:59], 0, v[152:153]
	s_add_i32 m0, s4, 0xc000
	ds_read_b128 v[180:183], v175
	ds_read_b128 v[184:187], v175 offset:1024
	ds_read_b128 v[188:191], v175 offset:2048
	ds_read_b128 v[192:195], v175 offset:3072
	ds_read_b128 v[196:199], v175 offset:4096
	ds_read_b128 v[206:209], v175 offset:5120
	ds_read_b128 v[210:213], v175 offset:6144
	ds_read_b128 v[214:217], v175 offset:7168
	global_load_lds_dwordx4 v[200:201], off
	v_lshl_add_u64 v[200:201], s[58:59], 0, v[154:155]
	s_add_i32 m0, s4, 0xe000
	s_nop 0
	global_load_lds_dwordx4 v[200:201], off
	s_waitcnt vmcnt(8)
	s_waitcnt lgkmcnt(0)
	s_barrier
	s_setprio 1
	s_waitcnt lgkmcnt(0)
	v_mfma_f32_16x16x32_bf16 v[124:127], v[128:131], v[180:183], 0
	v_mfma_f32_16x16x32_bf16 v[120:123], v[136:139], v[180:183], 0
	v_mfma_f32_16x16x32_bf16 v[112:115], v[128:131], v[188:191], 0
	v_mfma_f32_16x16x32_bf16 v[104:107], v[136:139], v[188:191], 0
	v_mfma_f32_16x16x32_bf16 v[96:99], v[128:131], v[196:199], 0
	v_mfma_f32_16x16x32_bf16 v[88:91], v[136:139], v[196:199], 0
	v_mfma_f32_16x16x32_bf16 v[80:83], v[128:131], v[210:213], 0
	v_mfma_f32_16x16x32_bf16 v[72:75], v[136:139], v[210:213], 0
	v_mfma_f32_16x16x32_bf16 v[124:127], v[132:135], v[184:187], v[124:127]
	v_mfma_f32_16x16x32_bf16 v[120:123], v[140:143], v[184:187], v[120:123]
	v_mfma_f32_16x16x32_bf16 v[112:115], v[132:135], v[192:195], v[112:115]
	v_mfma_f32_16x16x32_bf16 v[104:107], v[140:143], v[192:195], v[104:107]
	v_mfma_f32_16x16x32_bf16 v[96:99], v[132:135], v[206:209], v[96:99]
	v_mfma_f32_16x16x32_bf16 v[88:91], v[140:143], v[206:209], v[88:91]
	v_mfma_f32_16x16x32_bf16 v[80:83], v[132:135], v[214:217], v[80:83]
	v_mfma_f32_16x16x32_bf16 v[72:75], v[140:143], v[214:217], v[72:75]
	s_setprio 0
	s_setprio 1
	v_mfma_f32_16x16x32_bf16 v[116:119], v[156:159], v[180:183], 0
	v_mfma_f32_16x16x32_bf16 v[108:111], v[168:171], v[180:183], 0
	v_mfma_f32_16x16x32_bf16 v[100:103], v[156:159], v[188:191], 0
	v_mfma_f32_16x16x32_bf16 v[92:95], v[168:171], v[188:191], 0
	v_mfma_f32_16x16x32_bf16 v[84:87], v[156:159], v[196:199], 0
	v_mfma_f32_16x16x32_bf16 v[76:79], v[168:171], v[196:199], 0
	v_mfma_f32_16x16x32_bf16 v[68:71], v[156:159], v[210:213], 0
	v_mfma_f32_16x16x32_bf16 v[64:67], v[168:171], v[210:213], 0
	v_mfma_f32_16x16x32_bf16 v[116:119], v[164:167], v[184:187], v[116:119]
	v_mfma_f32_16x16x32_bf16 v[108:111], v[176:179], v[184:187], v[108:111]
	v_mfma_f32_16x16x32_bf16 v[100:103], v[164:167], v[192:195], v[100:103]
	v_mfma_f32_16x16x32_bf16 v[92:95], v[176:179], v[192:195], v[92:95]
	v_mfma_f32_16x16x32_bf16 v[84:87], v[164:167], v[206:209], v[84:87]
	v_mfma_f32_16x16x32_bf16 v[76:79], v[176:179], v[206:209], v[76:79]
	v_mfma_f32_16x16x32_bf16 v[68:71], v[164:167], v[214:217], v[68:71]
	v_mfma_f32_16x16x32_bf16 v[64:67], v[176:179], v[214:217], v[64:67]
	s_setprio 0
	s_barrier
	s_add_i32 s18, s20, s46
	v_lshl_add_u64 v[200:201], s[50:51], 0, v[148:149]
	s_mov_b32 m0, s18
	ds_read_b128 v[180:183], v175 offset:16384
	ds_read_b128 v[184:187], v175 offset:17408
	ds_read_b128 v[188:191], v175 offset:18432
	ds_read_b128 v[192:195], v175 offset:19456
	ds_read_b128 v[196:199], v175 offset:20480
	ds_read_b128 v[206:209], v175 offset:21504
	ds_read_b128 v[210:213], v175 offset:22528
	ds_read_b128 v[214:217], v175 offset:23552
	global_load_lds_dwordx4 v[200:201], off
	s_add_i32 m0, s18, 0x2000
	s_add_u32 s18, s50, 0x40000
	v_lshl_add_u64 v[218:219], s[50:51], 0, v[144:145]
	s_addc_u32 s19, s51, 0
	s_add_i32 s20, s21, s46
	global_load_lds_dwordx4 v[218:219], off
	v_lshl_add_u64 v[220:221], s[18:19], 0, v[148:149]
	s_mov_b32 m0, s20
	v_lshl_add_u64 v[222:223], s[60:61], 0, v[146:147]
	global_load_lds_dwordx4 v[220:221], off
	v_lshl_add_u64 v[220:221], s[18:19], 0, v[144:145]
	s_add_i32 m0, s20, 0x2000
	s_nop 0
	global_load_lds_dwordx4 v[220:221], off
	v_lshl_add_u64 v[220:221], s[60:61], 0, v[150:151]
	s_mov_b32 m0, s4
	s_nop 0
	global_load_lds_dwordx4 v[220:221], off
	s_mov_b32 m0, s5
	s_nop 0
	global_load_lds_dwordx4 v[222:223], off
	s_waitcnt vmcnt(8)
	s_waitcnt lgkmcnt(0)
	s_barrier
	s_setprio 1
	s_waitcnt lgkmcnt(0)
	v_mfma_f32_16x16x32_bf16 v[60:63], v[128:131], v[180:183], 0
	v_mfma_f32_16x16x32_bf16 v[56:59], v[136:139], v[180:183], 0
	v_mfma_f32_16x16x32_bf16 v[48:51], v[128:131], v[188:191], 0
	v_mfma_f32_16x16x32_bf16 v[40:43], v[136:139], v[188:191], 0
	v_mfma_f32_16x16x32_bf16 v[32:35], v[128:131], v[196:199], 0
	v_mfma_f32_16x16x32_bf16 v[24:27], v[136:139], v[196:199], 0
	v_mfma_f32_16x16x32_bf16 v[16:19], v[128:131], v[210:213], 0
	v_mfma_f32_16x16x32_bf16 v[8:11], v[136:139], v[210:213], 0
	v_mfma_f32_16x16x32_bf16 v[60:63], v[132:135], v[184:187], v[60:63]
	v_mfma_f32_16x16x32_bf16 v[56:59], v[140:143], v[184:187], v[56:59]
	v_mfma_f32_16x16x32_bf16 v[48:51], v[132:135], v[192:195], v[48:51]
	v_mfma_f32_16x16x32_bf16 v[40:43], v[140:143], v[192:195], v[40:43]
	v_mfma_f32_16x16x32_bf16 v[32:35], v[132:135], v[206:209], v[32:35]
	v_mfma_f32_16x16x32_bf16 v[24:27], v[140:143], v[206:209], v[24:27]
	v_mfma_f32_16x16x32_bf16 v[16:19], v[132:135], v[214:217], v[16:19]
	v_mfma_f32_16x16x32_bf16 v[8:11], v[140:143], v[214:217], v[8:11]
	s_setprio 0
	s_setprio 1
	v_mfma_f32_16x16x32_bf16 v[52:55], v[156:159], v[180:183], 0
	v_mfma_f32_16x16x32_bf16 v[44:47], v[168:171], v[180:183], 0
	v_mfma_f32_16x16x32_bf16 v[36:39], v[156:159], v[188:191], 0
	v_mfma_f32_16x16x32_bf16 v[28:31], v[168:171], v[188:191], 0
	v_mfma_f32_16x16x32_bf16 v[20:23], v[156:159], v[196:199], 0
	v_mfma_f32_16x16x32_bf16 v[12:15], v[168:171], v[196:199], 0
	v_mfma_f32_16x16x32_bf16 v[4:7], v[156:159], v[210:213], 0
	v_mfma_f32_16x16x32_bf16 v[0:3], v[168:171], v[210:213], 0
	v_mfma_f32_16x16x32_bf16 v[52:55], v[164:167], v[184:187], v[52:55]
	v_mfma_f32_16x16x32_bf16 v[44:47], v[176:179], v[184:187], v[44:47]
	v_mfma_f32_16x16x32_bf16 v[36:39], v[164:167], v[192:195], v[36:39]
	v_mfma_f32_16x16x32_bf16 v[28:31], v[176:179], v[192:195], v[28:31]
	v_mfma_f32_16x16x32_bf16 v[20:23], v[164:167], v[206:209], v[20:23]
	v_mfma_f32_16x16x32_bf16 v[12:15], v[176:179], v[206:209], v[12:15]
	v_mfma_f32_16x16x32_bf16 v[4:7], v[164:167], v[214:217], v[4:7]
	v_mfma_f32_16x16x32_bf16 v[0:3], v[176:179], v[214:217], v[0:3]
	s_setprio 0
	s_barrier
	s_add_i32 s20, 0, 0x18000
	s_add_i32 s21, 0, 0x1c000
	v_add_u32_e32 v140, s20, v174
	v_add_u32_e32 v162, s21, v174
	ds_read_b128 v[128:131], v140
	ds_read_b128 v[132:135], v140 offset:1024
	ds_read_b128 v[136:139], v140 offset:2048
	ds_read_b128 v[140:143], v140 offset:3072
	ds_read_b128 v[156:159], v162
	ds_read_b128 v[164:167], v162 offset:1024
	ds_read_b128 v[168:171], v162 offset:2048
	ds_read_b128 v[176:179], v162 offset:3072
	s_add_u32 s18, s60, 0x40000
	s_addc_u32 s19, s61, 0
	s_mov_b32 m0, s6
	v_lshl_add_u64 v[224:225], s[18:19], 0, v[150:151]
	ds_read_b128 v[180:183], v175 offset:32768
	ds_read_b128 v[184:187], v175 offset:33792
	ds_read_b128 v[188:191], v175 offset:34816
	ds_read_b128 v[192:195], v175 offset:35840
	ds_read_b128 v[196:199], v175 offset:36864
	ds_read_b128 v[206:209], v175 offset:37888
	ds_read_b128 v[210:213], v175 offset:38912
	ds_read_b128 v[214:217], v175 offset:39936
	global_load_lds_dwordx4 v[224:225], off
	v_lshl_add_u64 v[224:225], s[18:19], 0, v[146:147]
	s_mov_b32 m0, s7
	s_nop 0
	global_load_lds_dwordx4 v[224:225], off
	s_waitcnt vmcnt(8)
	s_waitcnt lgkmcnt(0)
	s_barrier
	s_setprio 1
	s_waitcnt lgkmcnt(0)
	v_mfma_f32_16x16x32_bf16 v[124:127], v[128:131], v[180:183], v[124:127]
	v_mfma_f32_16x16x32_bf16 v[120:123], v[136:139], v[180:183], v[120:123]
	v_mfma_f32_16x16x32_bf16 v[112:115], v[128:131], v[188:191], v[112:115]
	v_mfma_f32_16x16x32_bf16 v[104:107], v[136:139], v[188:191], v[104:107]
	v_mfma_f32_16x16x32_bf16 v[96:99], v[128:131], v[196:199], v[96:99]
	v_mfma_f32_16x16x32_bf16 v[88:91], v[136:139], v[196:199], v[88:91]
	v_mfma_f32_16x16x32_bf16 v[80:83], v[128:131], v[210:213], v[80:83]
	v_mfma_f32_16x16x32_bf16 v[72:75], v[136:139], v[210:213], v[72:75]
	v_mfma_f32_16x16x32_bf16 v[124:127], v[132:135], v[184:187], v[124:127]
	v_mfma_f32_16x16x32_bf16 v[120:123], v[140:143], v[184:187], v[120:123]
	v_mfma_f32_16x16x32_bf16 v[112:115], v[132:135], v[192:195], v[112:115]
	v_mfma_f32_16x16x32_bf16 v[104:107], v[140:143], v[192:195], v[104:107]
	v_mfma_f32_16x16x32_bf16 v[96:99], v[132:135], v[206:209], v[96:99]
	v_mfma_f32_16x16x32_bf16 v[88:91], v[140:143], v[206:209], v[88:91]
	v_mfma_f32_16x16x32_bf16 v[80:83], v[132:135], v[214:217], v[80:83]
	v_mfma_f32_16x16x32_bf16 v[72:75], v[140:143], v[214:217], v[72:75]
	s_setprio 0
	s_setprio 1
	v_mfma_f32_16x16x32_bf16 v[116:119], v[156:159], v[180:183], v[116:119]
	v_mfma_f32_16x16x32_bf16 v[108:111], v[168:171], v[180:183], v[108:111]
	v_mfma_f32_16x16x32_bf16 v[100:103], v[156:159], v[188:191], v[100:103]
	v_mfma_f32_16x16x32_bf16 v[92:95], v[168:171], v[188:191], v[92:95]
	v_mfma_f32_16x16x32_bf16 v[84:87], v[156:159], v[196:199], v[84:87]
	v_mfma_f32_16x16x32_bf16 v[76:79], v[168:171], v[196:199], v[76:79]
	v_mfma_f32_16x16x32_bf16 v[68:71], v[156:159], v[210:213], v[68:71]
	v_mfma_f32_16x16x32_bf16 v[64:67], v[168:171], v[210:213], v[64:67]
	v_mfma_f32_16x16x32_bf16 v[116:119], v[164:167], v[184:187], v[116:119]
	v_mfma_f32_16x16x32_bf16 v[108:111], v[176:179], v[184:187], v[108:111]
	v_mfma_f32_16x16x32_bf16 v[100:103], v[164:167], v[192:195], v[100:103]
	v_mfma_f32_16x16x32_bf16 v[92:95], v[176:179], v[192:195], v[92:95]
	v_mfma_f32_16x16x32_bf16 v[84:87], v[164:167], v[206:209], v[84:87]
	v_mfma_f32_16x16x32_bf16 v[76:79], v[176:179], v[206:209], v[76:79]
	v_mfma_f32_16x16x32_bf16 v[68:71], v[164:167], v[214:217], v[68:71]
	v_mfma_f32_16x16x32_bf16 v[64:67], v[176:179], v[214:217], v[64:67]
	s_setprio 0
	s_barrier
	s_add_i32 s18, s20, s46
	v_lshl_add_u64 v[200:201], v[200:201], 0, s[76:77]
	s_mov_b32 m0, s18
	ds_read_b128 v[180:183], v175 offset:49152
	ds_read_b128 v[184:187], v175 offset:50176
	ds_read_b128 v[188:191], v175 offset:51200
	ds_read_b128 v[192:195], v175 offset:52224
	ds_read_b128 v[196:199], v175 offset:53248
	ds_read_b128 v[206:209], v175 offset:54272
	ds_read_b128 v[210:213], v175 offset:55296
	ds_read_b128 v[214:217], v175 offset:56320
	global_load_lds_dwordx4 v[200:201], off
	s_add_i32 m0, s18, 0x2000
	s_add_u32 s18, s50, 0x40080
	v_lshl_add_u64 v[200:201], v[218:219], 0, s[76:77]
	s_addc_u32 s19, s51, 0
	s_add_i32 s20, s21, s46
	global_load_lds_dwordx4 v[200:201], off
	v_lshl_add_u64 v[200:201], s[18:19], 0, v[148:149]
	s_mov_b32 m0, s20
	s_nop 0
	global_load_lds_dwordx4 v[200:201], off
	v_lshl_add_u64 v[200:201], s[18:19], 0, v[144:145]
	s_add_i32 m0, s20, 0x2000
	s_nop 0
	global_load_lds_dwordx4 v[200:201], off
	v_lshl_add_u64 v[200:201], v[220:221], 0, s[76:77]
	s_mov_b32 m0, s9
	s_nop 0
	global_load_lds_dwordx4 v[200:201], off
	v_lshl_add_u64 v[200:201], v[222:223], 0, s[76:77]
	s_mov_b32 m0, s10
	s_nop 0
	global_load_lds_dwordx4 v[200:201], off
	s_waitcnt vmcnt(8)
	s_waitcnt lgkmcnt(0)
	s_barrier
	s_setprio 1
	s_waitcnt lgkmcnt(0)
	v_mfma_f32_16x16x32_bf16 v[60:63], v[128:131], v[180:183], v[60:63]
	v_mfma_f32_16x16x32_bf16 v[56:59], v[136:139], v[180:183], v[56:59]
	v_mfma_f32_16x16x32_bf16 v[48:51], v[128:131], v[188:191], v[48:51]
	v_mfma_f32_16x16x32_bf16 v[40:43], v[136:139], v[188:191], v[40:43]
	v_mfma_f32_16x16x32_bf16 v[32:35], v[128:131], v[196:199], v[32:35]
	v_mfma_f32_16x16x32_bf16 v[24:27], v[136:139], v[196:199], v[24:27]
	v_mfma_f32_16x16x32_bf16 v[16:19], v[128:131], v[210:213], v[16:19]
	v_mfma_f32_16x16x32_bf16 v[8:11], v[136:139], v[210:213], v[8:11]
	v_mfma_f32_16x16x32_bf16 v[60:63], v[132:135], v[184:187], v[60:63]
	v_mfma_f32_16x16x32_bf16 v[56:59], v[140:143], v[184:187], v[56:59]
	v_mfma_f32_16x16x32_bf16 v[48:51], v[132:135], v[192:195], v[48:51]
	v_mfma_f32_16x16x32_bf16 v[40:43], v[140:143], v[192:195], v[40:43]
	v_mfma_f32_16x16x32_bf16 v[32:35], v[132:135], v[206:209], v[32:35]
	v_mfma_f32_16x16x32_bf16 v[24:27], v[140:143], v[206:209], v[24:27]
	v_mfma_f32_16x16x32_bf16 v[16:19], v[132:135], v[214:217], v[16:19]
	v_mfma_f32_16x16x32_bf16 v[8:11], v[140:143], v[214:217], v[8:11]
	s_setprio 0
	s_setprio 1
	v_mfma_f32_16x16x32_bf16 v[52:55], v[156:159], v[180:183], v[52:55]
	v_mfma_f32_16x16x32_bf16 v[44:47], v[168:171], v[180:183], v[44:47]
	v_mfma_f32_16x16x32_bf16 v[36:39], v[156:159], v[188:191], v[36:39]
	v_mfma_f32_16x16x32_bf16 v[28:31], v[168:171], v[188:191], v[28:31]
	v_mfma_f32_16x16x32_bf16 v[20:23], v[156:159], v[196:199], v[20:23]
	v_mfma_f32_16x16x32_bf16 v[12:15], v[168:171], v[196:199], v[12:15]
	v_mfma_f32_16x16x32_bf16 v[4:7], v[156:159], v[210:213], v[4:7]
	v_mfma_f32_16x16x32_bf16 v[0:3], v[168:171], v[210:213], v[0:3]
	v_mfma_f32_16x16x32_bf16 v[52:55], v[164:167], v[184:187], v[52:55]
	v_mfma_f32_16x16x32_bf16 v[44:47], v[176:179], v[184:187], v[44:47]
	v_mfma_f32_16x16x32_bf16 v[36:39], v[164:167], v[192:195], v[36:39]
	v_mfma_f32_16x16x32_bf16 v[28:31], v[176:179], v[192:195], v[28:31]
	v_mfma_f32_16x16x32_bf16 v[20:23], v[164:167], v[206:209], v[20:23]
	v_mfma_f32_16x16x32_bf16 v[12:15], v[176:179], v[206:209], v[12:15]
	v_mfma_f32_16x16x32_bf16 v[4:7], v[164:167], v[214:217], v[4:7]
	v_mfma_f32_16x16x32_bf16 v[0:3], v[176:179], v[214:217], v[0:3]
	s_setprio 0
	s_barrier
	s_add_i32 s54, s54, 2
	s_add_u32 s58, s58, 0x100
	s_addc_u32 s59, s59, 0
	s_add_u32 s39, s39, 0x100
	s_addc_u32 s47, s47, 0
	s_cmp_gt_u32 s54, 13
	s_cbranch_scc0 .LBB0_983
	s_branch .Lpeel_x_983

.LBB0_1004:
	s_ashr_i32 s37, s36, 31
	s_lshl_b64 s[16:17], s[36:37], 19
	s_add_u32 s40, s94, s16
	s_addc_u32 s41, s95, s17
	s_and_b64 s[16:17], s[42:43], exec
	s_cselect_b32 s16, s41, s51
	s_cselect_b32 s17, s40, s50
	s_ashr_i32 s39, s38, 31
	s_lshl_b64 s[18:19], s[38:39], 19
	s_add_u32 s48, s22, s18
	s_addc_u32 s49, s23, s19
	s_and_b64 s[18:19], s[42:43], exec
	s_cselect_b32 s37, s49, s61
	s_cselect_b32 s39, s48, s60
	s_add_u32 s58, s50, 0x40080
	s_addc_u32 s59, s51, 0
	s_add_u32 s46, s60, 0x100
	s_addc_u32 s47, s61, 0
	s_mov_b32 s54, -2
	s_add_u32 s18, s58, 0xfffc0080
	s_addc_u32 s19, s59, -1
	s_add_i32 s20, 0, 0x10000
	s_cmp_eq_u32 s54, 12
	s_cselect_b32 s61, s16, s19
	s_cselect_b32 s60, s17, s18
	s_cselect_b32 s51, s37, s47
	s_cselect_b32 s50, s39, s46
	s_add_i32 s21, 0, 0x14000
	v_add_u32_e32 v140, s20, v170
	v_add_u32_e32 v162, s21, v170
	ds_read_b128 v[128:131], v140
	ds_read_b128 v[132:135], v140 offset:1024
	ds_read_b128 v[136:139], v140 offset:2048
	ds_read_b128 v[140:143], v140 offset:3072
	ds_read_b128 v[144:147], v162
	ds_read_b128 v[148:151], v162 offset:1024
	ds_read_b128 v[172:175], v162 offset:2048
	ds_read_b128 v[176:179], v162 offset:3072
	v_lshl_add_u64 v[200:201], s[58:59], 0, v[164:165]
	s_add_i32 m0, s5, 0xc000
	ds_read_b128 v[180:183], v171
	ds_read_b128 v[184:187], v171 offset:1024
	ds_read_b128 v[188:191], v171 offset:2048
	ds_read_b128 v[192:195], v171 offset:3072
	ds_read_b128 v[196:199], v171 offset:4096
	ds_read_b128 v[206:209], v171 offset:5120
	ds_read_b128 v[210:213], v171 offset:6144
	ds_read_b128 v[214:217], v171 offset:7168
	global_load_lds_dwordx4 v[200:201], off
	v_lshl_add_u64 v[200:201], s[58:59], 0, v[166:167]
	s_add_i32 m0, s5, 0xe000
	s_nop 0
	global_load_lds_dwordx4 v[200:201], off
	s_waitcnt vmcnt(8)
	s_waitcnt lgkmcnt(0)
	s_barrier
	s_setprio 1
	s_waitcnt lgkmcnt(0)
	v_mfma_f32_16x16x32_bf16 v[124:127], v[128:131], v[180:183], 0
	v_mfma_f32_16x16x32_bf16 v[120:123], v[136:139], v[180:183], 0
	v_mfma_f32_16x16x32_bf16 v[116:119], v[128:131], v[188:191], 0
	v_mfma_f32_16x16x32_bf16 v[112:115], v[136:139], v[188:191], 0
	v_mfma_f32_16x16x32_bf16 v[104:107], v[128:131], v[196:199], 0
	v_mfma_f32_16x16x32_bf16 v[96:99], v[136:139], v[196:199], 0
	v_mfma_f32_16x16x32_bf16 v[80:83], v[128:131], v[210:213], 0
	v_mfma_f32_16x16x32_bf16 v[72:75], v[136:139], v[210:213], 0
	v_mfma_f32_16x16x32_bf16 v[124:127], v[132:135], v[184:187], v[124:127]
	v_mfma_f32_16x16x32_bf16 v[120:123], v[140:143], v[184:187], v[120:123]
	v_mfma_f32_16x16x32_bf16 v[116:119], v[132:135], v[192:195], v[116:119]
	v_mfma_f32_16x16x32_bf16 v[112:115], v[140:143], v[192:195], v[112:115]
	v_mfma_f32_16x16x32_bf16 v[104:107], v[132:135], v[206:209], v[104:107]
	v_mfma_f32_16x16x32_bf16 v[96:99], v[140:143], v[206:209], v[96:99]
	v_mfma_f32_16x16x32_bf16 v[80:83], v[132:135], v[214:217], v[80:83]
	v_mfma_f32_16x16x32_bf16 v[72:75], v[140:143], v[214:217], v[72:75]
	s_setprio 0
	s_setprio 1
	v_mfma_f32_16x16x32_bf16 v[108:111], v[144:147], v[180:183], 0
	v_mfma_f32_16x16x32_bf16 v[100:103], v[172:175], v[180:183], 0
	v_mfma_f32_16x16x32_bf16 v[92:95], v[144:147], v[188:191], 0
	v_mfma_f32_16x16x32_bf16 v[88:91], v[172:175], v[188:191], 0
	v_mfma_f32_16x16x32_bf16 v[84:87], v[144:147], v[196:199], 0
	v_mfma_f32_16x16x32_bf16 v[76:79], v[172:175], v[196:199], 0
	v_mfma_f32_16x16x32_bf16 v[68:71], v[144:147], v[210:213], 0
	v_mfma_f32_16x16x32_bf16 v[64:67], v[172:175], v[210:213], 0
	v_mfma_f32_16x16x32_bf16 v[108:111], v[148:151], v[184:187], v[108:111]
	v_mfma_f32_16x16x32_bf16 v[100:103], v[176:179], v[184:187], v[100:103]
	v_mfma_f32_16x16x32_bf16 v[92:95], v[148:151], v[192:195], v[92:95]
	v_mfma_f32_16x16x32_bf16 v[88:91], v[176:179], v[192:195], v[88:91]
	v_mfma_f32_16x16x32_bf16 v[84:87], v[148:151], v[206:209], v[84:87]
	v_mfma_f32_16x16x32_bf16 v[76:79], v[176:179], v[206:209], v[76:79]
	v_mfma_f32_16x16x32_bf16 v[68:71], v[148:151], v[214:217], v[68:71]
	v_mfma_f32_16x16x32_bf16 v[64:67], v[176:179], v[214:217], v[64:67]
	s_setprio 0
	s_barrier
	s_add_i32 s18, s20, s4
	v_lshl_add_u64 v[200:201], s[50:51], 0, v[156:157]
	s_mov_b32 m0, s18
	ds_read_b128 v[180:183], v171 offset:16384
	ds_read_b128 v[184:187], v171 offset:17408
	ds_read_b128 v[188:191], v171 offset:18432
	ds_read_b128 v[192:195], v171 offset:19456
	ds_read_b128 v[196:199], v171 offset:20480
	ds_read_b128 v[206:209], v171 offset:21504
	ds_read_b128 v[210:213], v171 offset:22528
	ds_read_b128 v[214:217], v171 offset:23552
	global_load_lds_dwordx4 v[200:201], off
	s_add_i32 m0, s18, 0x2000
	s_add_u32 s18, s50, 0x40000
	v_lshl_add_u64 v[218:219], s[50:51], 0, v[152:153]
	s_addc_u32 s19, s51, 0
	s_add_i32 s20, s21, s4
	global_load_lds_dwordx4 v[218:219], off
	v_lshl_add_u64 v[220:221], s[18:19], 0, v[156:157]
	s_mov_b32 m0, s20
	v_lshl_add_u64 v[222:223], s[60:61], 0, v[154:155]
	global_load_lds_dwordx4 v[220:221], off
	v_lshl_add_u64 v[220:221], s[18:19], 0, v[152:153]
	s_add_i32 m0, s20, 0x2000
	s_nop 0
	global_load_lds_dwordx4 v[220:221], off
	v_lshl_add_u64 v[220:221], s[60:61], 0, v[158:159]
	s_mov_b32 m0, s5
	s_nop 0
	global_load_lds_dwordx4 v[220:221], off
	s_mov_b32 m0, s6
	s_nop 0
	global_load_lds_dwordx4 v[222:223], off
	s_waitcnt vmcnt(8)
	s_waitcnt lgkmcnt(0)
	s_barrier
	s_setprio 1
	s_waitcnt lgkmcnt(0)
	v_mfma_f32_16x16x32_bf16 v[60:63], v[128:131], v[180:183], 0
	v_mfma_f32_16x16x32_bf16 v[56:59], v[136:139], v[180:183], 0
	v_mfma_f32_16x16x32_bf16 v[52:55], v[128:131], v[188:191], 0
	v_mfma_f32_16x16x32_bf16 v[48:51], v[136:139], v[188:191], 0
	v_mfma_f32_16x16x32_bf16 v[28:31], v[128:131], v[196:199], 0
	v_mfma_f32_16x16x32_bf16 v[24:27], v[136:139], v[196:199], 0
	v_mfma_f32_16x16x32_bf16 v[16:19], v[128:131], v[210:213], 0
	v_mfma_f32_16x16x32_bf16 v[8:11], v[136:139], v[210:213], 0
	v_mfma_f32_16x16x32_bf16 v[60:63], v[132:135], v[184:187], v[60:63]
	v_mfma_f32_16x16x32_bf16 v[56:59], v[140:143], v[184:187], v[56:59]
	v_mfma_f32_16x16x32_bf16 v[52:55], v[132:135], v[192:195], v[52:55]
	v_mfma_f32_16x16x32_bf16 v[48:51], v[140:143], v[192:195], v[48:51]
	v_mfma_f32_16x16x32_bf16 v[28:31], v[132:135], v[206:209], v[28:31]
	v_mfma_f32_16x16x32_bf16 v[24:27], v[140:143], v[206:209], v[24:27]
	v_mfma_f32_16x16x32_bf16 v[16:19], v[132:135], v[214:217], v[16:19]
	v_mfma_f32_16x16x32_bf16 v[8:11], v[140:143], v[214:217], v[8:11]
	s_setprio 0
	s_setprio 1
	v_mfma_f32_16x16x32_bf16 v[44:47], v[144:147], v[180:183], 0
	v_mfma_f32_16x16x32_bf16 v[40:43], v[172:175], v[180:183], 0
	v_mfma_f32_16x16x32_bf16 v[36:39], v[144:147], v[188:191], 0
	v_mfma_f32_16x16x32_bf16 v[32:35], v[172:175], v[188:191], 0
	v_mfma_f32_16x16x32_bf16 v[20:23], v[144:147], v[196:199], 0
	v_mfma_f32_16x16x32_bf16 v[12:15], v[172:175], v[196:199], 0
	v_mfma_f32_16x16x32_bf16 v[4:7], v[144:147], v[210:213], 0
	v_mfma_f32_16x16x32_bf16 v[0:3], v[172:175], v[210:213], 0
	v_mfma_f32_16x16x32_bf16 v[44:47], v[148:151], v[184:187], v[44:47]
	v_mfma_f32_16x16x32_bf16 v[40:43], v[176:179], v[184:187], v[40:43]
	v_mfma_f32_16x16x32_bf16 v[36:39], v[148:151], v[192:195], v[36:39]
	v_mfma_f32_16x16x32_bf16 v[32:35], v[176:179], v[192:195], v[32:35]
	v_mfma_f32_16x16x32_bf16 v[20:23], v[148:151], v[206:209], v[20:23]
	v_mfma_f32_16x16x32_bf16 v[12:15], v[176:179], v[206:209], v[12:15]
	v_mfma_f32_16x16x32_bf16 v[4:7], v[148:151], v[214:217], v[4:7]
	v_mfma_f32_16x16x32_bf16 v[0:3], v[176:179], v[214:217], v[0:3]
	s_setprio 0
	s_barrier
	s_add_i32 s20, 0, 0x18000
	s_add_i32 s21, 0, 0x1c000
	v_add_u32_e32 v140, s20, v170
	v_add_u32_e32 v162, s21, v170
	ds_read_b128 v[128:131], v140
	ds_read_b128 v[132:135], v140 offset:1024
	ds_read_b128 v[136:139], v140 offset:2048
	ds_read_b128 v[140:143], v140 offset:3072
	ds_read_b128 v[144:147], v162
	ds_read_b128 v[148:151], v162 offset:1024
	ds_read_b128 v[172:175], v162 offset:2048
	ds_read_b128 v[176:179], v162 offset:3072
	s_add_u32 s18, s60, 0x40000
	s_addc_u32 s19, s61, 0
	s_mov_b32 m0, s7
	v_lshl_add_u64 v[224:225], s[18:19], 0, v[158:159]
	ds_read_b128 v[180:183], v171 offset:32768
	ds_read_b128 v[184:187], v171 offset:33792
	ds_read_b128 v[188:191], v171 offset:34816
	ds_read_b128 v[192:195], v171 offset:35840
	ds_read_b128 v[196:199], v171 offset:36864
	ds_read_b128 v[206:209], v171 offset:37888
	ds_read_b128 v[210:213], v171 offset:38912
	ds_read_b128 v[214:217], v171 offset:39936
	global_load_lds_dwordx4 v[224:225], off
	v_lshl_add_u64 v[224:225], s[18:19], 0, v[154:155]
	s_mov_b32 m0, s8
	s_nop 0
	global_load_lds_dwordx4 v[224:225], off
	s_waitcnt vmcnt(8)
	s_waitcnt lgkmcnt(0)
	s_barrier
	s_setprio 1
	s_waitcnt lgkmcnt(0)
	v_mfma_f32_16x16x32_bf16 v[124:127], v[128:131], v[180:183], v[124:127]
	v_mfma_f32_16x16x32_bf16 v[120:123], v[136:139], v[180:183], v[120:123]
	v_mfma_f32_16x16x32_bf16 v[116:119], v[128:131], v[188:191], v[116:119]
	v_mfma_f32_16x16x32_bf16 v[112:115], v[136:139], v[188:191], v[112:115]
	v_mfma_f32_16x16x32_bf16 v[104:107], v[128:131], v[196:199], v[104:107]
	v_mfma_f32_16x16x32_bf16 v[96:99], v[136:139], v[196:199], v[96:99]
	v_mfma_f32_16x16x32_bf16 v[80:83], v[128:131], v[210:213], v[80:83]
	v_mfma_f32_16x16x32_bf16 v[72:75], v[136:139], v[210:213], v[72:75]
	v_mfma_f32_16x16x32_bf16 v[124:127], v[132:135], v[184:187], v[124:127]
	v_mfma_f32_16x16x32_bf16 v[120:123], v[140:143], v[184:187], v[120:123]
	v_mfma_f32_16x16x32_bf16 v[116:119], v[132:135], v[192:195], v[116:119]
	v_mfma_f32_16x16x32_bf16 v[112:115], v[140:143], v[192:195], v[112:115]
	v_mfma_f32_16x16x32_bf16 v[104:107], v[132:135], v[206:209], v[104:107]
	v_mfma_f32_16x16x32_bf16 v[96:99], v[140:143], v[206:209], v[96:99]
	v_mfma_f32_16x16x32_bf16 v[80:83], v[132:135], v[214:217], v[80:83]
	v_mfma_f32_16x16x32_bf16 v[72:75], v[140:143], v[214:217], v[72:75]
	s_setprio 0
	s_setprio 1
	v_mfma_f32_16x16x32_bf16 v[108:111], v[144:147], v[180:183], v[108:111]
	v_mfma_f32_16x16x32_bf16 v[100:103], v[172:175], v[180:183], v[100:103]
	v_mfma_f32_16x16x32_bf16 v[92:95], v[144:147], v[188:191], v[92:95]
	v_mfma_f32_16x16x32_bf16 v[88:91], v[172:175], v[188:191], v[88:91]
	v_mfma_f32_16x16x32_bf16 v[84:87], v[144:147], v[196:199], v[84:87]
	v_mfma_f32_16x16x32_bf16 v[76:79], v[172:175], v[196:199], v[76:79]
	v_mfma_f32_16x16x32_bf16 v[68:71], v[144:147], v[210:213], v[68:71]
	v_mfma_f32_16x16x32_bf16 v[64:67], v[172:175], v[210:213], v[64:67]
	v_mfma_f32_16x16x32_bf16 v[108:111], v[148:151], v[184:187], v[108:111]
	v_mfma_f32_16x16x32_bf16 v[100:103], v[176:179], v[184:187], v[100:103]
	v_mfma_f32_16x16x32_bf16 v[92:95], v[148:151], v[192:195], v[92:95]
	v_mfma_f32_16x16x32_bf16 v[88:91], v[176:179], v[192:195], v[88:91]
	v_mfma_f32_16x16x32_bf16 v[84:87], v[148:151], v[206:209], v[84:87]
	v_mfma_f32_16x16x32_bf16 v[76:79], v[176:179], v[206:209], v[76:79]
	v_mfma_f32_16x16x32_bf16 v[68:71], v[148:151], v[214:217], v[68:71]
	v_mfma_f32_16x16x32_bf16 v[64:67], v[176:179], v[214:217], v[64:67]
	s_setprio 0
	s_barrier
	s_add_i32 s18, s20, s4
	v_lshl_add_u64 v[200:201], v[200:201], 0, s[76:77]
	s_mov_b32 m0, s18
	ds_read_b128 v[180:183], v171 offset:49152
	ds_read_b128 v[184:187], v171 offset:50176
	ds_read_b128 v[188:191], v171 offset:51200
	ds_read_b128 v[192:195], v171 offset:52224
	ds_read_b128 v[196:199], v171 offset:53248
	ds_read_b128 v[206:209], v171 offset:54272
	ds_read_b128 v[210:213], v171 offset:55296
	ds_read_b128 v[214:217], v171 offset:56320
	global_load_lds_dwordx4 v[200:201], off
	s_add_i32 m0, s18, 0x2000
	s_add_u32 s18, s50, 0x40080
	v_lshl_add_u64 v[200:201], v[218:219], 0, s[76:77]
	s_addc_u32 s19, s51, 0
	s_add_i32 s20, s21, s4
	global_load_lds_dwordx4 v[200:201], off
	v_lshl_add_u64 v[200:201], s[18:19], 0, v[156:157]
	s_mov_b32 m0, s20
	s_nop 0
	global_load_lds_dwordx4 v[200:201], off
	v_lshl_add_u64 v[200:201], s[18:19], 0, v[152:153]
	s_add_i32 m0, s20, 0x2000
	s_nop 0
	global_load_lds_dwordx4 v[200:201], off
	v_lshl_add_u64 v[200:201], v[220:221], 0, s[76:77]
	s_mov_b32 m0, s10
	s_nop 0
	global_load_lds_dwordx4 v[200:201], off
	v_lshl_add_u64 v[200:201], v[222:223], 0, s[76:77]
	s_mov_b32 m0, s11
	s_nop 0
	global_load_lds_dwordx4 v[200:201], off
	s_waitcnt vmcnt(8)
	s_waitcnt lgkmcnt(0)
	s_barrier
	s_setprio 1
	s_waitcnt lgkmcnt(0)
	v_mfma_f32_16x16x32_bf16 v[60:63], v[128:131], v[180:183], v[60:63]
	v_mfma_f32_16x16x32_bf16 v[56:59], v[136:139], v[180:183], v[56:59]
	v_mfma_f32_16x16x32_bf16 v[52:55], v[128:131], v[188:191], v[52:55]
	v_mfma_f32_16x16x32_bf16 v[48:51], v[136:139], v[188:191], v[48:51]
	v_mfma_f32_16x16x32_bf16 v[28:31], v[128:131], v[196:199], v[28:31]
	v_mfma_f32_16x16x32_bf16 v[24:27], v[136:139], v[196:199], v[24:27]
	v_mfma_f32_16x16x32_bf16 v[16:19], v[128:131], v[210:213], v[16:19]
	v_mfma_f32_16x16x32_bf16 v[8:11], v[136:139], v[210:213], v[8:11]
	v_mfma_f32_16x16x32_bf16 v[60:63], v[132:135], v[184:187], v[60:63]
	v_mfma_f32_16x16x32_bf16 v[56:59], v[140:143], v[184:187], v[56:59]
	v_mfma_f32_16x16x32_bf16 v[52:55], v[132:135], v[192:195], v[52:55]
	v_mfma_f32_16x16x32_bf16 v[48:51], v[140:143], v[192:195], v[48:51]
	v_mfma_f32_16x16x32_bf16 v[28:31], v[132:135], v[206:209], v[28:31]
	v_mfma_f32_16x16x32_bf16 v[24:27], v[140:143], v[206:209], v[24:27]
	v_mfma_f32_16x16x32_bf16 v[16:19], v[132:135], v[214:217], v[16:19]
	v_mfma_f32_16x16x32_bf16 v[8:11], v[140:143], v[214:217], v[8:11]
	s_setprio 0
	s_setprio 1
	v_mfma_f32_16x16x32_bf16 v[44:47], v[144:147], v[180:183], v[44:47]
	v_mfma_f32_16x16x32_bf16 v[40:43], v[172:175], v[180:183], v[40:43]
	v_mfma_f32_16x16x32_bf16 v[36:39], v[144:147], v[188:191], v[36:39]
	v_mfma_f32_16x16x32_bf16 v[32:35], v[172:175], v[188:191], v[32:35]
	v_mfma_f32_16x16x32_bf16 v[20:23], v[144:147], v[196:199], v[20:23]
	v_mfma_f32_16x16x32_bf16 v[12:15], v[172:175], v[196:199], v[12:15]
	v_mfma_f32_16x16x32_bf16 v[4:7], v[144:147], v[210:213], v[4:7]
	v_mfma_f32_16x16x32_bf16 v[0:3], v[172:175], v[210:213], v[0:3]
	v_mfma_f32_16x16x32_bf16 v[44:47], v[148:151], v[184:187], v[44:47]
	v_mfma_f32_16x16x32_bf16 v[40:43], v[176:179], v[184:187], v[40:43]
	v_mfma_f32_16x16x32_bf16 v[36:39], v[148:151], v[192:195], v[36:39]
	v_mfma_f32_16x16x32_bf16 v[32:35], v[176:179], v[192:195], v[32:35]
	v_mfma_f32_16x16x32_bf16 v[20:23], v[148:151], v[206:209], v[20:23]
	v_mfma_f32_16x16x32_bf16 v[12:15], v[176:179], v[206:209], v[12:15]
	v_mfma_f32_16x16x32_bf16 v[4:7], v[148:151], v[214:217], v[4:7]
	v_mfma_f32_16x16x32_bf16 v[0:3], v[176:179], v[214:217], v[0:3]
	s_setprio 0
	s_barrier
	s_add_i32 s54, s54, 2
	s_add_u32 s58, s58, 0x100
	s_addc_u32 s59, s59, 0
	s_add_u32 s46, s46, 0x100
	s_addc_u32 s47, s47, 0
	s_cmp_gt_u32 s54, 13
	s_cbranch_scc0 .LBB0_1005
	s_branch .Lpeel_x_1005

.LBB0_1137:
	s_ashr_i32 s37, s36, 31
	s_lshl_b64 s[18:19], s[36:37], 19
	s_add_u32 s40, s96, s18
	s_addc_u32 s41, s97, s19
	s_and_b64 s[18:19], s[42:43], exec
	s_cselect_b32 s17, s41, s59
	s_cselect_b32 s37, s40, s58
	s_ashr_i32 s39, s38, 31
	s_lshl_b64 s[18:19], s[38:39], 19
	s_add_u32 s48, s5, s18
	s_addc_u32 s49, s6, s19
	s_and_b64 s[18:19], s[42:43], exec
	s_cselect_b32 s39, s49, s51
	s_cselect_b32 s46, s48, s50
	s_add_u32 s58, s58, 0x40080
	s_addc_u32 s59, s59, 0
	s_add_u32 s47, s50, 0x100
	s_addc_u32 s62, s51, 0
	s_mov_b32 s63, -2
	s_add_u32 s18, s58, 0xfffc0080
	s_addc_u32 s19, s59, -1
	s_add_i32 s20, 0, 0x10000
	s_cmp_eq_u32 s63, 12
	s_cselect_b32 s61, s17, s19
	s_cselect_b32 s60, s37, s18
	v_add_u32_e32 v140, s20, v143
	s_cselect_b32 s51, s39, s62
	s_cselect_b32 s50, s46, s47
	s_add_i32 s21, 0, 0x14000
	ds_read_b128 v[146:149], v140
	ds_read_b128 v[150:153], v140 offset:1024
	ds_read_b128 v[154:157], v140 offset:2048
	ds_read_b128 v[164:167], v140 offset:3072
	v_add_u32_e32 v140, s21, v143
	ds_read_b128 v[168:171], v140
	ds_read_b128 v[172:175], v140 offset:1024
	ds_read_b128 v[176:179], v140 offset:2048
	ds_read_b128 v[180:183], v140 offset:3072
	v_lshl_add_u64 v[140:141], s[58:59], 0, v[136:137]
	s_add_i32 m0, s8, 0xc000
	ds_read_b128 v[184:187], v144
	ds_read_b128 v[188:191], v144 offset:1024
	ds_read_b128 v[192:195], v144 offset:2048
	ds_read_b128 v[196:199], v144 offset:3072
	ds_read_b128 v[206:209], v144 offset:4096
	ds_read_b128 v[210:213], v144 offset:5120
	ds_read_b128 v[214:217], v144 offset:6144
	ds_read_b128 v[218:221], v144 offset:7168
	global_load_lds_dwordx4 v[140:141], off
	v_lshl_add_u64 v[140:141], s[58:59], 0, v[138:139]
	s_add_i32 m0, s8, 0xe000
	s_nop 0
	global_load_lds_dwordx4 v[140:141], off
	s_waitcnt vmcnt(8)
	s_waitcnt lgkmcnt(0)
	s_barrier
	s_setprio 1
	s_waitcnt lgkmcnt(0)
	v_mfma_f32_16x16x32_bf16 v[124:127], v[146:149], v[184:187], 0
	v_mfma_f32_16x16x32_bf16 v[120:123], v[154:157], v[184:187], 0
	v_mfma_f32_16x16x32_bf16 v[108:111], v[146:149], v[192:195], 0
	v_mfma_f32_16x16x32_bf16 v[104:107], v[154:157], v[192:195], 0
	v_mfma_f32_16x16x32_bf16 v[92:95], v[146:149], v[206:209], 0
	v_mfma_f32_16x16x32_bf16 v[88:91], v[154:157], v[206:209], 0
	v_mfma_f32_16x16x32_bf16 v[76:79], v[146:149], v[214:217], 0
	v_mfma_f32_16x16x32_bf16 v[72:75], v[154:157], v[214:217], 0
	v_mfma_f32_16x16x32_bf16 v[124:127], v[150:153], v[188:191], v[124:127]
	v_mfma_f32_16x16x32_bf16 v[120:123], v[164:167], v[188:191], v[120:123]
	v_mfma_f32_16x16x32_bf16 v[108:111], v[150:153], v[196:199], v[108:111]
	v_mfma_f32_16x16x32_bf16 v[104:107], v[164:167], v[196:199], v[104:107]
	v_mfma_f32_16x16x32_bf16 v[92:95], v[150:153], v[210:213], v[92:95]
	v_mfma_f32_16x16x32_bf16 v[88:91], v[164:167], v[210:213], v[88:91]
	v_mfma_f32_16x16x32_bf16 v[76:79], v[150:153], v[218:221], v[76:79]
	v_mfma_f32_16x16x32_bf16 v[72:75], v[164:167], v[218:221], v[72:75]
	s_setprio 0
	s_setprio 1
	v_mfma_f32_16x16x32_bf16 v[116:119], v[168:171], v[184:187], 0
	v_mfma_f32_16x16x32_bf16 v[112:115], v[176:179], v[184:187], 0
	v_mfma_f32_16x16x32_bf16 v[100:103], v[168:171], v[192:195], 0
	v_mfma_f32_16x16x32_bf16 v[96:99], v[176:179], v[192:195], 0
	v_mfma_f32_16x16x32_bf16 v[84:87], v[168:171], v[206:209], 0
	v_mfma_f32_16x16x32_bf16 v[80:83], v[176:179], v[206:209], 0
	v_mfma_f32_16x16x32_bf16 v[68:71], v[168:171], v[214:217], 0
	v_mfma_f32_16x16x32_bf16 v[64:67], v[176:179], v[214:217], 0
	v_mfma_f32_16x16x32_bf16 v[116:119], v[172:175], v[188:191], v[116:119]
	v_mfma_f32_16x16x32_bf16 v[112:115], v[180:183], v[188:191], v[112:115]
	v_mfma_f32_16x16x32_bf16 v[100:103], v[172:175], v[196:199], v[100:103]
	v_mfma_f32_16x16x32_bf16 v[96:99], v[180:183], v[196:199], v[96:99]
	v_mfma_f32_16x16x32_bf16 v[84:87], v[172:175], v[210:213], v[84:87]
	v_mfma_f32_16x16x32_bf16 v[80:83], v[180:183], v[210:213], v[80:83]
	v_mfma_f32_16x16x32_bf16 v[68:71], v[172:175], v[218:221], v[68:71]
	v_mfma_f32_16x16x32_bf16 v[64:67], v[180:183], v[218:221], v[64:67]
	s_setprio 0
	s_barrier
	s_add_i32 s18, s20, s7
	v_lshl_add_u64 v[140:141], s[50:51], 0, v[132:133]
	s_mov_b32 m0, s18
	ds_read_b128 v[184:187], v144 offset:16384
	ds_read_b128 v[188:191], v144 offset:17408
	ds_read_b128 v[192:195], v144 offset:18432
	ds_read_b128 v[196:199], v144 offset:19456
	ds_read_b128 v[206:209], v144 offset:20480
	ds_read_b128 v[210:213], v144 offset:21504
	ds_read_b128 v[214:217], v144 offset:22528
	ds_read_b128 v[218:221], v144 offset:23552
	global_load_lds_dwordx4 v[140:141], off
	s_add_i32 m0, s18, 0x2000
	s_add_u32 s18, s50, 0x40000
	v_lshl_add_u64 v[158:159], s[50:51], 0, v[128:129]
	s_addc_u32 s19, s51, 0
	s_add_i32 s20, s21, s7
	global_load_lds_dwordx4 v[158:159], off
	v_lshl_add_u64 v[200:201], s[18:19], 0, v[132:133]
	s_mov_b32 m0, s20
	v_lshl_add_u64 v[222:223], s[60:61], 0, v[130:131]
	global_load_lds_dwordx4 v[200:201], off
	v_lshl_add_u64 v[200:201], s[18:19], 0, v[128:129]
	s_add_i32 m0, s20, 0x2000
	s_nop 0
	global_load_lds_dwordx4 v[200:201], off
	v_lshl_add_u64 v[200:201], s[60:61], 0, v[134:135]
	s_mov_b32 m0, s8
	s_nop 0
	global_load_lds_dwordx4 v[200:201], off
	s_mov_b32 m0, s9
	s_nop 0
	global_load_lds_dwordx4 v[222:223], off
	s_waitcnt vmcnt(8)
	s_waitcnt lgkmcnt(0)
	s_barrier
	s_setprio 1
	s_waitcnt lgkmcnt(0)
	v_mfma_f32_16x16x32_bf16 v[60:63], v[146:149], v[184:187], 0
	v_mfma_f32_16x16x32_bf16 v[56:59], v[154:157], v[184:187], 0
	v_mfma_f32_16x16x32_bf16 v[44:47], v[146:149], v[192:195], 0
	v_mfma_f32_16x16x32_bf16 v[40:43], v[154:157], v[192:195], 0
	v_mfma_f32_16x16x32_bf16 v[28:31], v[146:149], v[206:209], 0
	v_mfma_f32_16x16x32_bf16 v[24:27], v[154:157], v[206:209], 0
	v_mfma_f32_16x16x32_bf16 v[12:15], v[146:149], v[214:217], 0
	v_mfma_f32_16x16x32_bf16 v[8:11], v[154:157], v[214:217], 0
	v_mfma_f32_16x16x32_bf16 v[60:63], v[150:153], v[188:191], v[60:63]
	v_mfma_f32_16x16x32_bf16 v[56:59], v[164:167], v[188:191], v[56:59]
	v_mfma_f32_16x16x32_bf16 v[44:47], v[150:153], v[196:199], v[44:47]
	v_mfma_f32_16x16x32_bf16 v[40:43], v[164:167], v[196:199], v[40:43]
	v_mfma_f32_16x16x32_bf16 v[28:31], v[150:153], v[210:213], v[28:31]
	v_mfma_f32_16x16x32_bf16 v[24:27], v[164:167], v[210:213], v[24:27]
	v_mfma_f32_16x16x32_bf16 v[12:15], v[150:153], v[218:221], v[12:15]
	v_mfma_f32_16x16x32_bf16 v[8:11], v[164:167], v[218:221], v[8:11]
	s_setprio 0
	s_setprio 1
	v_mfma_f32_16x16x32_bf16 v[52:55], v[168:171], v[184:187], 0
	v_mfma_f32_16x16x32_bf16 v[48:51], v[176:179], v[184:187], 0
	v_mfma_f32_16x16x32_bf16 v[36:39], v[168:171], v[192:195], 0
	v_mfma_f32_16x16x32_bf16 v[32:35], v[176:179], v[192:195], 0
	v_mfma_f32_16x16x32_bf16 v[20:23], v[168:171], v[206:209], 0
	v_mfma_f32_16x16x32_bf16 v[16:19], v[176:179], v[206:209], 0
	v_mfma_f32_16x16x32_bf16 v[4:7], v[168:171], v[214:217], 0
	v_mfma_f32_16x16x32_bf16 v[0:3], v[176:179], v[214:217], 0
	v_mfma_f32_16x16x32_bf16 v[52:55], v[172:175], v[188:191], v[52:55]
	v_mfma_f32_16x16x32_bf16 v[48:51], v[180:183], v[188:191], v[48:51]
	v_mfma_f32_16x16x32_bf16 v[36:39], v[172:175], v[196:199], v[36:39]
	v_mfma_f32_16x16x32_bf16 v[32:35], v[180:183], v[196:199], v[32:35]
	v_mfma_f32_16x16x32_bf16 v[20:23], v[172:175], v[210:213], v[20:23]
	v_mfma_f32_16x16x32_bf16 v[16:19], v[180:183], v[210:213], v[16:19]
	v_mfma_f32_16x16x32_bf16 v[4:7], v[172:175], v[218:221], v[4:7]
	v_mfma_f32_16x16x32_bf16 v[0:3], v[180:183], v[218:221], v[0:3]
	s_setprio 0
	s_barrier
	s_add_i32 s20, 0, 0x18000
	v_add_u32_e32 v145, s20, v143
	s_add_i32 s21, 0, 0x1c000
	ds_read_b128 v[146:149], v145
	ds_read_b128 v[150:153], v145 offset:1024
	ds_read_b128 v[154:157], v145 offset:2048
	ds_read_b128 v[164:167], v145 offset:3072
	v_add_u32_e32 v145, s21, v143
	ds_read_b128 v[168:171], v145
	ds_read_b128 v[172:175], v145 offset:1024
	ds_read_b128 v[176:179], v145 offset:2048
	ds_read_b128 v[180:183], v145 offset:3072
	s_add_u32 s18, s60, 0x40000
	s_addc_u32 s19, s61, 0
	s_mov_b32 m0, s10
	v_lshl_add_u64 v[224:225], s[18:19], 0, v[134:135]
	ds_read_b128 v[184:187], v144 offset:32768
	ds_read_b128 v[188:191], v144 offset:33792
	ds_read_b128 v[192:195], v144 offset:34816
	ds_read_b128 v[196:199], v144 offset:35840
	ds_read_b128 v[206:209], v144 offset:36864
	ds_read_b128 v[210:213], v144 offset:37888
	ds_read_b128 v[214:217], v144 offset:38912
	ds_read_b128 v[218:221], v144 offset:39936
	global_load_lds_dwordx4 v[224:225], off
	v_lshl_add_u64 v[224:225], s[18:19], 0, v[130:131]
	s_mov_b32 m0, s11
	s_nop 0
	global_load_lds_dwordx4 v[224:225], off
	s_waitcnt vmcnt(8)
	s_waitcnt lgkmcnt(0)
	s_barrier
	s_setprio 1
	s_waitcnt lgkmcnt(0)
	v_mfma_f32_16x16x32_bf16 v[124:127], v[146:149], v[184:187], v[124:127]
	v_mfma_f32_16x16x32_bf16 v[120:123], v[154:157], v[184:187], v[120:123]
	v_mfma_f32_16x16x32_bf16 v[108:111], v[146:149], v[192:195], v[108:111]
	v_mfma_f32_16x16x32_bf16 v[104:107], v[154:157], v[192:195], v[104:107]
	v_mfma_f32_16x16x32_bf16 v[92:95], v[146:149], v[206:209], v[92:95]
	v_mfma_f32_16x16x32_bf16 v[88:91], v[154:157], v[206:209], v[88:91]
	v_mfma_f32_16x16x32_bf16 v[76:79], v[146:149], v[214:217], v[76:79]
	v_mfma_f32_16x16x32_bf16 v[72:75], v[154:157], v[214:217], v[72:75]
	v_mfma_f32_16x16x32_bf16 v[124:127], v[150:153], v[188:191], v[124:127]
	v_mfma_f32_16x16x32_bf16 v[120:123], v[164:167], v[188:191], v[120:123]
	v_mfma_f32_16x16x32_bf16 v[108:111], v[150:153], v[196:199], v[108:111]
	v_mfma_f32_16x16x32_bf16 v[104:107], v[164:167], v[196:199], v[104:107]
	v_mfma_f32_16x16x32_bf16 v[92:95], v[150:153], v[210:213], v[92:95]
	v_mfma_f32_16x16x32_bf16 v[88:91], v[164:167], v[210:213], v[88:91]
	v_mfma_f32_16x16x32_bf16 v[76:79], v[150:153], v[218:221], v[76:79]
	v_mfma_f32_16x16x32_bf16 v[72:75], v[164:167], v[218:221], v[72:75]
	s_setprio 0
	s_setprio 1
	v_mfma_f32_16x16x32_bf16 v[116:119], v[168:171], v[184:187], v[116:119]
	v_mfma_f32_16x16x32_bf16 v[112:115], v[176:179], v[184:187], v[112:115]
	v_mfma_f32_16x16x32_bf16 v[100:103], v[168:171], v[192:195], v[100:103]
	v_mfma_f32_16x16x32_bf16 v[96:99], v[176:179], v[192:195], v[96:99]
	v_mfma_f32_16x16x32_bf16 v[84:87], v[168:171], v[206:209], v[84:87]
	v_mfma_f32_16x16x32_bf16 v[80:83], v[176:179], v[206:209], v[80:83]
	v_mfma_f32_16x16x32_bf16 v[68:71], v[168:171], v[214:217], v[68:71]
	v_mfma_f32_16x16x32_bf16 v[64:67], v[176:179], v[214:217], v[64:67]
	v_mfma_f32_16x16x32_bf16 v[116:119], v[172:175], v[188:191], v[116:119]
	v_mfma_f32_16x16x32_bf16 v[112:115], v[180:183], v[188:191], v[112:115]
	v_mfma_f32_16x16x32_bf16 v[100:103], v[172:175], v[196:199], v[100:103]
	v_mfma_f32_16x16x32_bf16 v[96:99], v[180:183], v[196:199], v[96:99]
	v_mfma_f32_16x16x32_bf16 v[84:87], v[172:175], v[210:213], v[84:87]
	v_mfma_f32_16x16x32_bf16 v[80:83], v[180:183], v[210:213], v[80:83]
	v_mfma_f32_16x16x32_bf16 v[68:71], v[172:175], v[218:221], v[68:71]
	v_mfma_f32_16x16x32_bf16 v[64:67], v[180:183], v[218:221], v[64:67]
	s_setprio 0
	s_barrier
	s_add_i32 s18, s20, s7
	v_lshl_add_u64 v[140:141], v[140:141], 0, s[76:77]
	s_mov_b32 m0, s18
	ds_read_b128 v[184:187], v144 offset:49152
	ds_read_b128 v[188:191], v144 offset:50176
	ds_read_b128 v[192:195], v144 offset:51200
	ds_read_b128 v[196:199], v144 offset:52224
	ds_read_b128 v[206:209], v144 offset:53248
	ds_read_b128 v[210:213], v144 offset:54272
	ds_read_b128 v[214:217], v144 offset:55296
	ds_read_b128 v[218:221], v144 offset:56320
	global_load_lds_dwordx4 v[140:141], off
	s_add_i32 m0, s18, 0x2000
	s_add_u32 s18, s50, 0x40080
	v_lshl_add_u64 v[140:141], v[158:159], 0, s[76:77]
	s_addc_u32 s19, s51, 0
	s_add_i32 s20, s21, s7
	global_load_lds_dwordx4 v[140:141], off
	v_lshl_add_u64 v[140:141], s[18:19], 0, v[132:133]
	s_mov_b32 m0, s20
	s_nop 0
	global_load_lds_dwordx4 v[140:141], off
	v_lshl_add_u64 v[140:141], s[18:19], 0, v[128:129]
	s_add_i32 m0, s20, 0x2000
	s_nop 0
	global_load_lds_dwordx4 v[140:141], off
	v_lshl_add_u64 v[140:141], v[200:201], 0, s[76:77]
	s_mov_b32 m0, s12
	s_nop 0
	global_load_lds_dwordx4 v[140:141], off
	v_lshl_add_u64 v[140:141], v[222:223], 0, s[76:77]
	s_mov_b32 m0, s13
	s_nop 0
	global_load_lds_dwordx4 v[140:141], off
	s_waitcnt vmcnt(8)
	s_waitcnt lgkmcnt(0)
	s_barrier
	s_setprio 1
	s_waitcnt lgkmcnt(0)
	v_mfma_f32_16x16x32_bf16 v[60:63], v[146:149], v[184:187], v[60:63]
	v_mfma_f32_16x16x32_bf16 v[56:59], v[154:157], v[184:187], v[56:59]
	v_mfma_f32_16x16x32_bf16 v[44:47], v[146:149], v[192:195], v[44:47]
	v_mfma_f32_16x16x32_bf16 v[40:43], v[154:157], v[192:195], v[40:43]
	v_mfma_f32_16x16x32_bf16 v[28:31], v[146:149], v[206:209], v[28:31]
	v_mfma_f32_16x16x32_bf16 v[24:27], v[154:157], v[206:209], v[24:27]
	v_mfma_f32_16x16x32_bf16 v[12:15], v[146:149], v[214:217], v[12:15]
	v_mfma_f32_16x16x32_bf16 v[8:11], v[154:157], v[214:217], v[8:11]
	v_mfma_f32_16x16x32_bf16 v[60:63], v[150:153], v[188:191], v[60:63]
	v_mfma_f32_16x16x32_bf16 v[56:59], v[164:167], v[188:191], v[56:59]
	v_mfma_f32_16x16x32_bf16 v[44:47], v[150:153], v[196:199], v[44:47]
	v_mfma_f32_16x16x32_bf16 v[40:43], v[164:167], v[196:199], v[40:43]
	v_mfma_f32_16x16x32_bf16 v[28:31], v[150:153], v[210:213], v[28:31]
	v_mfma_f32_16x16x32_bf16 v[24:27], v[164:167], v[210:213], v[24:27]
	v_mfma_f32_16x16x32_bf16 v[12:15], v[150:153], v[218:221], v[12:15]
	v_mfma_f32_16x16x32_bf16 v[8:11], v[164:167], v[218:221], v[8:11]
	s_setprio 0
	s_setprio 1
	v_mfma_f32_16x16x32_bf16 v[52:55], v[168:171], v[184:187], v[52:55]
	v_mfma_f32_16x16x32_bf16 v[48:51], v[176:179], v[184:187], v[48:51]
	v_mfma_f32_16x16x32_bf16 v[36:39], v[168:171], v[192:195], v[36:39]
	v_mfma_f32_16x16x32_bf16 v[32:35], v[176:179], v[192:195], v[32:35]
	v_mfma_f32_16x16x32_bf16 v[20:23], v[168:171], v[206:209], v[20:23]
	v_mfma_f32_16x16x32_bf16 v[16:19], v[176:179], v[206:209], v[16:19]
	v_mfma_f32_16x16x32_bf16 v[4:7], v[168:171], v[214:217], v[4:7]
	v_mfma_f32_16x16x32_bf16 v[0:3], v[176:179], v[214:217], v[0:3]
	v_mfma_f32_16x16x32_bf16 v[52:55], v[172:175], v[188:191], v[52:55]
	v_mfma_f32_16x16x32_bf16 v[48:51], v[180:183], v[188:191], v[48:51]
	v_mfma_f32_16x16x32_bf16 v[36:39], v[172:175], v[196:199], v[36:39]
	v_mfma_f32_16x16x32_bf16 v[32:35], v[180:183], v[196:199], v[32:35]
	v_mfma_f32_16x16x32_bf16 v[20:23], v[172:175], v[210:213], v[20:23]
	v_mfma_f32_16x16x32_bf16 v[16:19], v[180:183], v[210:213], v[16:19]
	v_mfma_f32_16x16x32_bf16 v[4:7], v[172:175], v[218:221], v[4:7]
	v_mfma_f32_16x16x32_bf16 v[0:3], v[180:183], v[218:221], v[0:3]
	s_setprio 0
	s_barrier
	s_add_i32 s63, s63, 2
	s_add_u32 s58, s58, 0x100
	s_addc_u32 s59, s59, 0
	s_add_u32 s47, s47, 0x100
	s_addc_u32 s62, s62, 0
	s_cmp_gt_u32 s63, 13
	s_cbranch_scc0 .LBB0_1138
	s_branch .Lpeel_x_1138

.LBB0_1209:
	s_add_u32 s54, s48, 0x100
	s_addc_u32 s60, s49, 0
	s_mov_b32 s61, -2
	s_add_u32 s48, s42, 0x100
	s_addc_u32 s49, s43, 0
	s_add_i32 s18, 0, 0x10000
	s_cmp_eq_u32 s61, 40
	s_cselect_b32 s59, s39, s49
	s_cselect_b32 s58, s38, s48
	s_cselect_b32 s51, s41, s60
	s_cselect_b32 s50, s40, s54
	s_add_i32 s20, 0, 0x14000
	v_add_u32_e32 v140, s18, v174
	v_add_u32_e32 v162, s20, v174
	ds_read_b128 v[128:131], v140
	ds_read_b128 v[132:135], v140 offset:1024
	ds_read_b128 v[136:139], v140 offset:2048
	ds_read_b128 v[140:143], v140 offset:3072
	ds_read_b128 v[156:159], v162
	ds_read_b128 v[164:167], v162 offset:1024
	ds_read_b128 v[168:171], v162 offset:2048
	ds_read_b128 v[176:179], v162 offset:3072
	v_lshl_add_u64 v[200:201], s[42:43], 0, v[152:153]
	s_add_i32 m0, s4, 0xc000
	ds_read_b128 v[180:183], v175
	ds_read_b128 v[184:187], v175 offset:1024
	ds_read_b128 v[188:191], v175 offset:2048
	ds_read_b128 v[192:195], v175 offset:3072
	ds_read_b128 v[196:199], v175 offset:4096
	ds_read_b128 v[206:209], v175 offset:5120
	ds_read_b128 v[210:213], v175 offset:6144
	ds_read_b128 v[214:217], v175 offset:7168
	global_load_lds_dwordx4 v[200:201], off
	v_lshl_add_u64 v[200:201], s[42:43], 0, v[154:155]
	s_add_i32 m0, s4, 0xe000
	s_nop 0
	global_load_lds_dwordx4 v[200:201], off
	s_waitcnt vmcnt(8)
	s_waitcnt lgkmcnt(0)
	s_barrier
	s_setprio 1
	s_waitcnt lgkmcnt(0)
	v_mfma_f32_16x16x32_bf16 v[124:127], v[128:131], v[180:183], 0
	v_mfma_f32_16x16x32_bf16 v[120:123], v[136:139], v[180:183], 0
	v_mfma_f32_16x16x32_bf16 v[112:115], v[128:131], v[188:191], 0
	v_mfma_f32_16x16x32_bf16 v[104:107], v[136:139], v[188:191], 0
	v_mfma_f32_16x16x32_bf16 v[96:99], v[128:131], v[196:199], 0
	v_mfma_f32_16x16x32_bf16 v[88:91], v[136:139], v[196:199], 0
	v_mfma_f32_16x16x32_bf16 v[80:83], v[128:131], v[210:213], 0
	v_mfma_f32_16x16x32_bf16 v[72:75], v[136:139], v[210:213], 0
	v_mfma_f32_16x16x32_bf16 v[124:127], v[132:135], v[184:187], v[124:127]
	v_mfma_f32_16x16x32_bf16 v[120:123], v[140:143], v[184:187], v[120:123]
	v_mfma_f32_16x16x32_bf16 v[112:115], v[132:135], v[192:195], v[112:115]
	v_mfma_f32_16x16x32_bf16 v[104:107], v[140:143], v[192:195], v[104:107]
	v_mfma_f32_16x16x32_bf16 v[96:99], v[132:135], v[206:209], v[96:99]
	v_mfma_f32_16x16x32_bf16 v[88:91], v[140:143], v[206:209], v[88:91]
	v_mfma_f32_16x16x32_bf16 v[80:83], v[132:135], v[214:217], v[80:83]
	v_mfma_f32_16x16x32_bf16 v[72:75], v[140:143], v[214:217], v[72:75]
	s_setprio 0
	s_setprio 1
	v_mfma_f32_16x16x32_bf16 v[116:119], v[156:159], v[180:183], 0
	v_mfma_f32_16x16x32_bf16 v[108:111], v[168:171], v[180:183], 0
	v_mfma_f32_16x16x32_bf16 v[100:103], v[156:159], v[188:191], 0
	v_mfma_f32_16x16x32_bf16 v[92:95], v[168:171], v[188:191], 0
	v_mfma_f32_16x16x32_bf16 v[84:87], v[156:159], v[196:199], 0
	v_mfma_f32_16x16x32_bf16 v[76:79], v[168:171], v[196:199], 0
	v_mfma_f32_16x16x32_bf16 v[68:71], v[156:159], v[210:213], 0
	v_mfma_f32_16x16x32_bf16 v[64:67], v[168:171], v[210:213], 0
	v_mfma_f32_16x16x32_bf16 v[116:119], v[164:167], v[184:187], v[116:119]
	v_mfma_f32_16x16x32_bf16 v[108:111], v[176:179], v[184:187], v[108:111]
	v_mfma_f32_16x16x32_bf16 v[100:103], v[164:167], v[192:195], v[100:103]
	v_mfma_f32_16x16x32_bf16 v[92:95], v[176:179], v[192:195], v[92:95]
	v_mfma_f32_16x16x32_bf16 v[84:87], v[164:167], v[206:209], v[84:87]
	v_mfma_f32_16x16x32_bf16 v[76:79], v[176:179], v[206:209], v[76:79]
	v_mfma_f32_16x16x32_bf16 v[68:71], v[164:167], v[214:217], v[68:71]
	v_mfma_f32_16x16x32_bf16 v[64:67], v[176:179], v[214:217], v[64:67]
	s_setprio 0
	s_barrier
	s_add_i32 s18, s18, s46
	v_lshl_add_u64 v[200:201], s[50:51], 0, v[148:149]
	s_mov_b32 m0, s18
	ds_read_b128 v[180:183], v175 offset:16384
	ds_read_b128 v[184:187], v175 offset:17408
	ds_read_b128 v[188:191], v175 offset:18432
	ds_read_b128 v[192:195], v175 offset:19456
	ds_read_b128 v[196:199], v175 offset:20480
	ds_read_b128 v[206:209], v175 offset:21504
	ds_read_b128 v[210:213], v175 offset:22528
	ds_read_b128 v[214:217], v175 offset:23552
	global_load_lds_dwordx4 v[200:201], off
	s_add_i32 m0, s18, 0x2000
	s_add_u32 s18, s50, 0xb0000
	v_lshl_add_u64 v[218:219], s[50:51], 0, v[144:145]
	s_addc_u32 s19, s51, 0
	s_add_i32 s20, s20, s46
	global_load_lds_dwordx4 v[218:219], off
	v_lshl_add_u64 v[220:221], s[18:19], 0, v[148:149]
	s_mov_b32 m0, s20
	v_lshl_add_u64 v[222:223], s[58:59], 0, v[146:147]
	global_load_lds_dwordx4 v[220:221], off
	v_lshl_add_u64 v[220:221], s[18:19], 0, v[144:145]
	s_add_i32 m0, s20, 0x2000
	s_nop 0
	global_load_lds_dwordx4 v[220:221], off
	v_lshl_add_u64 v[220:221], s[58:59], 0, v[150:151]
	s_mov_b32 m0, s4
	s_nop 0
	global_load_lds_dwordx4 v[220:221], off
	s_mov_b32 m0, s5
	s_nop 0
	global_load_lds_dwordx4 v[222:223], off
	s_waitcnt vmcnt(8)
	s_waitcnt lgkmcnt(0)
	s_barrier
	s_setprio 1
	s_waitcnt lgkmcnt(0)
	v_mfma_f32_16x16x32_bf16 v[60:63], v[128:131], v[180:183], 0
	v_mfma_f32_16x16x32_bf16 v[56:59], v[136:139], v[180:183], 0
	v_mfma_f32_16x16x32_bf16 v[48:51], v[128:131], v[188:191], 0
	v_mfma_f32_16x16x32_bf16 v[40:43], v[136:139], v[188:191], 0
	v_mfma_f32_16x16x32_bf16 v[32:35], v[128:131], v[196:199], 0
	v_mfma_f32_16x16x32_bf16 v[24:27], v[136:139], v[196:199], 0
	v_mfma_f32_16x16x32_bf16 v[16:19], v[128:131], v[210:213], 0
	v_mfma_f32_16x16x32_bf16 v[8:11], v[136:139], v[210:213], 0
	v_mfma_f32_16x16x32_bf16 v[60:63], v[132:135], v[184:187], v[60:63]
	v_mfma_f32_16x16x32_bf16 v[56:59], v[140:143], v[184:187], v[56:59]
	v_mfma_f32_16x16x32_bf16 v[48:51], v[132:135], v[192:195], v[48:51]
	v_mfma_f32_16x16x32_bf16 v[40:43], v[140:143], v[192:195], v[40:43]
	v_mfma_f32_16x16x32_bf16 v[32:35], v[132:135], v[206:209], v[32:35]
	v_mfma_f32_16x16x32_bf16 v[24:27], v[140:143], v[206:209], v[24:27]
	v_mfma_f32_16x16x32_bf16 v[16:19], v[132:135], v[214:217], v[16:19]
	v_mfma_f32_16x16x32_bf16 v[8:11], v[140:143], v[214:217], v[8:11]
	s_setprio 0
	s_setprio 1
	v_mfma_f32_16x16x32_bf16 v[52:55], v[156:159], v[180:183], 0
	v_mfma_f32_16x16x32_bf16 v[44:47], v[168:171], v[180:183], 0
	v_mfma_f32_16x16x32_bf16 v[36:39], v[156:159], v[188:191], 0
	v_mfma_f32_16x16x32_bf16 v[28:31], v[168:171], v[188:191], 0
	v_mfma_f32_16x16x32_bf16 v[20:23], v[156:159], v[196:199], 0
	v_mfma_f32_16x16x32_bf16 v[12:15], v[168:171], v[196:199], 0
	v_mfma_f32_16x16x32_bf16 v[4:7], v[156:159], v[210:213], 0
	v_mfma_f32_16x16x32_bf16 v[0:3], v[168:171], v[210:213], 0
	v_mfma_f32_16x16x32_bf16 v[52:55], v[164:167], v[184:187], v[52:55]
	v_mfma_f32_16x16x32_bf16 v[44:47], v[176:179], v[184:187], v[44:47]
	v_mfma_f32_16x16x32_bf16 v[36:39], v[164:167], v[192:195], v[36:39]
	v_mfma_f32_16x16x32_bf16 v[28:31], v[176:179], v[192:195], v[28:31]
	v_mfma_f32_16x16x32_bf16 v[20:23], v[164:167], v[206:209], v[20:23]
	v_mfma_f32_16x16x32_bf16 v[12:15], v[176:179], v[206:209], v[12:15]
	v_mfma_f32_16x16x32_bf16 v[4:7], v[164:167], v[214:217], v[4:7]
	v_mfma_f32_16x16x32_bf16 v[0:3], v[176:179], v[214:217], v[0:3]
	s_setprio 0
	s_barrier
	s_add_i32 s20, 0, 0x18000
	s_add_i32 s21, 0, 0x1c000
	v_add_u32_e32 v140, s20, v174
	v_add_u32_e32 v162, s21, v174
	ds_read_b128 v[128:131], v140
	ds_read_b128 v[132:135], v140 offset:1024
	ds_read_b128 v[136:139], v140 offset:2048
	ds_read_b128 v[140:143], v140 offset:3072
	ds_read_b128 v[156:159], v162
	ds_read_b128 v[164:167], v162 offset:1024
	ds_read_b128 v[168:171], v162 offset:2048
	ds_read_b128 v[176:179], v162 offset:3072
	s_add_u32 s18, s58, 0xb0000
	s_addc_u32 s19, s59, 0
	s_mov_b32 m0, s6
	v_lshl_add_u64 v[224:225], s[18:19], 0, v[150:151]
	ds_read_b128 v[180:183], v175 offset:32768
	ds_read_b128 v[184:187], v175 offset:33792
	ds_read_b128 v[188:191], v175 offset:34816
	ds_read_b128 v[192:195], v175 offset:35840
	ds_read_b128 v[196:199], v175 offset:36864
	ds_read_b128 v[206:209], v175 offset:37888
	ds_read_b128 v[210:213], v175 offset:38912
	ds_read_b128 v[214:217], v175 offset:39936
	global_load_lds_dwordx4 v[224:225], off
	v_lshl_add_u64 v[224:225], s[18:19], 0, v[146:147]
	s_mov_b32 m0, s7
	s_nop 0
	global_load_lds_dwordx4 v[224:225], off
	s_waitcnt vmcnt(8)
	s_waitcnt lgkmcnt(0)
	s_barrier
	s_setprio 1
	s_waitcnt lgkmcnt(0)
	v_mfma_f32_16x16x32_bf16 v[124:127], v[128:131], v[180:183], v[124:127]
	v_mfma_f32_16x16x32_bf16 v[120:123], v[136:139], v[180:183], v[120:123]
	v_mfma_f32_16x16x32_bf16 v[112:115], v[128:131], v[188:191], v[112:115]
	v_mfma_f32_16x16x32_bf16 v[104:107], v[136:139], v[188:191], v[104:107]
	v_mfma_f32_16x16x32_bf16 v[96:99], v[128:131], v[196:199], v[96:99]
	v_mfma_f32_16x16x32_bf16 v[88:91], v[136:139], v[196:199], v[88:91]
	v_mfma_f32_16x16x32_bf16 v[80:83], v[128:131], v[210:213], v[80:83]
	v_mfma_f32_16x16x32_bf16 v[72:75], v[136:139], v[210:213], v[72:75]
	v_mfma_f32_16x16x32_bf16 v[124:127], v[132:135], v[184:187], v[124:127]
	v_mfma_f32_16x16x32_bf16 v[120:123], v[140:143], v[184:187], v[120:123]
	v_mfma_f32_16x16x32_bf16 v[112:115], v[132:135], v[192:195], v[112:115]
	v_mfma_f32_16x16x32_bf16 v[104:107], v[140:143], v[192:195], v[104:107]
	v_mfma_f32_16x16x32_bf16 v[96:99], v[132:135], v[206:209], v[96:99]
	v_mfma_f32_16x16x32_bf16 v[88:91], v[140:143], v[206:209], v[88:91]
	v_mfma_f32_16x16x32_bf16 v[80:83], v[132:135], v[214:217], v[80:83]
	v_mfma_f32_16x16x32_bf16 v[72:75], v[140:143], v[214:217], v[72:75]
	s_setprio 0
	s_setprio 1
	v_mfma_f32_16x16x32_bf16 v[116:119], v[156:159], v[180:183], v[116:119]
	v_mfma_f32_16x16x32_bf16 v[108:111], v[168:171], v[180:183], v[108:111]
	v_mfma_f32_16x16x32_bf16 v[100:103], v[156:159], v[188:191], v[100:103]
	v_mfma_f32_16x16x32_bf16 v[92:95], v[168:171], v[188:191], v[92:95]
	v_mfma_f32_16x16x32_bf16 v[84:87], v[156:159], v[196:199], v[84:87]
	v_mfma_f32_16x16x32_bf16 v[76:79], v[168:171], v[196:199], v[76:79]
	v_mfma_f32_16x16x32_bf16 v[68:71], v[156:159], v[210:213], v[68:71]
	v_mfma_f32_16x16x32_bf16 v[64:67], v[168:171], v[210:213], v[64:67]
	v_mfma_f32_16x16x32_bf16 v[116:119], v[164:167], v[184:187], v[116:119]
	v_mfma_f32_16x16x32_bf16 v[108:111], v[176:179], v[184:187], v[108:111]
	v_mfma_f32_16x16x32_bf16 v[100:103], v[164:167], v[192:195], v[100:103]
	v_mfma_f32_16x16x32_bf16 v[92:95], v[176:179], v[192:195], v[92:95]
	v_mfma_f32_16x16x32_bf16 v[84:87], v[164:167], v[206:209], v[84:87]
	v_mfma_f32_16x16x32_bf16 v[76:79], v[176:179], v[206:209], v[76:79]
	v_mfma_f32_16x16x32_bf16 v[68:71], v[164:167], v[214:217], v[68:71]
	v_mfma_f32_16x16x32_bf16 v[64:67], v[176:179], v[214:217], v[64:67]
	s_setprio 0
	s_barrier
	s_add_i32 s18, s20, s46
	v_lshl_add_u64 v[200:201], v[200:201], 0, s[76:77]
	s_mov_b32 m0, s18
	ds_read_b128 v[180:183], v175 offset:49152
	ds_read_b128 v[184:187], v175 offset:50176
	ds_read_b128 v[188:191], v175 offset:51200
	ds_read_b128 v[192:195], v175 offset:52224
	ds_read_b128 v[196:199], v175 offset:53248
	ds_read_b128 v[206:209], v175 offset:54272
	ds_read_b128 v[210:213], v175 offset:55296
	ds_read_b128 v[214:217], v175 offset:56320
	global_load_lds_dwordx4 v[200:201], off
	s_add_i32 m0, s18, 0x2000
	s_add_u32 s18, s50, 0xb0080
	v_lshl_add_u64 v[200:201], v[218:219], 0, s[76:77]
	s_addc_u32 s19, s51, 0
	s_add_i32 s20, s21, s46
	global_load_lds_dwordx4 v[200:201], off
	v_lshl_add_u64 v[200:201], s[18:19], 0, v[148:149]
	s_mov_b32 m0, s20
	s_nop 0
	global_load_lds_dwordx4 v[200:201], off
	v_lshl_add_u64 v[200:201], s[18:19], 0, v[144:145]
	s_add_i32 m0, s20, 0x2000
	s_nop 0
	global_load_lds_dwordx4 v[200:201], off
	v_lshl_add_u64 v[200:201], v[220:221], 0, s[76:77]
	s_mov_b32 m0, s11
	s_nop 0
	global_load_lds_dwordx4 v[200:201], off
	v_lshl_add_u64 v[200:201], v[222:223], 0, s[76:77]
	s_mov_b32 m0, s12
	s_nop 0
	global_load_lds_dwordx4 v[200:201], off
	s_waitcnt vmcnt(8)
	s_waitcnt lgkmcnt(0)
	s_barrier
	s_setprio 1
	s_waitcnt lgkmcnt(0)
	v_mfma_f32_16x16x32_bf16 v[60:63], v[128:131], v[180:183], v[60:63]
	v_mfma_f32_16x16x32_bf16 v[56:59], v[136:139], v[180:183], v[56:59]
	v_mfma_f32_16x16x32_bf16 v[48:51], v[128:131], v[188:191], v[48:51]
	v_mfma_f32_16x16x32_bf16 v[40:43], v[136:139], v[188:191], v[40:43]
	v_mfma_f32_16x16x32_bf16 v[32:35], v[128:131], v[196:199], v[32:35]
	v_mfma_f32_16x16x32_bf16 v[24:27], v[136:139], v[196:199], v[24:27]
	v_mfma_f32_16x16x32_bf16 v[16:19], v[128:131], v[210:213], v[16:19]
	v_mfma_f32_16x16x32_bf16 v[8:11], v[136:139], v[210:213], v[8:11]
	v_mfma_f32_16x16x32_bf16 v[60:63], v[132:135], v[184:187], v[60:63]
	v_mfma_f32_16x16x32_bf16 v[56:59], v[140:143], v[184:187], v[56:59]
	v_mfma_f32_16x16x32_bf16 v[48:51], v[132:135], v[192:195], v[48:51]
	v_mfma_f32_16x16x32_bf16 v[40:43], v[140:143], v[192:195], v[40:43]
	v_mfma_f32_16x16x32_bf16 v[32:35], v[132:135], v[206:209], v[32:35]
	v_mfma_f32_16x16x32_bf16 v[24:27], v[140:143], v[206:209], v[24:27]
	v_mfma_f32_16x16x32_bf16 v[16:19], v[132:135], v[214:217], v[16:19]
	v_mfma_f32_16x16x32_bf16 v[8:11], v[140:143], v[214:217], v[8:11]
	s_setprio 0
	s_setprio 1
	v_mfma_f32_16x16x32_bf16 v[52:55], v[156:159], v[180:183], v[52:55]
	v_mfma_f32_16x16x32_bf16 v[44:47], v[168:171], v[180:183], v[44:47]
	v_mfma_f32_16x16x32_bf16 v[36:39], v[156:159], v[188:191], v[36:39]
	v_mfma_f32_16x16x32_bf16 v[28:31], v[168:171], v[188:191], v[28:31]
	v_mfma_f32_16x16x32_bf16 v[20:23], v[156:159], v[196:199], v[20:23]
	v_mfma_f32_16x16x32_bf16 v[12:15], v[168:171], v[196:199], v[12:15]
	v_mfma_f32_16x16x32_bf16 v[4:7], v[156:159], v[210:213], v[4:7]
	v_mfma_f32_16x16x32_bf16 v[0:3], v[168:171], v[210:213], v[0:3]
	v_mfma_f32_16x16x32_bf16 v[52:55], v[164:167], v[184:187], v[52:55]
	v_mfma_f32_16x16x32_bf16 v[44:47], v[176:179], v[184:187], v[44:47]
	v_mfma_f32_16x16x32_bf16 v[36:39], v[164:167], v[192:195], v[36:39]
	v_mfma_f32_16x16x32_bf16 v[28:31], v[176:179], v[192:195], v[28:31]
	v_mfma_f32_16x16x32_bf16 v[20:23], v[164:167], v[206:209], v[20:23]
	v_mfma_f32_16x16x32_bf16 v[12:15], v[176:179], v[206:209], v[12:15]
	v_mfma_f32_16x16x32_bf16 v[4:7], v[164:167], v[214:217], v[4:7]
	v_mfma_f32_16x16x32_bf16 v[0:3], v[176:179], v[214:217], v[0:3]
	s_setprio 0
	s_barrier
	s_add_i32 s61, s61, 2
	s_add_u32 s54, s54, 0x100
	s_addc_u32 s60, s60, 0
	s_cmp_gt_u32 s61, 41
	s_mov_b64 s[42:43], s[48:49]
	s_cbranch_scc0 .LBB0_1210
	s_branch .Lpeel_x_1210

.LBB0_1234:
	s_add_u32 s43, s58, 0x100
	s_addc_u32 s46, s59, 0
	s_mov_b32 s47, -2
	s_add_u32 s58, s48, 0x100
	s_addc_u32 s59, s49, 0
	s_add_i32 s18, 0, 0x10000
	s_cmp_eq_u32 s47, 18
	s_cselect_b32 s61, s39, s59
	s_cselect_b32 s60, s38, s58
	v_add_u32_e32 v158, s18, v152
	s_cselect_b32 s51, s41, s46
	s_cselect_b32 s50, s40, s43
	s_add_i32 s20, 0, 0x14000
	ds_read_b128 v[154:157], v158
	ds_read_b128 v[164:167], v158 offset:1024
	ds_read_b128 v[168:171], v158 offset:2048
	ds_read_b128 v[172:175], v158 offset:3072
	v_add_u32_e32 v158, s20, v152
	ds_read_b128 v[176:179], v158
	ds_read_b128 v[180:183], v158 offset:1024
	ds_read_b128 v[184:187], v158 offset:2048
	ds_read_b128 v[188:191], v158 offset:3072
	v_lshl_add_u64 v[158:159], s[48:49], 0, v[148:149]
	s_add_i32 m0, s5, 0xc000
	ds_read_b128 v[192:195], v153
	ds_read_b128 v[196:199], v153 offset:1024
	ds_read_b128 v[206:209], v153 offset:2048
	ds_read_b128 v[210:213], v153 offset:3072
	ds_read_b128 v[214:217], v153 offset:4096
	ds_read_b128 v[218:221], v153 offset:5120
	ds_read_b128 v[222:225], v153 offset:6144
	ds_read_b128 v[226:229], v153 offset:7168
	global_load_lds_dwordx4 v[158:159], off
	v_lshl_add_u64 v[158:159], s[48:49], 0, v[150:151]
	s_add_i32 m0, s5, 0xe000
	s_nop 0
	global_load_lds_dwordx4 v[158:159], off
	s_waitcnt vmcnt(8)
	s_waitcnt lgkmcnt(0)
	s_barrier
	s_setprio 1
	s_waitcnt lgkmcnt(0)
	v_mfma_f32_16x16x32_bf16 v[124:127], v[154:157], v[192:195], 0
	v_mfma_f32_16x16x32_bf16 v[120:123], v[168:171], v[192:195], 0
	v_mfma_f32_16x16x32_bf16 v[116:119], v[154:157], v[206:209], 0
	v_mfma_f32_16x16x32_bf16 v[112:115], v[168:171], v[206:209], 0
	v_mfma_f32_16x16x32_bf16 v[108:111], v[154:157], v[214:217], 0
	v_mfma_f32_16x16x32_bf16 v[104:107], v[168:171], v[214:217], 0
	v_mfma_f32_16x16x32_bf16 v[96:99], v[154:157], v[222:225], 0
	v_mfma_f32_16x16x32_bf16 v[88:91], v[168:171], v[222:225], 0
	v_mfma_f32_16x16x32_bf16 v[124:127], v[164:167], v[196:199], v[124:127]
	v_mfma_f32_16x16x32_bf16 v[120:123], v[172:175], v[196:199], v[120:123]
	v_mfma_f32_16x16x32_bf16 v[116:119], v[164:167], v[210:213], v[116:119]
	v_mfma_f32_16x16x32_bf16 v[112:115], v[172:175], v[210:213], v[112:115]
	v_mfma_f32_16x16x32_bf16 v[108:111], v[164:167], v[218:221], v[108:111]
	v_mfma_f32_16x16x32_bf16 v[104:107], v[172:175], v[218:221], v[104:107]
	v_mfma_f32_16x16x32_bf16 v[96:99], v[164:167], v[226:229], v[96:99]
	v_mfma_f32_16x16x32_bf16 v[88:91], v[172:175], v[226:229], v[88:91]
	s_setprio 0
	s_setprio 1
	v_mfma_f32_16x16x32_bf16 v[100:103], v[176:179], v[192:195], 0
	v_mfma_f32_16x16x32_bf16 v[92:95], v[184:187], v[192:195], 0
	v_mfma_f32_16x16x32_bf16 v[84:87], v[176:179], v[206:209], 0
	v_mfma_f32_16x16x32_bf16 v[80:83], v[184:187], v[206:209], 0
	v_mfma_f32_16x16x32_bf16 v[76:79], v[176:179], v[214:217], 0
	v_mfma_f32_16x16x32_bf16 v[72:75], v[184:187], v[214:217], 0
	v_mfma_f32_16x16x32_bf16 v[68:71], v[176:179], v[222:225], 0
	v_mfma_f32_16x16x32_bf16 v[64:67], v[184:187], v[222:225], 0
	v_mfma_f32_16x16x32_bf16 v[100:103], v[180:183], v[196:199], v[100:103]
	v_mfma_f32_16x16x32_bf16 v[92:95], v[188:191], v[196:199], v[92:95]
	v_mfma_f32_16x16x32_bf16 v[84:87], v[180:183], v[210:213], v[84:87]
	v_mfma_f32_16x16x32_bf16 v[80:83], v[188:191], v[210:213], v[80:83]
	v_mfma_f32_16x16x32_bf16 v[76:79], v[180:183], v[218:221], v[76:79]
	v_mfma_f32_16x16x32_bf16 v[72:75], v[188:191], v[218:221], v[72:75]
	v_mfma_f32_16x16x32_bf16 v[68:71], v[180:183], v[226:229], v[68:71]
	v_mfma_f32_16x16x32_bf16 v[64:67], v[188:191], v[226:229], v[64:67]
	s_setprio 0
	s_barrier
	s_add_i32 s18, s18, s4
	v_lshl_add_u64 v[158:159], s[50:51], 0, v[130:131]
	s_mov_b32 m0, s18
	ds_read_b128 v[192:195], v153 offset:16384
	ds_read_b128 v[196:199], v153 offset:17408
	ds_read_b128 v[206:209], v153 offset:18432
	ds_read_b128 v[210:213], v153 offset:19456
	ds_read_b128 v[214:217], v153 offset:20480
	ds_read_b128 v[218:221], v153 offset:21504
	ds_read_b128 v[222:225], v153 offset:22528
	ds_read_b128 v[226:229], v153 offset:23552
	global_load_lds_dwordx4 v[158:159], off
	s_add_i32 m0, s18, 0x2000
	s_add_u32 s18, s50, 0xb0000
	v_lshl_add_u64 v[200:201], s[50:51], 0, v[128:129]
	s_addc_u32 s19, s51, 0
	s_add_i32 s20, s20, s4
	global_load_lds_dwordx4 v[200:201], off
	v_lshl_add_u64 v[230:231], s[18:19], 0, v[130:131]
	s_mov_b32 m0, s20
	v_lshl_add_u64 v[232:233], s[60:61], 0, v[128:129]
	global_load_lds_dwordx4 v[230:231], off
	v_lshl_add_u64 v[230:231], s[18:19], 0, v[128:129]
	s_add_i32 m0, s20, 0x2000
	s_nop 0
	global_load_lds_dwordx4 v[230:231], off
	v_lshl_add_u64 v[230:231], s[60:61], 0, v[130:131]
	s_mov_b32 m0, s5
	s_nop 0
	global_load_lds_dwordx4 v[230:231], off
	s_mov_b32 m0, s6
	s_nop 0
	global_load_lds_dwordx4 v[232:233], off
	s_waitcnt vmcnt(8)
	s_waitcnt lgkmcnt(0)
	s_barrier
	s_setprio 1
	s_waitcnt lgkmcnt(0)
	v_mfma_f32_16x16x32_bf16 v[60:63], v[154:157], v[192:195], 0
	v_mfma_f32_16x16x32_bf16 v[56:59], v[168:171], v[192:195], 0
	v_mfma_f32_16x16x32_bf16 v[52:55], v[154:157], v[206:209], 0
	v_mfma_f32_16x16x32_bf16 v[48:51], v[168:171], v[206:209], 0
	v_mfma_f32_16x16x32_bf16 v[44:47], v[154:157], v[214:217], 0
	v_mfma_f32_16x16x32_bf16 v[40:43], v[168:171], v[214:217], 0
	v_mfma_f32_16x16x32_bf16 v[32:35], v[154:157], v[222:225], 0
	v_mfma_f32_16x16x32_bf16 v[24:27], v[168:171], v[222:225], 0
	v_mfma_f32_16x16x32_bf16 v[60:63], v[164:167], v[196:199], v[60:63]
	v_mfma_f32_16x16x32_bf16 v[56:59], v[172:175], v[196:199], v[56:59]
	v_mfma_f32_16x16x32_bf16 v[52:55], v[164:167], v[210:213], v[52:55]
	v_mfma_f32_16x16x32_bf16 v[48:51], v[172:175], v[210:213], v[48:51]
	v_mfma_f32_16x16x32_bf16 v[44:47], v[164:167], v[218:221], v[44:47]
	v_mfma_f32_16x16x32_bf16 v[40:43], v[172:175], v[218:221], v[40:43]
	v_mfma_f32_16x16x32_bf16 v[32:35], v[164:167], v[226:229], v[32:35]
	v_mfma_f32_16x16x32_bf16 v[24:27], v[172:175], v[226:229], v[24:27]
	s_setprio 0
	s_setprio 1
	v_mfma_f32_16x16x32_bf16 v[36:39], v[176:179], v[192:195], 0
	v_mfma_f32_16x16x32_bf16 v[28:31], v[184:187], v[192:195], 0
	v_mfma_f32_16x16x32_bf16 v[20:23], v[176:179], v[206:209], 0
	v_mfma_f32_16x16x32_bf16 v[16:19], v[184:187], v[206:209], 0
	v_mfma_f32_16x16x32_bf16 v[12:15], v[176:179], v[214:217], 0
	v_mfma_f32_16x16x32_bf16 v[8:11], v[184:187], v[214:217], 0
	v_mfma_f32_16x16x32_bf16 v[4:7], v[176:179], v[222:225], 0
	v_mfma_f32_16x16x32_bf16 v[0:3], v[184:187], v[222:225], 0
	v_mfma_f32_16x16x32_bf16 v[36:39], v[180:183], v[196:199], v[36:39]
	v_mfma_f32_16x16x32_bf16 v[28:31], v[188:191], v[196:199], v[28:31]
	v_mfma_f32_16x16x32_bf16 v[20:23], v[180:183], v[210:213], v[20:23]
	v_mfma_f32_16x16x32_bf16 v[16:19], v[188:191], v[210:213], v[16:19]
	v_mfma_f32_16x16x32_bf16 v[12:15], v[180:183], v[218:221], v[12:15]
	v_mfma_f32_16x16x32_bf16 v[8:11], v[188:191], v[218:221], v[8:11]
	v_mfma_f32_16x16x32_bf16 v[4:7], v[180:183], v[226:229], v[4:7]
	v_mfma_f32_16x16x32_bf16 v[0:3], v[188:191], v[226:229], v[0:3]
	s_setprio 0
	s_barrier
	s_add_i32 s20, 0, 0x18000
	s_add_i32 s21, 0, 0x1c000
	v_add_u32_e32 v172, s20, v152
	v_add_u32_e32 v188, s21, v152
	ds_read_b128 v[154:157], v172
	ds_read_b128 v[164:167], v172 offset:1024
	ds_read_b128 v[168:171], v172 offset:2048
	ds_read_b128 v[172:175], v172 offset:3072
	ds_read_b128 v[176:179], v188
	ds_read_b128 v[180:183], v188 offset:1024
	ds_read_b128 v[184:187], v188 offset:2048
	ds_read_b128 v[188:191], v188 offset:3072
	s_add_u32 s18, s60, 0xb0000
	s_addc_u32 s19, s61, 0
	s_mov_b32 m0, s7
	v_lshl_add_u64 v[234:235], s[18:19], 0, v[130:131]
	ds_read_b128 v[192:195], v153 offset:32768
	ds_read_b128 v[196:199], v153 offset:33792
	ds_read_b128 v[206:209], v153 offset:34816
	ds_read_b128 v[210:213], v153 offset:35840
	ds_read_b128 v[214:217], v153 offset:36864
	ds_read_b128 v[218:221], v153 offset:37888
	ds_read_b128 v[222:225], v153 offset:38912
	ds_read_b128 v[226:229], v153 offset:39936
	global_load_lds_dwordx4 v[234:235], off
	v_lshl_add_u64 v[234:235], s[18:19], 0, v[128:129]
	s_mov_b32 m0, s8
	s_nop 0
	global_load_lds_dwordx4 v[234:235], off
	s_waitcnt vmcnt(8)
	s_waitcnt lgkmcnt(0)
	s_barrier
	s_setprio 1
	s_waitcnt lgkmcnt(0)
	v_mfma_f32_16x16x32_bf16 v[124:127], v[154:157], v[192:195], v[124:127]
	v_mfma_f32_16x16x32_bf16 v[120:123], v[168:171], v[192:195], v[120:123]
	v_mfma_f32_16x16x32_bf16 v[116:119], v[154:157], v[206:209], v[116:119]
	v_mfma_f32_16x16x32_bf16 v[112:115], v[168:171], v[206:209], v[112:115]
	v_mfma_f32_16x16x32_bf16 v[108:111], v[154:157], v[214:217], v[108:111]
	v_mfma_f32_16x16x32_bf16 v[104:107], v[168:171], v[214:217], v[104:107]
	v_mfma_f32_16x16x32_bf16 v[96:99], v[154:157], v[222:225], v[96:99]
	v_mfma_f32_16x16x32_bf16 v[88:91], v[168:171], v[222:225], v[88:91]
	v_mfma_f32_16x16x32_bf16 v[124:127], v[164:167], v[196:199], v[124:127]
	v_mfma_f32_16x16x32_bf16 v[120:123], v[172:175], v[196:199], v[120:123]
	v_mfma_f32_16x16x32_bf16 v[116:119], v[164:167], v[210:213], v[116:119]
	v_mfma_f32_16x16x32_bf16 v[112:115], v[172:175], v[210:213], v[112:115]
	v_mfma_f32_16x16x32_bf16 v[108:111], v[164:167], v[218:221], v[108:111]
	v_mfma_f32_16x16x32_bf16 v[104:107], v[172:175], v[218:221], v[104:107]
	v_mfma_f32_16x16x32_bf16 v[96:99], v[164:167], v[226:229], v[96:99]
	v_mfma_f32_16x16x32_bf16 v[88:91], v[172:175], v[226:229], v[88:91]
	s_setprio 0
	s_setprio 1
	v_mfma_f32_16x16x32_bf16 v[100:103], v[176:179], v[192:195], v[100:103]
	v_mfma_f32_16x16x32_bf16 v[92:95], v[184:187], v[192:195], v[92:95]
	v_mfma_f32_16x16x32_bf16 v[84:87], v[176:179], v[206:209], v[84:87]
	v_mfma_f32_16x16x32_bf16 v[80:83], v[184:187], v[206:209], v[80:83]
	v_mfma_f32_16x16x32_bf16 v[76:79], v[176:179], v[214:217], v[76:79]
	v_mfma_f32_16x16x32_bf16 v[72:75], v[184:187], v[214:217], v[72:75]
	v_mfma_f32_16x16x32_bf16 v[68:71], v[176:179], v[222:225], v[68:71]
	v_mfma_f32_16x16x32_bf16 v[64:67], v[184:187], v[222:225], v[64:67]
	v_mfma_f32_16x16x32_bf16 v[100:103], v[180:183], v[196:199], v[100:103]
	v_mfma_f32_16x16x32_bf16 v[92:95], v[188:191], v[196:199], v[92:95]
	v_mfma_f32_16x16x32_bf16 v[84:87], v[180:183], v[210:213], v[84:87]
	v_mfma_f32_16x16x32_bf16 v[80:83], v[188:191], v[210:213], v[80:83]
	v_mfma_f32_16x16x32_bf16 v[76:79], v[180:183], v[218:221], v[76:79]
	v_mfma_f32_16x16x32_bf16 v[72:75], v[188:191], v[218:221], v[72:75]
	v_mfma_f32_16x16x32_bf16 v[68:71], v[180:183], v[226:229], v[68:71]
	v_mfma_f32_16x16x32_bf16 v[64:67], v[188:191], v[226:229], v[64:67]
	s_setprio 0
	s_barrier
	s_add_i32 s18, s20, s4
	v_lshl_add_u64 v[158:159], v[158:159], 0, s[76:77]
	s_mov_b32 m0, s18
	ds_read_b128 v[192:195], v153 offset:49152
	ds_read_b128 v[196:199], v153 offset:50176
	ds_read_b128 v[206:209], v153 offset:51200
	ds_read_b128 v[210:213], v153 offset:52224
	ds_read_b128 v[214:217], v153 offset:53248
	ds_read_b128 v[218:221], v153 offset:54272
	ds_read_b128 v[222:225], v153 offset:55296
	ds_read_b128 v[226:229], v153 offset:56320
	global_load_lds_dwordx4 v[158:159], off
	s_add_i32 m0, s18, 0x2000
	s_add_u32 s18, s50, 0xb0080
	v_lshl_add_u64 v[158:159], v[200:201], 0, s[76:77]
	s_addc_u32 s19, s51, 0
	s_add_i32 s20, s21, s4
	global_load_lds_dwordx4 v[158:159], off
	v_lshl_add_u64 v[158:159], s[18:19], 0, v[130:131]
	s_mov_b32 m0, s20
	s_nop 0
	global_load_lds_dwordx4 v[158:159], off
	v_lshl_add_u64 v[158:159], s[18:19], 0, v[128:129]
	s_add_i32 m0, s20, 0x2000
	s_nop 0
	global_load_lds_dwordx4 v[158:159], off
	v_lshl_add_u64 v[158:159], v[230:231], 0, s[76:77]
	s_mov_b32 m0, s9
	s_nop 0
	global_load_lds_dwordx4 v[158:159], off
	v_lshl_add_u64 v[158:159], v[232:233], 0, s[76:77]
	s_mov_b32 m0, s10
	s_nop 0
	global_load_lds_dwordx4 v[158:159], off
	s_waitcnt vmcnt(8)
	s_waitcnt lgkmcnt(0)
	s_barrier
	s_setprio 1
	s_waitcnt lgkmcnt(0)
	v_mfma_f32_16x16x32_bf16 v[60:63], v[154:157], v[192:195], v[60:63]
	v_mfma_f32_16x16x32_bf16 v[56:59], v[168:171], v[192:195], v[56:59]
	v_mfma_f32_16x16x32_bf16 v[52:55], v[154:157], v[206:209], v[52:55]
	v_mfma_f32_16x16x32_bf16 v[48:51], v[168:171], v[206:209], v[48:51]
	v_mfma_f32_16x16x32_bf16 v[44:47], v[154:157], v[214:217], v[44:47]
	v_mfma_f32_16x16x32_bf16 v[40:43], v[168:171], v[214:217], v[40:43]
	v_mfma_f32_16x16x32_bf16 v[32:35], v[154:157], v[222:225], v[32:35]
	v_mfma_f32_16x16x32_bf16 v[24:27], v[168:171], v[222:225], v[24:27]
	v_mfma_f32_16x16x32_bf16 v[60:63], v[164:167], v[196:199], v[60:63]
	v_mfma_f32_16x16x32_bf16 v[56:59], v[172:175], v[196:199], v[56:59]
	v_mfma_f32_16x16x32_bf16 v[52:55], v[164:167], v[210:213], v[52:55]
	v_mfma_f32_16x16x32_bf16 v[48:51], v[172:175], v[210:213], v[48:51]
	v_mfma_f32_16x16x32_bf16 v[44:47], v[164:167], v[218:221], v[44:47]
	v_mfma_f32_16x16x32_bf16 v[40:43], v[172:175], v[218:221], v[40:43]
	v_mfma_f32_16x16x32_bf16 v[32:35], v[164:167], v[226:229], v[32:35]
	v_mfma_f32_16x16x32_bf16 v[24:27], v[172:175], v[226:229], v[24:27]
	s_setprio 0
	s_setprio 1
	v_mfma_f32_16x16x32_bf16 v[36:39], v[176:179], v[192:195], v[36:39]
	v_mfma_f32_16x16x32_bf16 v[28:31], v[184:187], v[192:195], v[28:31]
	v_mfma_f32_16x16x32_bf16 v[20:23], v[176:179], v[206:209], v[20:23]
	v_mfma_f32_16x16x32_bf16 v[16:19], v[184:187], v[206:209], v[16:19]
	v_mfma_f32_16x16x32_bf16 v[12:15], v[176:179], v[214:217], v[12:15]
	v_mfma_f32_16x16x32_bf16 v[8:11], v[184:187], v[214:217], v[8:11]
	v_mfma_f32_16x16x32_bf16 v[4:7], v[176:179], v[222:225], v[4:7]
	v_mfma_f32_16x16x32_bf16 v[0:3], v[184:187], v[222:225], v[0:3]
	v_mfma_f32_16x16x32_bf16 v[36:39], v[180:183], v[196:199], v[36:39]
	v_mfma_f32_16x16x32_bf16 v[28:31], v[188:191], v[196:199], v[28:31]
	v_mfma_f32_16x16x32_bf16 v[20:23], v[180:183], v[210:213], v[20:23]
	v_mfma_f32_16x16x32_bf16 v[16:19], v[188:191], v[210:213], v[16:19]
	v_mfma_f32_16x16x32_bf16 v[12:15], v[180:183], v[218:221], v[12:15]
	v_mfma_f32_16x16x32_bf16 v[8:11], v[188:191], v[218:221], v[8:11]
	v_mfma_f32_16x16x32_bf16 v[4:7], v[180:183], v[226:229], v[4:7]
	v_mfma_f32_16x16x32_bf16 v[0:3], v[188:191], v[226:229], v[0:3]
	s_setprio 0
	s_barrier
	s_add_i32 s47, s47, 2
	s_add_u32 s43, s43, 0x100
	s_addc_u32 s46, s46, 0
	s_cmp_gt_u32 s47, 19
	s_mov_b64 s[48:49], s[58:59]
	s_cbranch_scc0 .LBB0_1235
	s_branch .Lpeel_x_1235
